# GEMM K-loops: second-half-tile LDS-DMA stages add the half-tile step on the scalar side and use the SGPR-base form (37 more v_lshl_add_u64 removed)
# baseline (speedup 1.0000x reference)
.LBB0_305:
	s_add_u32 s30, s4, 0xfffc0080
	s_addc_u32 s31, s5, -1
	s_add_i32 s52, 0, 0x10000
	v_add_u32_e32 v48, s52, v141
	ds_read_b128 v[150:153], v48
	ds_read_b128 v[156:159], v48 offset:1024
	ds_read_b128 v[160:163], v48 offset:2048
	ds_read_b128 v[164:167], v48 offset:3072
	s_cmp_eq_u32 s51, 12
	s_cselect_b32 s35, s27, s31
	s_cselect_b32 s34, s26, s30
	s_cselect_b32 s31, s29, s25
	s_cselect_b32 s30, s28, s23
	s_add_i32 m0, s42, 0xc000
	ds_read_b128 v[168:171], v155
	ds_read_b128 v[172:175], v155 offset:1024
	ds_read_b128 v[176:179], v155 offset:2048
	ds_read_b128 v[180:183], v155 offset:3072
	ds_read_b128 v[184:187], v155 offset:4096
	ds_read_b128 v[188:191], v155 offset:5120
	ds_read_b128 v[198:201], v155 offset:6144
	ds_read_b128 v[202:205], v155 offset:7168
	global_load_lds_dwordx4 v146, s[4:5]
	s_add_i32 m0, s42, 0xe000
	s_nop 0
	global_load_lds_dwordx4 v148, s[4:5]
	s_waitcnt lgkmcnt(8)
	s_barrier
	s_waitcnt lgkmcnt(0)
	s_setprio 1
	s_waitcnt lgkmcnt(0)
	v_mfma_f32_16x16x32_bf16 v[126:129], v[150:153], v[168:171], v[126:129]
	v_mfma_f32_16x16x32_bf16 v[122:125], v[160:163], v[168:171], v[122:125]
	v_mfma_f32_16x16x32_bf16 v[110:113], v[150:153], v[176:179], v[110:113]
	v_mfma_f32_16x16x32_bf16 v[106:109], v[160:163], v[176:179], v[106:109]
	v_mfma_f32_16x16x32_bf16 v[94:97], v[150:153], v[184:187], v[94:97]
	v_mfma_f32_16x16x32_bf16 v[90:93], v[160:163], v[184:187], v[90:93]
	v_mfma_f32_16x16x32_bf16 v[78:81], v[150:153], v[198:201], v[78:81]
	v_mfma_f32_16x16x32_bf16 v[74:77], v[160:163], v[198:201], v[74:77]
	v_mfma_f32_16x16x32_bf16 v[126:129], v[156:159], v[172:175], v[126:129]
	v_mfma_f32_16x16x32_bf16 v[122:125], v[164:167], v[172:175], v[122:125]
	v_mfma_f32_16x16x32_bf16 v[110:113], v[156:159], v[180:183], v[110:113]
	v_mfma_f32_16x16x32_bf16 v[106:109], v[164:167], v[180:183], v[106:109]
	v_mfma_f32_16x16x32_bf16 v[94:97], v[156:159], v[188:191], v[94:97]
	v_mfma_f32_16x16x32_bf16 v[90:93], v[164:167], v[188:191], v[90:93]
	v_mfma_f32_16x16x32_bf16 v[78:81], v[156:159], v[202:205], v[78:81]
	v_mfma_f32_16x16x32_bf16 v[74:77], v[164:167], v[202:205], v[74:77]
	s_setprio 0
	s_barrier
	s_add_i32 s54, 0, 0x14000
	s_add_i32 s52, s52, s41
	v_add_u32_e32 v48, s54, v141
	s_mov_b32 m0, s52
	ds_read_b128 v[206:209], v48
	ds_read_b128 v[210:213], v48 offset:1024
	ds_read_b128 v[214:217], v48 offset:2048
	ds_read_b128 v[218:221], v48 offset:3072
	global_load_lds_dwordx4 v132, s[30:31]
	s_add_i32 m0, s52, 0x2000
	s_nop 0
	global_load_lds_dwordx4 v136, s[30:31]
	s_barrier
	s_waitcnt lgkmcnt(0)
	s_setprio 1
	s_waitcnt lgkmcnt(0)
	v_mfma_f32_16x16x32_bf16 v[118:121], v[206:209], v[168:171], v[118:121]
	v_mfma_f32_16x16x32_bf16 v[114:117], v[214:217], v[168:171], v[114:117]
	v_mfma_f32_16x16x32_bf16 v[102:105], v[206:209], v[176:179], v[102:105]
	v_mfma_f32_16x16x32_bf16 v[98:101], v[214:217], v[176:179], v[98:101]
	v_mfma_f32_16x16x32_bf16 v[86:89], v[206:209], v[184:187], v[86:89]
	v_mfma_f32_16x16x32_bf16 v[82:85], v[214:217], v[184:187], v[82:85]
	v_mfma_f32_16x16x32_bf16 v[70:73], v[206:209], v[198:201], v[70:73]
	v_mfma_f32_16x16x32_bf16 v[66:69], v[214:217], v[198:201], v[66:69]
	v_mfma_f32_16x16x32_bf16 v[118:121], v[210:213], v[172:175], v[118:121]
	v_mfma_f32_16x16x32_bf16 v[114:117], v[218:221], v[172:175], v[114:117]
	v_mfma_f32_16x16x32_bf16 v[102:105], v[210:213], v[180:183], v[102:105]
	v_mfma_f32_16x16x32_bf16 v[98:101], v[218:221], v[180:183], v[98:101]
	v_mfma_f32_16x16x32_bf16 v[86:89], v[210:213], v[188:191], v[86:89]
	v_mfma_f32_16x16x32_bf16 v[82:85], v[218:221], v[188:191], v[82:85]
	v_mfma_f32_16x16x32_bf16 v[70:73], v[210:213], v[202:205], v[70:73]
	v_mfma_f32_16x16x32_bf16 v[66:69], v[218:221], v[202:205], v[66:69]
	s_setprio 0
	s_mov_b32 m0, s42
	v_lshl_add_u64 v[242:243], s[34:35], 0, v[130:131]
	s_barrier
	ds_read_b128 v[168:171], v155 offset:16384
	ds_read_b128 v[172:175], v155 offset:17408
	ds_read_b128 v[176:179], v155 offset:18432
	ds_read_b128 v[180:183], v155 offset:19456
	ds_read_b128 v[184:187], v155 offset:20480
	ds_read_b128 v[188:191], v155 offset:21504
	ds_read_b128 v[198:201], v155 offset:22528
	ds_read_b128 v[202:205], v155 offset:23552
	global_load_lds_dwordx4 v[242:243], off
	v_lshl_add_u64 v[244:245], s[34:35], 0, v[134:135]
	s_mov_b32 m0, s43
	s_nop 0
	global_load_lds_dwordx4 v[244:245], off
	s_barrier
	s_waitcnt lgkmcnt(0)
	s_setprio 1
	s_waitcnt lgkmcnt(0)
	v_mfma_f32_16x16x32_bf16 v[62:65], v[150:153], v[168:171], v[62:65]
	v_mfma_f32_16x16x32_bf16 v[58:61], v[160:163], v[168:171], v[58:61]
	v_mfma_f32_16x16x32_bf16 v[44:47], v[150:153], v[176:179], v[44:47]
	v_mfma_f32_16x16x32_bf16 v[40:43], v[160:163], v[176:179], v[40:43]
	v_mfma_f32_16x16x32_bf16 v[28:31], v[150:153], v[184:187], v[28:31]
	v_mfma_f32_16x16x32_bf16 v[24:27], v[160:163], v[184:187], v[24:27]
	v_mfma_f32_16x16x32_bf16 v[12:15], v[150:153], v[198:201], v[12:15]
	v_mfma_f32_16x16x32_bf16 v[8:11], v[160:163], v[198:201], v[8:11]
	v_mfma_f32_16x16x32_bf16 v[62:65], v[156:159], v[172:175], v[62:65]
	v_mfma_f32_16x16x32_bf16 v[58:61], v[164:167], v[172:175], v[58:61]
	v_mfma_f32_16x16x32_bf16 v[44:47], v[156:159], v[180:183], v[44:47]
	v_mfma_f32_16x16x32_bf16 v[40:43], v[164:167], v[180:183], v[40:43]
	v_mfma_f32_16x16x32_bf16 v[28:31], v[156:159], v[188:191], v[28:31]
	v_mfma_f32_16x16x32_bf16 v[24:27], v[164:167], v[188:191], v[24:27]
	v_mfma_f32_16x16x32_bf16 v[12:15], v[156:159], v[202:205], v[12:15]
	v_mfma_f32_16x16x32_bf16 v[8:11], v[164:167], v[202:205], v[8:11]
	s_setprio 0
	s_barrier
	s_add_u32 s52, s30, 0x40000
	s_addc_u32 s53, s31, 0
	s_add_i32 s54, s54, s41
	s_mov_b32 m0, s54
	s_nop 0
	global_load_lds_dwordx4 v132, s[52:53]
	s_add_i32 m0, s54, 0x2000
	s_nop 0
	global_load_lds_dwordx4 v136, s[52:53]
	s_waitcnt vmcnt(6)
	s_barrier
	s_setprio 1
	v_mfma_f32_16x16x32_bf16 v[54:57], v[206:209], v[168:171], v[54:57]
	v_mfma_f32_16x16x32_bf16 v[50:53], v[214:217], v[168:171], v[50:53]
	v_mfma_f32_16x16x32_bf16 v[36:39], v[206:209], v[176:179], v[36:39]
	v_mfma_f32_16x16x32_bf16 v[32:35], v[214:217], v[176:179], v[32:35]
	v_mfma_f32_16x16x32_bf16 v[20:23], v[206:209], v[184:187], v[20:23]
	v_mfma_f32_16x16x32_bf16 v[16:19], v[214:217], v[184:187], v[16:19]
	v_mfma_f32_16x16x32_bf16 v[4:7], v[206:209], v[198:201], v[4:7]
	v_mfma_f32_16x16x32_bf16 v[0:3], v[214:217], v[198:201], v[0:3]
	v_mfma_f32_16x16x32_bf16 v[54:57], v[210:213], v[172:175], v[54:57]
	v_mfma_f32_16x16x32_bf16 v[50:53], v[218:221], v[172:175], v[50:53]
	v_mfma_f32_16x16x32_bf16 v[36:39], v[210:213], v[180:183], v[36:39]
	v_mfma_f32_16x16x32_bf16 v[32:35], v[218:221], v[180:183], v[32:35]
	v_mfma_f32_16x16x32_bf16 v[20:23], v[210:213], v[188:191], v[20:23]
	v_mfma_f32_16x16x32_bf16 v[16:19], v[218:221], v[188:191], v[16:19]
	v_mfma_f32_16x16x32_bf16 v[4:7], v[210:213], v[202:205], v[4:7]
	v_mfma_f32_16x16x32_bf16 v[0:3], v[218:221], v[202:205], v[0:3]
	s_setprio 0
	s_add_i32 s52, 0, 0x18000
	v_add_u32_e32 v48, s52, v141
	s_barrier
	ds_read_b128 v[150:153], v48
	ds_read_b128 v[156:159], v48 offset:1024
	ds_read_b128 v[160:163], v48 offset:2048
	ds_read_b128 v[164:167], v48 offset:3072
	s_add_u32 s34, s34, 0x40000
	s_addc_u32 s35, s35, 0
	s_mov_b32 m0, s44
	ds_read_b128 v[168:171], v155 offset:32768
	ds_read_b128 v[172:175], v155 offset:33792
	ds_read_b128 v[176:179], v155 offset:34816
	ds_read_b128 v[180:183], v155 offset:35840
	ds_read_b128 v[184:187], v155 offset:36864
	ds_read_b128 v[188:191], v155 offset:37888
	ds_read_b128 v[198:201], v155 offset:38912
	ds_read_b128 v[202:205], v155 offset:39936
	global_load_lds_dwordx4 v130, s[34:35]
	s_mov_b32 m0, s45
	s_nop 0
	global_load_lds_dwordx4 v134, s[34:35]
	s_waitcnt lgkmcnt(8)
	s_barrier
	s_waitcnt lgkmcnt(0)
	s_setprio 1
	s_waitcnt lgkmcnt(0)
	v_mfma_f32_16x16x32_bf16 v[126:129], v[150:153], v[168:171], v[126:129]
	v_mfma_f32_16x16x32_bf16 v[122:125], v[160:163], v[168:171], v[122:125]
	v_mfma_f32_16x16x32_bf16 v[110:113], v[150:153], v[176:179], v[110:113]
	v_mfma_f32_16x16x32_bf16 v[106:109], v[160:163], v[176:179], v[106:109]
	v_mfma_f32_16x16x32_bf16 v[94:97], v[150:153], v[184:187], v[94:97]
	v_mfma_f32_16x16x32_bf16 v[90:93], v[160:163], v[184:187], v[90:93]
	v_mfma_f32_16x16x32_bf16 v[78:81], v[150:153], v[198:201], v[78:81]
	v_mfma_f32_16x16x32_bf16 v[74:77], v[160:163], v[198:201], v[74:77]
	v_mfma_f32_16x16x32_bf16 v[126:129], v[156:159], v[172:175], v[126:129]
	v_mfma_f32_16x16x32_bf16 v[122:125], v[164:167], v[172:175], v[122:125]
	v_mfma_f32_16x16x32_bf16 v[110:113], v[156:159], v[180:183], v[110:113]
	v_mfma_f32_16x16x32_bf16 v[106:109], v[164:167], v[180:183], v[106:109]
	v_mfma_f32_16x16x32_bf16 v[94:97], v[156:159], v[188:191], v[94:97]
	v_mfma_f32_16x16x32_bf16 v[90:93], v[164:167], v[188:191], v[90:93]
	v_mfma_f32_16x16x32_bf16 v[78:81], v[156:159], v[202:205], v[78:81]
	v_mfma_f32_16x16x32_bf16 v[74:77], v[164:167], v[202:205], v[74:77]
	s_setprio 0
	s_barrier
	s_add_i32 s34, 0, 0x1c000
	s_add_i32 s35, s52, s41
	v_add_u32_e32 v48, s34, v141
	s_add_u32 s52, s30, s66
	s_addc_u32 s53, s31, s67
	s_mov_b32 m0, s35
	ds_read_b128 v[206:209], v48
	ds_read_b128 v[210:213], v48 offset:1024
	ds_read_b128 v[214:217], v48 offset:2048
	ds_read_b128 v[218:221], v48 offset:3072
	global_load_lds_dwordx4 v132, s[52:53]
	s_add_u32 s52, s30, s66
	s_addc_u32 s53, s31, s67
	s_add_i32 m0, s35, 0x2000
	s_nop 0
	global_load_lds_dwordx4 v136, s[52:53]
	s_barrier
	s_waitcnt lgkmcnt(0)
	s_setprio 1
	s_waitcnt lgkmcnt(0)
	v_mfma_f32_16x16x32_bf16 v[118:121], v[206:209], v[168:171], v[118:121]
	v_mfma_f32_16x16x32_bf16 v[114:117], v[214:217], v[168:171], v[114:117]
	v_mfma_f32_16x16x32_bf16 v[102:105], v[206:209], v[176:179], v[102:105]
	v_mfma_f32_16x16x32_bf16 v[98:101], v[214:217], v[176:179], v[98:101]
	v_mfma_f32_16x16x32_bf16 v[86:89], v[206:209], v[184:187], v[86:89]
	v_mfma_f32_16x16x32_bf16 v[82:85], v[214:217], v[184:187], v[82:85]
	v_mfma_f32_16x16x32_bf16 v[70:73], v[206:209], v[198:201], v[70:73]
	v_mfma_f32_16x16x32_bf16 v[66:69], v[214:217], v[198:201], v[66:69]
	v_mfma_f32_16x16x32_bf16 v[118:121], v[210:213], v[172:175], v[118:121]
	v_mfma_f32_16x16x32_bf16 v[114:117], v[218:221], v[172:175], v[114:117]
	v_mfma_f32_16x16x32_bf16 v[102:105], v[210:213], v[180:183], v[102:105]
	v_mfma_f32_16x16x32_bf16 v[98:101], v[218:221], v[180:183], v[98:101]
	v_mfma_f32_16x16x32_bf16 v[86:89], v[210:213], v[188:191], v[86:89]
	v_mfma_f32_16x16x32_bf16 v[82:85], v[218:221], v[188:191], v[82:85]
	v_mfma_f32_16x16x32_bf16 v[70:73], v[210:213], v[202:205], v[70:73]
	v_mfma_f32_16x16x32_bf16 v[66:69], v[218:221], v[202:205], v[66:69]
	s_setprio 0
	s_mov_b32 m0, s46
	v_lshl_add_u64 v[192:193], v[242:243], 0, s[66:67]
	s_barrier
	ds_read_b128 v[168:171], v155 offset:49152
	ds_read_b128 v[172:175], v155 offset:50176
	ds_read_b128 v[176:179], v155 offset:51200
	ds_read_b128 v[180:183], v155 offset:52224
	ds_read_b128 v[184:187], v155 offset:53248
	ds_read_b128 v[188:191], v155 offset:54272
	ds_read_b128 v[198:201], v155 offset:55296
	ds_read_b128 v[202:205], v155 offset:56320
	global_load_lds_dwordx4 v[192:193], off
	v_lshl_add_u64 v[192:193], v[244:245], 0, s[66:67]
	s_mov_b32 m0, s47
	s_nop 0
	global_load_lds_dwordx4 v[192:193], off
	s_barrier
	s_waitcnt lgkmcnt(0)
	s_setprio 1
	s_waitcnt lgkmcnt(0)
	v_mfma_f32_16x16x32_bf16 v[62:65], v[150:153], v[168:171], v[62:65]
	v_mfma_f32_16x16x32_bf16 v[58:61], v[160:163], v[168:171], v[58:61]
	v_mfma_f32_16x16x32_bf16 v[44:47], v[150:153], v[176:179], v[44:47]
	v_mfma_f32_16x16x32_bf16 v[40:43], v[160:163], v[176:179], v[40:43]
	v_mfma_f32_16x16x32_bf16 v[28:31], v[150:153], v[184:187], v[28:31]
	v_mfma_f32_16x16x32_bf16 v[24:27], v[160:163], v[184:187], v[24:27]
	v_mfma_f32_16x16x32_bf16 v[12:15], v[150:153], v[198:201], v[12:15]
	v_mfma_f32_16x16x32_bf16 v[8:11], v[160:163], v[198:201], v[8:11]
	v_mfma_f32_16x16x32_bf16 v[62:65], v[156:159], v[172:175], v[62:65]
	v_mfma_f32_16x16x32_bf16 v[58:61], v[164:167], v[172:175], v[58:61]
	v_mfma_f32_16x16x32_bf16 v[44:47], v[156:159], v[180:183], v[44:47]
	v_mfma_f32_16x16x32_bf16 v[40:43], v[164:167], v[180:183], v[40:43]
	v_mfma_f32_16x16x32_bf16 v[28:31], v[156:159], v[188:191], v[28:31]
	v_mfma_f32_16x16x32_bf16 v[24:27], v[164:167], v[188:191], v[24:27]
	v_mfma_f32_16x16x32_bf16 v[12:15], v[156:159], v[202:205], v[12:15]
	v_mfma_f32_16x16x32_bf16 v[8:11], v[164:167], v[202:205], v[8:11]
	s_setprio 0
	s_barrier
	s_add_u32 s30, s30, 0x40080
	s_addc_u32 s31, s31, 0
	s_add_i32 s34, s34, s41
	s_mov_b32 m0, s34
	s_nop 0
	global_load_lds_dwordx4 v132, s[30:31]
	s_add_i32 m0, s34, 0x2000
	s_nop 0
	global_load_lds_dwordx4 v136, s[30:31]
	s_waitcnt vmcnt(6)
	s_barrier
	s_setprio 1
	v_mfma_f32_16x16x32_bf16 v[54:57], v[206:209], v[168:171], v[54:57]
	v_mfma_f32_16x16x32_bf16 v[50:53], v[214:217], v[168:171], v[50:53]
	v_mfma_f32_16x16x32_bf16 v[36:39], v[206:209], v[176:179], v[36:39]
	v_mfma_f32_16x16x32_bf16 v[32:35], v[214:217], v[176:179], v[32:35]
	v_mfma_f32_16x16x32_bf16 v[20:23], v[206:209], v[184:187], v[20:23]
	v_mfma_f32_16x16x32_bf16 v[16:19], v[214:217], v[184:187], v[16:19]
	v_mfma_f32_16x16x32_bf16 v[4:7], v[206:209], v[198:201], v[4:7]
	v_mfma_f32_16x16x32_bf16 v[0:3], v[214:217], v[198:201], v[0:3]
	v_mfma_f32_16x16x32_bf16 v[54:57], v[210:213], v[172:175], v[54:57]
	v_mfma_f32_16x16x32_bf16 v[50:53], v[218:221], v[172:175], v[50:53]
	v_mfma_f32_16x16x32_bf16 v[36:39], v[210:213], v[180:183], v[36:39]
	v_mfma_f32_16x16x32_bf16 v[32:35], v[218:221], v[180:183], v[32:35]
	v_mfma_f32_16x16x32_bf16 v[20:23], v[210:213], v[188:191], v[20:23]
	v_mfma_f32_16x16x32_bf16 v[16:19], v[218:221], v[188:191], v[16:19]
	v_mfma_f32_16x16x32_bf16 v[4:7], v[210:213], v[202:205], v[4:7]
	v_mfma_f32_16x16x32_bf16 v[0:3], v[218:221], v[202:205], v[0:3]
	s_setprio 0
	s_add_i32 s51, s51, 2
	s_add_u32 s4, s4, 0x100
	s_addc_u32 s5, s5, 0
	s_add_u32 s23, s23, 0x100
	s_addc_u32 s25, s25, 0
	s_cmp_gt_u32 s51, 13
	s_barrier
	s_cbranch_scc0 .LBB0_305
	v_lshl_add_u32 v156, s50, 8, v139
	v_ashrrev_i32_e32 v48, 31, v156
	v_alignbit_b32 v150, v48, v156, 6
	v_mad_u64_u32 v[150:151], s[4:5], v150, s71, 0
	v_mad_i32_i24 v151, v48, s71, v151
	v_lshlrev_b32_e32 v48, 3, v156
	s_cmp_lg_u32 s49, 0
	v_and_b32_e32 v48, 0x78, v48
	s_cselect_b64 s[30:31], -1, 0
	s_and_b64 vcc, exec, s[30:31]
	v_lshl_add_u32 v157, s49, 8, v145
	v_lshlrev_b32_e32 v48, 1, v48
	s_cbranch_vccz .LBB0_314
	v_ashrrev_i32_e32 v152, 3, v157
	v_ashrrev_i32_e32 v153, 31, v152
	v_lshl_add_u64 v[152:153], v[150:151], 0, v[152:153]
	v_lshlrev_b64 v[152:153], 10, v[152:153]
	v_lshl_add_u64 v[152:153], s[18:19], 0, v[152:153]
	v_lshl_add_u64 v[152:153], v[152:153], 0, v[48:49]
	v_ashrrev_i32_e32 v159, 5, v156
	v_add_u32_e32 v158, v159, v140
	s_cbranch_execnz .LBB0_309

.LBB0_641:
	s_add_u32 s24, s22, 0x100
	s_addc_u32 s25, s23, 0
	s_add_i32 s50, 0, 0x10000
	v_add_u32_e32 v145, s50, v143
	ds_read_b128 v[146:149], v145
	ds_read_b128 v[150:153], v145 offset:1024
	ds_read_b128 v[154:157], v145 offset:2048
	ds_read_b128 v[158:161], v145 offset:3072
	s_cmp_eq_u32 s49, 4
	s_cselect_b32 s29, s19, s25
	s_cselect_b32 s28, s18, s24
	s_cselect_b32 s27, s21, s48
	s_cselect_b32 s26, s20, s5
	v_lshl_add_u64 v[198:199], s[22:23], 0, v[138:139]
	s_add_i32 m0, s38, 0xc000
	ds_read_b128 v[162:165], v144
	ds_read_b128 v[166:169], v144 offset:1024
	ds_read_b128 v[170:173], v144 offset:2048
	ds_read_b128 v[174:177], v144 offset:3072
	ds_read_b128 v[178:181], v144 offset:4096
	ds_read_b128 v[182:185], v144 offset:5120
	ds_read_b128 v[186:189], v144 offset:6144
	ds_read_b128 v[190:193], v144 offset:7168
	global_load_lds_dwordx4 v[198:199], off
	v_lshl_add_u64 v[198:199], s[22:23], 0, v[140:141]
	s_add_i32 m0, s38, 0xe000
	s_nop 0
	global_load_lds_dwordx4 v[198:199], off
	s_waitcnt lgkmcnt(8)
	s_barrier
	s_waitcnt lgkmcnt(0)
	s_setprio 1
	s_waitcnt lgkmcnt(0)
	v_mfma_f32_16x16x32_bf16 v[126:129], v[146:149], v[162:165], v[126:129]
	v_mfma_f32_16x16x32_bf16 v[122:125], v[154:157], v[162:165], v[122:125]
	v_mfma_f32_16x16x32_bf16 v[118:121], v[146:149], v[170:173], v[118:121]
	v_mfma_f32_16x16x32_bf16 v[114:117], v[154:157], v[170:173], v[114:117]
	v_mfma_f32_16x16x32_bf16 v[106:109], v[146:149], v[178:181], v[106:109]
	v_mfma_f32_16x16x32_bf16 v[98:101], v[154:157], v[178:181], v[98:101]
	v_mfma_f32_16x16x32_bf16 v[90:93], v[146:149], v[186:189], v[90:93]
	v_mfma_f32_16x16x32_bf16 v[82:85], v[154:157], v[186:189], v[82:85]
	v_mfma_f32_16x16x32_bf16 v[126:129], v[150:153], v[166:169], v[126:129]
	v_mfma_f32_16x16x32_bf16 v[122:125], v[158:161], v[166:169], v[122:125]
	v_mfma_f32_16x16x32_bf16 v[118:121], v[150:153], v[174:177], v[118:121]
	v_mfma_f32_16x16x32_bf16 v[114:117], v[158:161], v[174:177], v[114:117]
	v_mfma_f32_16x16x32_bf16 v[106:109], v[150:153], v[182:185], v[106:109]
	v_mfma_f32_16x16x32_bf16 v[98:101], v[158:161], v[182:185], v[98:101]
	v_mfma_f32_16x16x32_bf16 v[90:93], v[150:153], v[190:193], v[90:93]
	v_mfma_f32_16x16x32_bf16 v[82:85], v[158:161], v[190:193], v[82:85]
	s_setprio 0
	s_barrier
	s_add_i32 s51, 0, 0x14000
	s_add_i32 s22, s50, s37
	v_add_u32_e32 v145, s51, v143
	s_mov_b32 m0, s22
	ds_read_b128 v[198:201], v145
	ds_read_b128 v[202:205], v145 offset:1024
	ds_read_b128 v[206:209], v145 offset:2048
	ds_read_b128 v[210:213], v145 offset:3072
	global_load_lds_dwordx4 v48, s[26:27]
	s_add_i32 m0, s22, 0x2000
	s_nop 0
	global_load_lds_dwordx4 v130, s[26:27]
	s_barrier
	s_waitcnt lgkmcnt(0)
	s_setprio 1
	s_waitcnt lgkmcnt(0)
	v_mfma_f32_16x16x32_bf16 v[110:113], v[198:201], v[162:165], v[110:113]
	v_mfma_f32_16x16x32_bf16 v[102:105], v[206:209], v[162:165], v[102:105]
	v_mfma_f32_16x16x32_bf16 v[94:97], v[198:201], v[170:173], v[94:97]
	v_mfma_f32_16x16x32_bf16 v[86:89], v[206:209], v[170:173], v[86:89]
	v_mfma_f32_16x16x32_bf16 v[78:81], v[198:201], v[178:181], v[78:81]
	v_mfma_f32_16x16x32_bf16 v[74:77], v[206:209], v[178:181], v[74:77]
	v_mfma_f32_16x16x32_bf16 v[70:73], v[198:201], v[186:189], v[70:73]
	v_mfma_f32_16x16x32_bf16 v[66:69], v[206:209], v[186:189], v[66:69]
	v_mfma_f32_16x16x32_bf16 v[110:113], v[202:205], v[166:169], v[110:113]
	v_mfma_f32_16x16x32_bf16 v[102:105], v[210:213], v[166:169], v[102:105]
	v_mfma_f32_16x16x32_bf16 v[94:97], v[202:205], v[174:177], v[94:97]
	v_mfma_f32_16x16x32_bf16 v[86:89], v[210:213], v[174:177], v[86:89]
	v_mfma_f32_16x16x32_bf16 v[78:81], v[202:205], v[182:185], v[78:81]
	v_mfma_f32_16x16x32_bf16 v[74:77], v[210:213], v[182:185], v[74:77]
	v_mfma_f32_16x16x32_bf16 v[70:73], v[202:205], v[190:193], v[70:73]
	v_mfma_f32_16x16x32_bf16 v[66:69], v[210:213], v[190:193], v[66:69]
	s_setprio 0
	s_mov_b32 m0, s38
	v_lshl_add_u64 v[218:219], s[28:29], 0, v[134:135]
	s_barrier
	ds_read_b128 v[162:165], v144 offset:16384
	ds_read_b128 v[166:169], v144 offset:17408
	ds_read_b128 v[170:173], v144 offset:18432
	ds_read_b128 v[174:177], v144 offset:19456
	ds_read_b128 v[178:181], v144 offset:20480
	ds_read_b128 v[182:185], v144 offset:21504
	ds_read_b128 v[186:189], v144 offset:22528
	ds_read_b128 v[190:193], v144 offset:23552
	global_load_lds_dwordx4 v[218:219], off
	v_lshl_add_u64 v[220:221], s[28:29], 0, v[132:133]
	s_mov_b32 m0, s39
	s_nop 0
	global_load_lds_dwordx4 v[220:221], off
	s_barrier
	s_waitcnt lgkmcnt(0)
	s_setprio 1
	s_waitcnt lgkmcnt(0)
	v_mfma_f32_16x16x32_bf16 v[62:65], v[146:149], v[162:165], v[62:65]
	v_mfma_f32_16x16x32_bf16 v[58:61], v[154:157], v[162:165], v[58:61]
	v_mfma_f32_16x16x32_bf16 v[54:57], v[146:149], v[170:173], v[54:57]
	v_mfma_f32_16x16x32_bf16 v[50:53], v[154:157], v[170:173], v[50:53]
	v_mfma_f32_16x16x32_bf16 v[36:39], v[146:149], v[178:181], v[36:39]
	v_mfma_f32_16x16x32_bf16 v[32:35], v[154:157], v[178:181], v[32:35]
	v_mfma_f32_16x16x32_bf16 v[20:23], v[146:149], v[186:189], v[20:23]
	v_mfma_f32_16x16x32_bf16 v[16:19], v[154:157], v[186:189], v[16:19]
	v_mfma_f32_16x16x32_bf16 v[62:65], v[150:153], v[166:169], v[62:65]
	v_mfma_f32_16x16x32_bf16 v[58:61], v[158:161], v[166:169], v[58:61]
	v_mfma_f32_16x16x32_bf16 v[54:57], v[150:153], v[174:177], v[54:57]
	v_mfma_f32_16x16x32_bf16 v[50:53], v[158:161], v[174:177], v[50:53]
	v_mfma_f32_16x16x32_bf16 v[36:39], v[150:153], v[182:185], v[36:39]
	v_mfma_f32_16x16x32_bf16 v[32:35], v[158:161], v[182:185], v[32:35]
	v_mfma_f32_16x16x32_bf16 v[20:23], v[150:153], v[190:193], v[20:23]
	v_mfma_f32_16x16x32_bf16 v[16:19], v[158:161], v[190:193], v[16:19]
	s_setprio 0
	s_barrier
	s_add_u32 s22, s26, 0x20000
	s_addc_u32 s23, s27, 0
	s_add_i32 s50, s51, s37
	s_mov_b32 m0, s50
	s_nop 0
	global_load_lds_dwordx4 v48, s[22:23]
	s_add_i32 m0, s50, 0x2000
	s_nop 0
	global_load_lds_dwordx4 v130, s[22:23]
	s_waitcnt vmcnt(6)
	s_barrier
	s_setprio 1
	v_mfma_f32_16x16x32_bf16 v[44:47], v[198:201], v[162:165], v[44:47]
	v_mfma_f32_16x16x32_bf16 v[40:43], v[206:209], v[162:165], v[40:43]
	v_mfma_f32_16x16x32_bf16 v[28:31], v[198:201], v[170:173], v[28:31]
	v_mfma_f32_16x16x32_bf16 v[24:27], v[206:209], v[170:173], v[24:27]
	v_mfma_f32_16x16x32_bf16 v[12:15], v[198:201], v[178:181], v[12:15]
	v_mfma_f32_16x16x32_bf16 v[8:11], v[206:209], v[178:181], v[8:11]
	v_mfma_f32_16x16x32_bf16 v[4:7], v[198:201], v[186:189], v[4:7]
	v_mfma_f32_16x16x32_bf16 v[0:3], v[206:209], v[186:189], v[0:3]
	v_mfma_f32_16x16x32_bf16 v[44:47], v[202:205], v[166:169], v[44:47]
	v_mfma_f32_16x16x32_bf16 v[40:43], v[210:213], v[166:169], v[40:43]
	v_mfma_f32_16x16x32_bf16 v[28:31], v[202:205], v[174:177], v[28:31]
	v_mfma_f32_16x16x32_bf16 v[24:27], v[210:213], v[174:177], v[24:27]
	v_mfma_f32_16x16x32_bf16 v[12:15], v[202:205], v[182:185], v[12:15]
	v_mfma_f32_16x16x32_bf16 v[8:11], v[210:213], v[182:185], v[8:11]
	v_mfma_f32_16x16x32_bf16 v[4:7], v[202:205], v[190:193], v[4:7]
	v_mfma_f32_16x16x32_bf16 v[0:3], v[210:213], v[190:193], v[0:3]
	s_setprio 0
	s_add_i32 s50, 0, 0x18000
	v_add_u32_e32 v145, s50, v143
	s_barrier
	ds_read_b128 v[146:149], v145
	ds_read_b128 v[150:153], v145 offset:1024
	ds_read_b128 v[154:157], v145 offset:2048
	ds_read_b128 v[158:161], v145 offset:3072
	s_add_u32 s22, s28, 0x30000
	s_addc_u32 s23, s29, 0
	s_mov_b32 m0, s40
	ds_read_b128 v[162:165], v144 offset:32768
	ds_read_b128 v[166:169], v144 offset:33792
	ds_read_b128 v[170:173], v144 offset:34816
	ds_read_b128 v[174:177], v144 offset:35840
	ds_read_b128 v[178:181], v144 offset:36864
	ds_read_b128 v[182:185], v144 offset:37888
	ds_read_b128 v[186:189], v144 offset:38912
	ds_read_b128 v[190:193], v144 offset:39936
	global_load_lds_dwordx4 v134, s[22:23]
	s_mov_b32 m0, s41
	s_nop 0
	global_load_lds_dwordx4 v132, s[22:23]
	s_waitcnt lgkmcnt(8)
	s_barrier
	s_waitcnt lgkmcnt(0)
	s_setprio 1
	s_waitcnt lgkmcnt(0)
	v_mfma_f32_16x16x32_bf16 v[126:129], v[146:149], v[162:165], v[126:129]
	v_mfma_f32_16x16x32_bf16 v[122:125], v[154:157], v[162:165], v[122:125]
	v_mfma_f32_16x16x32_bf16 v[118:121], v[146:149], v[170:173], v[118:121]
	v_mfma_f32_16x16x32_bf16 v[114:117], v[154:157], v[170:173], v[114:117]
	v_mfma_f32_16x16x32_bf16 v[106:109], v[146:149], v[178:181], v[106:109]
	v_mfma_f32_16x16x32_bf16 v[98:101], v[154:157], v[178:181], v[98:101]
	v_mfma_f32_16x16x32_bf16 v[90:93], v[146:149], v[186:189], v[90:93]
	v_mfma_f32_16x16x32_bf16 v[82:85], v[154:157], v[186:189], v[82:85]
	v_mfma_f32_16x16x32_bf16 v[126:129], v[150:153], v[166:169], v[126:129]
	v_mfma_f32_16x16x32_bf16 v[122:125], v[158:161], v[166:169], v[122:125]
	v_mfma_f32_16x16x32_bf16 v[118:121], v[150:153], v[174:177], v[118:121]
	v_mfma_f32_16x16x32_bf16 v[114:117], v[158:161], v[174:177], v[114:117]
	v_mfma_f32_16x16x32_bf16 v[106:109], v[150:153], v[182:185], v[106:109]
	v_mfma_f32_16x16x32_bf16 v[98:101], v[158:161], v[182:185], v[98:101]
	v_mfma_f32_16x16x32_bf16 v[90:93], v[150:153], v[190:193], v[90:93]
	v_mfma_f32_16x16x32_bf16 v[82:85], v[158:161], v[190:193], v[82:85]
	s_setprio 0
	s_barrier
	s_add_i32 s28, 0, 0x1c000
	s_add_i32 s22, s50, s37
	v_add_u32_e32 v145, s28, v143
	s_add_u32 s52, s26, s66
	s_addc_u32 s53, s27, s67
	s_mov_b32 m0, s22
	ds_read_b128 v[198:201], v145
	ds_read_b128 v[202:205], v145 offset:1024
	ds_read_b128 v[206:209], v145 offset:2048
	ds_read_b128 v[210:213], v145 offset:3072
	global_load_lds_dwordx4 v48, s[52:53]
	s_add_u32 s52, s26, s66
	s_addc_u32 s53, s27, s67
	s_add_i32 m0, s22, 0x2000
	s_nop 0
	global_load_lds_dwordx4 v130, s[52:53]
	s_barrier
	s_waitcnt lgkmcnt(0)
	s_setprio 1
	s_waitcnt lgkmcnt(0)
	v_mfma_f32_16x16x32_bf16 v[110:113], v[198:201], v[162:165], v[110:113]
	v_mfma_f32_16x16x32_bf16 v[102:105], v[206:209], v[162:165], v[102:105]
	v_mfma_f32_16x16x32_bf16 v[94:97], v[198:201], v[170:173], v[94:97]
	v_mfma_f32_16x16x32_bf16 v[86:89], v[206:209], v[170:173], v[86:89]
	v_mfma_f32_16x16x32_bf16 v[78:81], v[198:201], v[178:181], v[78:81]
	v_mfma_f32_16x16x32_bf16 v[74:77], v[206:209], v[178:181], v[74:77]
	v_mfma_f32_16x16x32_bf16 v[70:73], v[198:201], v[186:189], v[70:73]
	v_mfma_f32_16x16x32_bf16 v[66:69], v[206:209], v[186:189], v[66:69]
	v_mfma_f32_16x16x32_bf16 v[110:113], v[202:205], v[166:169], v[110:113]
	v_mfma_f32_16x16x32_bf16 v[102:105], v[210:213], v[166:169], v[102:105]
	v_mfma_f32_16x16x32_bf16 v[94:97], v[202:205], v[174:177], v[94:97]
	v_mfma_f32_16x16x32_bf16 v[86:89], v[210:213], v[174:177], v[86:89]
	v_mfma_f32_16x16x32_bf16 v[78:81], v[202:205], v[182:185], v[78:81]
	v_mfma_f32_16x16x32_bf16 v[74:77], v[210:213], v[182:185], v[74:77]
	v_mfma_f32_16x16x32_bf16 v[70:73], v[202:205], v[190:193], v[70:73]
	v_mfma_f32_16x16x32_bf16 v[66:69], v[210:213], v[190:193], v[66:69]
	s_setprio 0
	s_mov_b32 m0, s42
	v_lshl_add_u64 v[214:215], v[218:219], 0, s[66:67]
	s_barrier
	ds_read_b128 v[162:165], v144 offset:49152
	ds_read_b128 v[166:169], v144 offset:50176
	ds_read_b128 v[170:173], v144 offset:51200
	ds_read_b128 v[174:177], v144 offset:52224
	ds_read_b128 v[178:181], v144 offset:53248
	ds_read_b128 v[182:185], v144 offset:54272
	ds_read_b128 v[186:189], v144 offset:55296
	ds_read_b128 v[190:193], v144 offset:56320
	global_load_lds_dwordx4 v[214:215], off
	v_lshl_add_u64 v[214:215], v[220:221], 0, s[66:67]
	s_mov_b32 m0, s43
	s_nop 0
	global_load_lds_dwordx4 v[214:215], off
	s_barrier
	s_waitcnt lgkmcnt(0)
	s_setprio 1
	s_waitcnt lgkmcnt(0)
	v_mfma_f32_16x16x32_bf16 v[62:65], v[146:149], v[162:165], v[62:65]
	v_mfma_f32_16x16x32_bf16 v[58:61], v[154:157], v[162:165], v[58:61]
	v_mfma_f32_16x16x32_bf16 v[54:57], v[146:149], v[170:173], v[54:57]
	v_mfma_f32_16x16x32_bf16 v[50:53], v[154:157], v[170:173], v[50:53]
	v_mfma_f32_16x16x32_bf16 v[36:39], v[146:149], v[178:181], v[36:39]
	v_mfma_f32_16x16x32_bf16 v[32:35], v[154:157], v[178:181], v[32:35]
	v_mfma_f32_16x16x32_bf16 v[20:23], v[146:149], v[186:189], v[20:23]
	v_mfma_f32_16x16x32_bf16 v[16:19], v[154:157], v[186:189], v[16:19]
	v_mfma_f32_16x16x32_bf16 v[62:65], v[150:153], v[166:169], v[62:65]
	v_mfma_f32_16x16x32_bf16 v[58:61], v[158:161], v[166:169], v[58:61]
	v_mfma_f32_16x16x32_bf16 v[54:57], v[150:153], v[174:177], v[54:57]
	v_mfma_f32_16x16x32_bf16 v[50:53], v[158:161], v[174:177], v[50:53]
	v_mfma_f32_16x16x32_bf16 v[36:39], v[150:153], v[182:185], v[36:39]
	v_mfma_f32_16x16x32_bf16 v[32:35], v[158:161], v[182:185], v[32:35]
	v_mfma_f32_16x16x32_bf16 v[20:23], v[150:153], v[190:193], v[20:23]
	v_mfma_f32_16x16x32_bf16 v[16:19], v[158:161], v[190:193], v[16:19]
	s_setprio 0
	s_barrier
	s_add_u32 s22, s26, 0x20080
	s_addc_u32 s23, s27, 0
	s_add_i32 s26, s28, s37
	s_mov_b32 m0, s26
	s_nop 0
	global_load_lds_dwordx4 v48, s[22:23]
	s_add_i32 m0, s26, 0x2000
	s_nop 0
	global_load_lds_dwordx4 v130, s[22:23]
	s_waitcnt vmcnt(6)
	s_barrier
	s_setprio 1
	v_mfma_f32_16x16x32_bf16 v[44:47], v[198:201], v[162:165], v[44:47]
	v_mfma_f32_16x16x32_bf16 v[40:43], v[206:209], v[162:165], v[40:43]
	v_mfma_f32_16x16x32_bf16 v[28:31], v[198:201], v[170:173], v[28:31]
	v_mfma_f32_16x16x32_bf16 v[24:27], v[206:209], v[170:173], v[24:27]
	v_mfma_f32_16x16x32_bf16 v[12:15], v[198:201], v[178:181], v[12:15]
	v_mfma_f32_16x16x32_bf16 v[8:11], v[206:209], v[178:181], v[8:11]
	v_mfma_f32_16x16x32_bf16 v[4:7], v[198:201], v[186:189], v[4:7]
	v_mfma_f32_16x16x32_bf16 v[0:3], v[206:209], v[186:189], v[0:3]
	v_mfma_f32_16x16x32_bf16 v[44:47], v[202:205], v[166:169], v[44:47]
	v_mfma_f32_16x16x32_bf16 v[40:43], v[210:213], v[166:169], v[40:43]
	v_mfma_f32_16x16x32_bf16 v[28:31], v[202:205], v[174:177], v[28:31]
	v_mfma_f32_16x16x32_bf16 v[24:27], v[210:213], v[174:177], v[24:27]
	v_mfma_f32_16x16x32_bf16 v[12:15], v[202:205], v[182:185], v[12:15]
	v_mfma_f32_16x16x32_bf16 v[8:11], v[210:213], v[182:185], v[8:11]
	v_mfma_f32_16x16x32_bf16 v[4:7], v[202:205], v[190:193], v[4:7]
	v_mfma_f32_16x16x32_bf16 v[0:3], v[210:213], v[190:193], v[0:3]
	s_setprio 0
	s_add_i32 s49, s49, 2
	s_add_u32 s5, s5, 0x100
	s_addc_u32 s48, s48, 0
	s_cmp_gt_u32 s49, 5
	s_mov_b64 s[22:23], s[24:25]
	s_barrier
	s_cbranch_scc0 .LBB0_641
	v_lshl_add_u32 v146, s47, 8, v142
	v_mov_b32_e32 v145, 0x240000
	v_ashrrev_i32_e32 v147, 31, v146
	v_mad_i64_i32 v[148:149], s[22:23], s46, v145, v[136:137]
	v_lshlrev_b64 v[150:151], 10, v[146:147]
	v_lshl_add_u64 v[150:151], v[148:149], 0, v[150:151]
	global_store_dwordx4 v[150:151], v[126:129], off
	global_store_dwordx4 v[150:151], v[122:125], off offset:64
	global_store_dwordx4 v[150:151], v[110:113], off offset:512
	global_store_dwordx4 v[150:151], v[102:105], off offset:576
	s_mov_b32 s5, 0x20000
	s_mov_b64 s[22:23], 0x20000
	v_or_b32_e32 v102, 16, v146
	v_ashrrev_i32_e32 v103, 31, v102
	v_lshlrev_b64 v[102:103], 10, v[102:103]
	v_lshl_add_u64 v[102:103], v[148:149], 0, v[102:103]
	global_store_dwordx4 v[102:103], v[118:121], off
	global_store_dwordx4 v[102:103], v[114:117], off offset:64
	global_store_dwordx4 v[102:103], v[94:97], off offset:512
	global_store_dwordx4 v[102:103], v[86:89], off offset:576
	s_mov_b32 s46, s4
	s_mov_b32 s47, s45
	v_or_b32_e32 v86, 32, v146
	v_ashrrev_i32_e32 v87, 31, v86
	v_lshlrev_b64 v[86:87], 10, v[86:87]
	v_lshl_add_u64 v[86:87], v[148:149], 0, v[86:87]
	global_store_dwordx4 v[86:87], v[106:109], off
	global_store_dwordx4 v[86:87], v[98:101], off offset:64
	global_store_dwordx4 v[86:87], v[78:81], off offset:512
	global_store_dwordx4 v[86:87], v[74:77], off offset:576
	s_mov_b64 s[24:25], s[20:21]
	s_nop 0
	v_or_b32_e32 v74, 48, v146
	v_ashrrev_i32_e32 v75, 31, v74
	v_lshlrev_b64 v[74:75], 10, v[74:75]
	v_lshl_add_u64 v[74:75], v[148:149], 0, v[74:75]
	global_store_dwordx4 v[74:75], v[90:93], off
	global_store_dwordx4 v[74:75], v[82:85], off offset:64
	global_store_dwordx4 v[74:75], v[70:73], off offset:512
	global_store_dwordx4 v[74:75], v[66:69], off offset:576
	s_nop 1
	v_add_co_u32_e32 v68, vcc, s5, v150
	s_mov_b32 s5, 0x24000
	s_nop 0
	v_addc_co_u32_e32 v69, vcc, 0, v151, vcc
	v_lshl_add_u64 v[66:67], v[150:151], 0, s[22:23]
	global_store_dwordx4 v[68:69], v[62:65], off
	global_store_dwordx4 v[66:67], v[58:61], off offset:64
	global_store_dwordx4 v[66:67], v[44:47], off offset:512
	global_store_dwordx4 v[66:67], v[40:43], off offset:576
	s_mov_b64 s[22:23], 0x24000
	s_nop 0
	v_add_co_u32_e32 v42, vcc, s5, v150
	s_mov_b32 s5, 0x28000
	s_nop 0
	v_addc_co_u32_e32 v43, vcc, 0, v151, vcc
	v_lshl_add_u64 v[40:41], v[150:151], 0, s[22:23]
	global_store_dwordx4 v[42:43], v[54:57], off
	global_store_dwordx4 v[40:41], v[50:53], off offset:64
	global_store_dwordx4 v[40:41], v[28:31], off offset:512
	global_store_dwordx4 v[40:41], v[24:27], off offset:576
	s_mov_b64 s[22:23], 0x28000
	s_nop 0
	v_add_co_u32_e32 v26, vcc, s5, v150
	v_lshl_add_u64 v[24:25], v[150:151], 0, s[22:23]
	s_nop 0
	v_addc_co_u32_e32 v27, vcc, 0, v151, vcc
	global_store_dwordx4 v[26:27], v[36:39], off
	global_store_dwordx4 v[24:25], v[32:35], off offset:64
	global_store_dwordx4 v[24:25], v[12:15], off offset:512
	global_store_dwordx4 v[24:25], v[8:11], off offset:576
	s_mov_b64 s[22:23], 0x2c000
	s_nop 0
	v_add_co_u32_e32 v10, vcc, 0x2c000, v150
	v_lshl_add_u64 v[8:9], v[150:151], 0, s[22:23]
	s_nop 0
	v_addc_co_u32_e32 v11, vcc, 0, v151, vcc
	s_and_b64 vcc, exec, s[0:1]
	s_mov_b64 s[22:23], s[18:19]
	global_store_dwordx4 v[10:11], v[20:23], off
	global_store_dwordx4 v[8:9], v[16:19], off offset:64
	global_store_dwordx4 v[8:9], v[4:7], off offset:512
	global_store_dwordx4 v[8:9], v[0:3], off offset:576
	s_cbranch_vccz .LBB0_638
	s_waitcnt vmcnt(0)
	s_cmpk_gt_u32 s30, 0xff
	s_cbranch_scc1 .LBB0_645
	s_barrier

.LBB0_822:
	s_add_u32 s12, s10, 0x100
	s_addc_u32 s13, s11, 0
	s_add_i32 s42, 0, 0x10000
	v_add_u32_e32 v158, s42, v147
	ds_read_b128 v[142:145], v158
	ds_read_b128 v[150:153], v158 offset:1024
	ds_read_b128 v[154:157], v158 offset:2048
	ds_read_b128 v[158:161], v158 offset:3072
	s_cmp_eq_u32 s41, 8
	s_cselect_b32 s17, s5, s13
	s_cselect_b32 s16, s4, s12
	s_cselect_b32 s15, s7, s40
	s_cselect_b32 s14, s6, s39
	v_lshl_add_u64 v[198:199], s[10:11], 0, v[138:139]
	s_add_i32 m0, s24, 0xc000
	ds_read_b128 v[162:165], v149
	ds_read_b128 v[166:169], v149 offset:1024
	ds_read_b128 v[170:173], v149 offset:2048
	ds_read_b128 v[174:177], v149 offset:3072
	ds_read_b128 v[178:181], v149 offset:4096
	ds_read_b128 v[182:185], v149 offset:5120
	ds_read_b128 v[186:189], v149 offset:6144
	ds_read_b128 v[190:193], v149 offset:7168
	global_load_lds_dwordx4 v[198:199], off
	v_lshl_add_u64 v[198:199], s[10:11], 0, v[140:141]
	s_add_i32 m0, s24, 0xe000
	s_nop 0
	global_load_lds_dwordx4 v[198:199], off
	s_waitcnt lgkmcnt(8)
	s_barrier
	s_waitcnt lgkmcnt(0)
	s_setprio 1
	s_waitcnt lgkmcnt(0)
	v_mfma_f32_16x16x32_bf16 v[126:129], v[142:145], v[162:165], v[126:129]
	v_mfma_f32_16x16x32_bf16 v[122:125], v[154:157], v[162:165], v[122:125]
	v_mfma_f32_16x16x32_bf16 v[110:113], v[142:145], v[170:173], v[110:113]
	v_mfma_f32_16x16x32_bf16 v[106:109], v[154:157], v[170:173], v[106:109]
	v_mfma_f32_16x16x32_bf16 v[94:97], v[142:145], v[178:181], v[94:97]
	v_mfma_f32_16x16x32_bf16 v[90:93], v[154:157], v[178:181], v[90:93]
	v_mfma_f32_16x16x32_bf16 v[78:81], v[142:145], v[186:189], v[78:81]
	v_mfma_f32_16x16x32_bf16 v[74:77], v[154:157], v[186:189], v[74:77]
	v_mfma_f32_16x16x32_bf16 v[126:129], v[150:153], v[166:169], v[126:129]
	v_mfma_f32_16x16x32_bf16 v[122:125], v[158:161], v[166:169], v[122:125]
	v_mfma_f32_16x16x32_bf16 v[110:113], v[150:153], v[174:177], v[110:113]
	v_mfma_f32_16x16x32_bf16 v[106:109], v[158:161], v[174:177], v[106:109]
	v_mfma_f32_16x16x32_bf16 v[94:97], v[150:153], v[182:185], v[94:97]
	v_mfma_f32_16x16x32_bf16 v[90:93], v[158:161], v[182:185], v[90:93]
	v_mfma_f32_16x16x32_bf16 v[78:81], v[150:153], v[190:193], v[78:81]
	v_mfma_f32_16x16x32_bf16 v[74:77], v[158:161], v[190:193], v[74:77]
	s_setprio 0
	s_barrier
	s_add_i32 s43, 0, 0x14000
	s_add_i32 s10, s42, s23
	v_add_u32_e32 v210, s43, v147
	s_mov_b32 m0, s10
	ds_read_b128 v[198:201], v210
	ds_read_b128 v[202:205], v210 offset:1024
	ds_read_b128 v[206:209], v210 offset:2048
	ds_read_b128 v[210:213], v210 offset:3072
	global_load_lds_dwordx4 v134, s[14:15]
	s_add_i32 m0, s10, 0x2000
	s_nop 0
	global_load_lds_dwordx4 v130, s[14:15]
	s_barrier
	s_waitcnt lgkmcnt(0)
	s_setprio 1
	s_waitcnt lgkmcnt(0)
	v_mfma_f32_16x16x32_bf16 v[118:121], v[198:201], v[162:165], v[118:121]
	v_mfma_f32_16x16x32_bf16 v[114:117], v[206:209], v[162:165], v[114:117]
	v_mfma_f32_16x16x32_bf16 v[102:105], v[198:201], v[170:173], v[102:105]
	v_mfma_f32_16x16x32_bf16 v[98:101], v[206:209], v[170:173], v[98:101]
	v_mfma_f32_16x16x32_bf16 v[86:89], v[198:201], v[178:181], v[86:89]
	v_mfma_f32_16x16x32_bf16 v[82:85], v[206:209], v[178:181], v[82:85]
	v_mfma_f32_16x16x32_bf16 v[70:73], v[198:201], v[186:189], v[70:73]
	v_mfma_f32_16x16x32_bf16 v[66:69], v[206:209], v[186:189], v[66:69]
	v_mfma_f32_16x16x32_bf16 v[118:121], v[202:205], v[166:169], v[118:121]
	v_mfma_f32_16x16x32_bf16 v[114:117], v[210:213], v[166:169], v[114:117]
	v_mfma_f32_16x16x32_bf16 v[102:105], v[202:205], v[174:177], v[102:105]
	v_mfma_f32_16x16x32_bf16 v[98:101], v[210:213], v[174:177], v[98:101]
	v_mfma_f32_16x16x32_bf16 v[86:89], v[202:205], v[182:185], v[86:89]
	v_mfma_f32_16x16x32_bf16 v[82:85], v[210:213], v[182:185], v[82:85]
	v_mfma_f32_16x16x32_bf16 v[70:73], v[202:205], v[190:193], v[70:73]
	v_mfma_f32_16x16x32_bf16 v[66:69], v[210:213], v[190:193], v[66:69]
	s_setprio 0
	s_mov_b32 m0, s24
	v_lshl_add_u64 v[218:219], s[16:17], 0, v[136:137]
	s_barrier
	ds_read_b128 v[162:165], v149 offset:16384
	ds_read_b128 v[166:169], v149 offset:17408
	ds_read_b128 v[170:173], v149 offset:18432
	ds_read_b128 v[174:177], v149 offset:19456
	ds_read_b128 v[178:181], v149 offset:20480
	ds_read_b128 v[182:185], v149 offset:21504
	ds_read_b128 v[186:189], v149 offset:22528
	ds_read_b128 v[190:193], v149 offset:23552
	global_load_lds_dwordx4 v[218:219], off
	v_lshl_add_u64 v[220:221], s[16:17], 0, v[132:133]
	s_mov_b32 m0, s25
	s_nop 0
	global_load_lds_dwordx4 v[220:221], off
	s_barrier
	s_waitcnt lgkmcnt(0)
	s_setprio 1
	s_waitcnt lgkmcnt(0)
	v_mfma_f32_16x16x32_bf16 v[62:65], v[142:145], v[162:165], v[62:65]
	v_mfma_f32_16x16x32_bf16 v[58:61], v[154:157], v[162:165], v[58:61]
	v_mfma_f32_16x16x32_bf16 v[44:47], v[142:145], v[170:173], v[44:47]
	v_mfma_f32_16x16x32_bf16 v[40:43], v[154:157], v[170:173], v[40:43]
	v_mfma_f32_16x16x32_bf16 v[28:31], v[142:145], v[178:181], v[28:31]
	v_mfma_f32_16x16x32_bf16 v[24:27], v[154:157], v[178:181], v[24:27]
	v_mfma_f32_16x16x32_bf16 v[12:15], v[142:145], v[186:189], v[12:15]
	v_mfma_f32_16x16x32_bf16 v[8:11], v[154:157], v[186:189], v[8:11]
	v_mfma_f32_16x16x32_bf16 v[62:65], v[150:153], v[166:169], v[62:65]
	v_mfma_f32_16x16x32_bf16 v[58:61], v[158:161], v[166:169], v[58:61]
	v_mfma_f32_16x16x32_bf16 v[44:47], v[150:153], v[174:177], v[44:47]
	v_mfma_f32_16x16x32_bf16 v[40:43], v[158:161], v[174:177], v[40:43]
	v_mfma_f32_16x16x32_bf16 v[28:31], v[150:153], v[182:185], v[28:31]
	v_mfma_f32_16x16x32_bf16 v[24:27], v[158:161], v[182:185], v[24:27]
	v_mfma_f32_16x16x32_bf16 v[12:15], v[150:153], v[190:193], v[12:15]
	v_mfma_f32_16x16x32_bf16 v[8:11], v[158:161], v[190:193], v[8:11]
	s_setprio 0
	s_barrier
	s_add_u32 s10, s14, 0x30000
	s_addc_u32 s11, s15, 0
	s_add_i32 s42, s43, s23
	s_mov_b32 m0, s42
	s_nop 0
	global_load_lds_dwordx4 v134, s[10:11]
	s_add_i32 m0, s42, 0x2000
	s_nop 0
	global_load_lds_dwordx4 v130, s[10:11]
	s_waitcnt vmcnt(6)
	s_barrier
	s_setprio 1
	v_mfma_f32_16x16x32_bf16 v[54:57], v[198:201], v[162:165], v[54:57]
	v_mfma_f32_16x16x32_bf16 v[50:53], v[206:209], v[162:165], v[50:53]
	v_mfma_f32_16x16x32_bf16 v[36:39], v[198:201], v[170:173], v[36:39]
	v_mfma_f32_16x16x32_bf16 v[32:35], v[206:209], v[170:173], v[32:35]
	v_mfma_f32_16x16x32_bf16 v[20:23], v[198:201], v[178:181], v[20:23]
	v_mfma_f32_16x16x32_bf16 v[16:19], v[206:209], v[178:181], v[16:19]
	v_mfma_f32_16x16x32_bf16 v[4:7], v[198:201], v[186:189], v[4:7]
	v_mfma_f32_16x16x32_bf16 v[0:3], v[206:209], v[186:189], v[0:3]
	v_mfma_f32_16x16x32_bf16 v[54:57], v[202:205], v[166:169], v[54:57]
	v_mfma_f32_16x16x32_bf16 v[50:53], v[210:213], v[166:169], v[50:53]
	v_mfma_f32_16x16x32_bf16 v[36:39], v[202:205], v[174:177], v[36:39]
	v_mfma_f32_16x16x32_bf16 v[32:35], v[210:213], v[174:177], v[32:35]
	v_mfma_f32_16x16x32_bf16 v[20:23], v[202:205], v[182:185], v[20:23]
	v_mfma_f32_16x16x32_bf16 v[16:19], v[210:213], v[182:185], v[16:19]
	v_mfma_f32_16x16x32_bf16 v[4:7], v[202:205], v[190:193], v[4:7]
	v_mfma_f32_16x16x32_bf16 v[0:3], v[210:213], v[190:193], v[0:3]
	s_setprio 0
	s_add_i32 s42, 0, 0x18000
	v_add_u32_e32 v158, s42, v147
	s_barrier
	ds_read_b128 v[142:145], v158
	ds_read_b128 v[150:153], v158 offset:1024
	ds_read_b128 v[154:157], v158 offset:2048
	ds_read_b128 v[158:161], v158 offset:3072
	s_add_u32 s10, s16, 0x30000
	s_addc_u32 s11, s17, 0
	s_mov_b32 m0, s26
	ds_read_b128 v[162:165], v149 offset:32768
	ds_read_b128 v[166:169], v149 offset:33792
	ds_read_b128 v[170:173], v149 offset:34816
	ds_read_b128 v[174:177], v149 offset:35840
	ds_read_b128 v[178:181], v149 offset:36864
	ds_read_b128 v[182:185], v149 offset:37888
	ds_read_b128 v[186:189], v149 offset:38912
	ds_read_b128 v[190:193], v149 offset:39936
	global_load_lds_dwordx4 v136, s[10:11]
	s_mov_b32 m0, s27
	s_nop 0
	global_load_lds_dwordx4 v132, s[10:11]
	s_waitcnt lgkmcnt(8)
	s_barrier
	s_waitcnt lgkmcnt(0)
	s_setprio 1
	s_waitcnt lgkmcnt(0)
	v_mfma_f32_16x16x32_bf16 v[126:129], v[142:145], v[162:165], v[126:129]
	v_mfma_f32_16x16x32_bf16 v[122:125], v[154:157], v[162:165], v[122:125]
	v_mfma_f32_16x16x32_bf16 v[110:113], v[142:145], v[170:173], v[110:113]
	v_mfma_f32_16x16x32_bf16 v[106:109], v[154:157], v[170:173], v[106:109]
	v_mfma_f32_16x16x32_bf16 v[94:97], v[142:145], v[178:181], v[94:97]
	v_mfma_f32_16x16x32_bf16 v[90:93], v[154:157], v[178:181], v[90:93]
	v_mfma_f32_16x16x32_bf16 v[78:81], v[142:145], v[186:189], v[78:81]
	v_mfma_f32_16x16x32_bf16 v[74:77], v[154:157], v[186:189], v[74:77]
	v_mfma_f32_16x16x32_bf16 v[126:129], v[150:153], v[166:169], v[126:129]
	v_mfma_f32_16x16x32_bf16 v[122:125], v[158:161], v[166:169], v[122:125]
	v_mfma_f32_16x16x32_bf16 v[110:113], v[150:153], v[174:177], v[110:113]
	v_mfma_f32_16x16x32_bf16 v[106:109], v[158:161], v[174:177], v[106:109]
	v_mfma_f32_16x16x32_bf16 v[94:97], v[150:153], v[182:185], v[94:97]
	v_mfma_f32_16x16x32_bf16 v[90:93], v[158:161], v[182:185], v[90:93]
	v_mfma_f32_16x16x32_bf16 v[78:81], v[150:153], v[190:193], v[78:81]
	v_mfma_f32_16x16x32_bf16 v[74:77], v[158:161], v[190:193], v[74:77]
	s_setprio 0
	s_barrier
	s_add_i32 s16, 0, 0x1c000
	s_add_i32 s10, s42, s23
	v_add_u32_e32 v210, s16, v147
	s_add_u32 s72, s14, s66
	s_addc_u32 s73, s15, s67
	s_mov_b32 m0, s10
	ds_read_b128 v[198:201], v210
	ds_read_b128 v[202:205], v210 offset:1024
	ds_read_b128 v[206:209], v210 offset:2048
	ds_read_b128 v[210:213], v210 offset:3072
	global_load_lds_dwordx4 v134, s[72:73]
	s_add_u32 s72, s14, s66
	s_addc_u32 s73, s15, s67
	s_add_i32 m0, s10, 0x2000
	s_nop 0
	global_load_lds_dwordx4 v130, s[72:73]
	s_barrier
	s_waitcnt lgkmcnt(0)
	s_setprio 1
	s_waitcnt lgkmcnt(0)
	v_mfma_f32_16x16x32_bf16 v[118:121], v[198:201], v[162:165], v[118:121]
	v_mfma_f32_16x16x32_bf16 v[114:117], v[206:209], v[162:165], v[114:117]
	v_mfma_f32_16x16x32_bf16 v[102:105], v[198:201], v[170:173], v[102:105]
	v_mfma_f32_16x16x32_bf16 v[98:101], v[206:209], v[170:173], v[98:101]
	v_mfma_f32_16x16x32_bf16 v[86:89], v[198:201], v[178:181], v[86:89]
	v_mfma_f32_16x16x32_bf16 v[82:85], v[206:209], v[178:181], v[82:85]
	v_mfma_f32_16x16x32_bf16 v[70:73], v[198:201], v[186:189], v[70:73]
	v_mfma_f32_16x16x32_bf16 v[66:69], v[206:209], v[186:189], v[66:69]
	v_mfma_f32_16x16x32_bf16 v[118:121], v[202:205], v[166:169], v[118:121]
	v_mfma_f32_16x16x32_bf16 v[114:117], v[210:213], v[166:169], v[114:117]
	v_mfma_f32_16x16x32_bf16 v[102:105], v[202:205], v[174:177], v[102:105]
	v_mfma_f32_16x16x32_bf16 v[98:101], v[210:213], v[174:177], v[98:101]
	v_mfma_f32_16x16x32_bf16 v[86:89], v[202:205], v[182:185], v[86:89]
	v_mfma_f32_16x16x32_bf16 v[82:85], v[210:213], v[182:185], v[82:85]
	v_mfma_f32_16x16x32_bf16 v[70:73], v[202:205], v[190:193], v[70:73]
	v_mfma_f32_16x16x32_bf16 v[66:69], v[210:213], v[190:193], v[66:69]
	s_setprio 0
	s_mov_b32 m0, s28
	v_lshl_add_u64 v[214:215], v[218:219], 0, s[66:67]
	s_barrier
	ds_read_b128 v[162:165], v149 offset:49152
	ds_read_b128 v[166:169], v149 offset:50176
	ds_read_b128 v[170:173], v149 offset:51200
	ds_read_b128 v[174:177], v149 offset:52224
	ds_read_b128 v[178:181], v149 offset:53248
	ds_read_b128 v[182:185], v149 offset:54272
	ds_read_b128 v[186:189], v149 offset:55296
	ds_read_b128 v[190:193], v149 offset:56320
	global_load_lds_dwordx4 v[214:215], off
	v_lshl_add_u64 v[214:215], v[220:221], 0, s[66:67]
	s_mov_b32 m0, s29
	s_nop 0
	global_load_lds_dwordx4 v[214:215], off
	s_barrier
	s_waitcnt lgkmcnt(0)
	s_setprio 1
	s_waitcnt lgkmcnt(0)
	v_mfma_f32_16x16x32_bf16 v[62:65], v[142:145], v[162:165], v[62:65]
	v_mfma_f32_16x16x32_bf16 v[58:61], v[154:157], v[162:165], v[58:61]
	v_mfma_f32_16x16x32_bf16 v[44:47], v[142:145], v[170:173], v[44:47]
	v_mfma_f32_16x16x32_bf16 v[40:43], v[154:157], v[170:173], v[40:43]
	v_mfma_f32_16x16x32_bf16 v[28:31], v[142:145], v[178:181], v[28:31]
	v_mfma_f32_16x16x32_bf16 v[24:27], v[154:157], v[178:181], v[24:27]
	v_mfma_f32_16x16x32_bf16 v[12:15], v[142:145], v[186:189], v[12:15]
	v_mfma_f32_16x16x32_bf16 v[8:11], v[154:157], v[186:189], v[8:11]
	v_mfma_f32_16x16x32_bf16 v[62:65], v[150:153], v[166:169], v[62:65]
	v_mfma_f32_16x16x32_bf16 v[58:61], v[158:161], v[166:169], v[58:61]
	v_mfma_f32_16x16x32_bf16 v[44:47], v[150:153], v[174:177], v[44:47]
	v_mfma_f32_16x16x32_bf16 v[40:43], v[158:161], v[174:177], v[40:43]
	v_mfma_f32_16x16x32_bf16 v[28:31], v[150:153], v[182:185], v[28:31]
	v_mfma_f32_16x16x32_bf16 v[24:27], v[158:161], v[182:185], v[24:27]
	v_mfma_f32_16x16x32_bf16 v[12:15], v[150:153], v[190:193], v[12:15]
	v_mfma_f32_16x16x32_bf16 v[8:11], v[158:161], v[190:193], v[8:11]
	s_setprio 0
	s_barrier
	s_add_u32 s10, s14, 0x30080
	s_addc_u32 s11, s15, 0
	s_add_i32 s14, s16, s23
	s_mov_b32 m0, s14
	s_nop 0
	global_load_lds_dwordx4 v134, s[10:11]
	s_add_i32 m0, s14, 0x2000
	s_nop 0
	global_load_lds_dwordx4 v130, s[10:11]
	s_waitcnt vmcnt(6)
	s_barrier
	s_setprio 1
	v_mfma_f32_16x16x32_bf16 v[54:57], v[198:201], v[162:165], v[54:57]
	v_mfma_f32_16x16x32_bf16 v[50:53], v[206:209], v[162:165], v[50:53]
	v_mfma_f32_16x16x32_bf16 v[36:39], v[198:201], v[170:173], v[36:39]
	v_mfma_f32_16x16x32_bf16 v[32:35], v[206:209], v[170:173], v[32:35]
	v_mfma_f32_16x16x32_bf16 v[20:23], v[198:201], v[178:181], v[20:23]
	v_mfma_f32_16x16x32_bf16 v[16:19], v[206:209], v[178:181], v[16:19]
	v_mfma_f32_16x16x32_bf16 v[4:7], v[198:201], v[186:189], v[4:7]
	v_mfma_f32_16x16x32_bf16 v[0:3], v[206:209], v[186:189], v[0:3]
	v_mfma_f32_16x16x32_bf16 v[54:57], v[202:205], v[166:169], v[54:57]
	v_mfma_f32_16x16x32_bf16 v[50:53], v[210:213], v[166:169], v[50:53]
	v_mfma_f32_16x16x32_bf16 v[36:39], v[202:205], v[174:177], v[36:39]
	v_mfma_f32_16x16x32_bf16 v[32:35], v[210:213], v[174:177], v[32:35]
	v_mfma_f32_16x16x32_bf16 v[20:23], v[202:205], v[182:185], v[20:23]
	v_mfma_f32_16x16x32_bf16 v[16:19], v[210:213], v[182:185], v[16:19]
	v_mfma_f32_16x16x32_bf16 v[4:7], v[202:205], v[190:193], v[4:7]
	v_mfma_f32_16x16x32_bf16 v[0:3], v[210:213], v[190:193], v[0:3]
	s_setprio 0
	s_add_i32 s41, s41, 2
	s_add_u32 s39, s39, 0x100
	s_addc_u32 s40, s40, 0
	s_cmp_gt_u32 s41, 9
	s_mov_b64 s[10:11], s[12:13]
	s_barrier
	s_cbranch_scc0 .LBB0_822
	v_lshl_add_u32 v142, s38, 8, v146
	v_ashrrev_i32_e32 v143, 31, v142
	v_lshlrev_b64 v[144:145], 14, v[142:143]
	v_mul_f32_e32 v143, 0x3d372713, v126
	v_mul_f32_e32 v143, v126, v143
	v_fma_f32 v143, v126, v143, v126
	v_mul_f32_e32 v143, 0xbfcc422a, v143
	v_mul_f32_e32 v143, 0x3fb8aa3b, v143
	v_exp_f32_e32 v150, v143
	v_mul_f32_e32 v143, 0x3d372713, v122
	v_mul_f32_e32 v143, v122, v143
	v_fma_f32 v143, v122, v143, v122
	v_mul_f32_e32 v143, 0xbfcc422a, v143
	v_mul_f32_e32 v143, 0x3fb8aa3b, v143
	v_exp_f32_e32 v152, v143
	v_mul_f32_e32 v143, 0x3d372713, v127
	v_mul_f32_e32 v143, v127, v143
	v_fma_f32 v143, v127, v143, v127
	v_mul_f32_e32 v143, 0xbfcc422a, v143
	v_mul_f32_e32 v143, 0x3fb8aa3b, v143
	v_exp_f32_e32 v151, v143
	v_lshl_or_b32 v154, s37, 8, v148
	s_lshl_b32 s10, s36, 4
	s_ashr_i32 s11, s10, 31
	v_pk_add_f32 v[150:151], v[150:151], 1.0 op_sel_hi:[1,0]
	s_lshl_b64 s[10:11], s[10:11], 1
	s_mov_b32 s36, s31
	s_mov_b32 s37, s35
	s_mov_b32 s38, s34
	v_rcp_f32_e32 v143, v151
	s_nop 0
	v_mul_f32_e32 v143, v127, v143
	s_nop 0
	v_rcp_f32_e32 v127, v150
	s_nop 0
	v_mul_f32_e32 v150, v126, v127
	v_mul_f32_e32 v126, 0x3d372713, v123
	v_mul_f32_e32 v126, v123, v126
	v_fma_f32 v126, v123, v126, v123
	v_mul_f32_e32 v126, 0xbfcc422a, v126
	v_mul_f32_e32 v126, 0x3fb8aa3b, v126
	v_exp_f32_e32 v153, v126
	v_cvt_pk_bf16_f32 v150, v150, v143
	v_pk_add_f32 v[126:127], v[152:153], 1.0 op_sel_hi:[1,0]
	s_nop 0
	s_nop 0
	v_rcp_f32_e32 v151, v127
	s_nop 0
	v_mul_f32_e32 v152, v123, v151
	s_nop 0
	v_rcp_f32_e32 v123, v126
	s_nop 0
	v_mul_f32_e32 v153, v122, v123
	v_mul_f32_e32 v123, 0x3d372713, v124
	v_mul_f32_e32 v123, v124, v123
	v_fma_f32 v123, v124, v123, v124
	v_mul_f32_e32 v123, 0xbfcc422a, v123
	v_mul_f32_e32 v123, 0x3fb8aa3b, v123
	v_mul_f32_e32 v122, 0x3d372713, v128
	v_exp_f32_e32 v126, v123
	v_mul_f32_e32 v123, 0x3d372713, v129
	v_mul_f32_e32 v122, v128, v122
	v_mul_f32_e32 v123, v129, v123
	v_fma_f32 v122, v128, v122, v128
	v_fma_f32 v123, v129, v123, v129
	v_mul_f32_e32 v122, 0xbfcc422a, v122
	v_mul_f32_e32 v123, 0xbfcc422a, v123
	v_mul_f32_e32 v122, 0x3fb8aa3b, v122
	v_mul_f32_e32 v123, 0x3fb8aa3b, v123
	v_exp_f32_e32 v122, v122
	v_exp_f32_e32 v123, v123
	v_cvt_pk_bf16_f32 v152, v153, v152
	v_pk_add_f32 v[122:123], v[122:123], 1.0 op_sel_hi:[1,0]
	s_nop 0
	s_nop 0
	v_rcp_f32_e32 v127, v123
	s_nop 0
	v_mul_f32_e32 v129, v129, v127
	s_nop 0
	v_rcp_f32_e32 v123, v122
	s_nop 0
	v_mul_f32_e32 v128, v128, v123
	v_mul_f32_e32 v122, 0x3d372713, v125
	v_mul_f32_e32 v122, v125, v122
	v_fma_f32 v122, v125, v122, v125
	v_mul_f32_e32 v122, 0xbfcc422a, v122
	v_mul_f32_e32 v122, 0x3fb8aa3b, v122
	v_exp_f32_e32 v127, v122
	s_nop 0
	v_pk_add_f32 v[122:123], v[126:127], 1.0 op_sel_hi:[1,0]
	s_nop 0
	s_nop 0
	v_rcp_f32_e32 v126, v123
	s_nop 0
	v_mul_f32_e32 v123, v125, v126
	s_nop 0
	v_ashrrev_i32_e32 v126, 4, v154
	v_ashrrev_i32_e32 v127, 31, v126
	v_rcp_f32_e32 v125, v122
	s_nop 0
	v_mul_f32_e32 v122, v124, v125
	v_lshlrev_b64 v[124:125], 9, v[126:127]
	v_mul_f32_e32 v127, 0x3d372713, v118
	v_cvt_pk_bf16_f32 v153, v122, v123
	v_lshl_add_u64 v[122:123], s[0:1], 0, v[144:145]
	v_mul_f32_e32 v127, v118, v127
	v_cvt_pk_bf16_f32 v151, v128, v129
	v_lshl_add_u64 v[128:129], v[122:123], 0, v[124:125]
	v_fma_f32 v127, v118, v127, v118
	v_lshl_add_u64 v[128:129], v[128:129], 0, s[10:11]
	v_mul_f32_e32 v127, 0xbfcc422a, v127
	v_lshl_add_u64 v[128:129], v[128:129], 0, v[48:49]
	v_mul_f32_e32 v127, 0x3fb8aa3b, v127
	global_store_dwordx4 v[128:129], v[150:153], off
	v_exp_f32_e32 v128, v127
	v_mul_f32_e32 v127, 0x3d372713, v114
	v_mul_f32_e32 v127, v114, v127
	v_fma_f32 v127, v114, v127, v114
	v_mul_f32_e32 v127, 0xbfcc422a, v127
	v_mul_f32_e32 v127, 0x3fb8aa3b, v127
	v_exp_f32_e32 v144, v127
	v_mul_f32_e32 v127, 0x3d372713, v119
	v_mul_f32_e32 v127, v119, v127
	v_fma_f32 v127, v119, v127, v119
	v_mul_f32_e32 v127, 0xbfcc422a, v127
	v_mul_f32_e32 v127, 0x3fb8aa3b, v127
	v_exp_f32_e32 v129, v127
	s_nop 0
	v_pk_add_f32 v[128:129], v[128:129], 1.0 op_sel_hi:[1,0]
	s_nop 0
	s_nop 0
	v_rcp_f32_e32 v127, v129
	s_nop 0
	v_mul_f32_e32 v127, v119, v127
	s_nop 0
	v_rcp_f32_e32 v119, v128
	s_nop 0
	v_mul_f32_e32 v128, v118, v119
	v_mul_f32_e32 v118, 0x3d372713, v115
	v_mul_f32_e32 v118, v115, v118
	v_fma_f32 v118, v115, v118, v115
	v_mul_f32_e32 v118, 0xbfcc422a, v118
	v_mul_f32_e32 v118, 0x3fb8aa3b, v118
	v_exp_f32_e32 v145, v118
	s_nop 0
	v_pk_add_f32 v[118:119], v[144:145], 1.0 op_sel_hi:[1,0]
	s_nop 0
	s_nop 0
	v_rcp_f32_e32 v129, v119
	s_nop 0
	v_mul_f32_e32 v129, v115, v129
	s_nop 0
	v_rcp_f32_e32 v115, v118
	s_nop 0
	v_mul_f32_e32 v143, v114, v115
	v_mul_f32_e32 v115, 0x3d372713, v116
	v_mul_f32_e32 v115, v116, v115
	v_fma_f32 v115, v116, v115, v116
	v_mul_f32_e32 v115, 0xbfcc422a, v115
	v_mul_f32_e32 v115, 0x3fb8aa3b, v115
	v_mul_f32_e32 v114, 0x3d372713, v120
	v_exp_f32_e32 v118, v115
	v_mul_f32_e32 v115, 0x3d372713, v121
	v_mul_f32_e32 v114, v120, v114
	v_mul_f32_e32 v115, v121, v115
	v_fma_f32 v114, v120, v114, v120
	v_fma_f32 v115, v121, v115, v121
	v_mul_f32_e32 v114, 0xbfcc422a, v114
	v_mul_f32_e32 v115, 0xbfcc422a, v115
	v_mul_f32_e32 v114, 0x3fb8aa3b, v114
	v_mul_f32_e32 v115, 0x3fb8aa3b, v115
	v_exp_f32_e32 v114, v114
	v_exp_f32_e32 v115, v115
	s_nop 0
	v_pk_add_f32 v[114:115], v[114:115], 1.0 op_sel_hi:[1,0]
	s_nop 0
	s_nop 0
	v_rcp_f32_e32 v119, v115
	s_nop 0
	v_mul_f32_e32 v121, v121, v119
	s_nop 0
	v_rcp_f32_e32 v115, v114
	s_nop 0
	v_mul_f32_e32 v120, v120, v115
	v_mul_f32_e32 v114, 0x3d372713, v117
	v_mul_f32_e32 v114, v117, v114
	v_fma_f32 v114, v117, v114, v117
	v_mul_f32_e32 v114, 0xbfcc422a, v114
	v_mul_f32_e32 v114, 0x3fb8aa3b, v114
	v_exp_f32_e32 v119, v114
	s_nop 0
	v_pk_add_f32 v[114:115], v[118:119], 1.0 op_sel_hi:[1,0]
	s_nop 0
	s_nop 0
	v_rcp_f32_e32 v118, v115
	s_nop 0
	v_mul_f32_e32 v115, v117, v118
	s_nop 0
	v_rcp_f32_e32 v117, v114
	s_nop 0
	v_mul_f32_e32 v119, v116, v117
	v_or_b32_e32 v114, 8, v126
	v_cvt_pk_bf16_f32 v119, v119, v115
	v_ashrrev_i32_e32 v115, 31, v114
	v_lshlrev_b64 v[114:115], 9, v[114:115]
	v_cvt_pk_bf16_f32 v117, v120, v121
	v_lshl_add_u64 v[120:121], v[122:123], 0, v[114:115]
	v_lshl_add_u64 v[120:121], v[120:121], 0, s[10:11]
	v_cvt_pk_bf16_f32 v116, v128, v127
	v_cvt_pk_bf16_f32 v118, v143, v129
	v_lshl_add_u64 v[120:121], v[120:121], 0, v[48:49]
	global_store_dwordx4 v[120:121], v[116:119], off
	s_nop 1
	v_mul_f32_e32 v119, 0x3d372713, v106
	v_mul_f32_e32 v119, v106, v119
	v_fma_f32 v119, v106, v119, v106
	v_mul_f32_e32 v119, 0xbfcc422a, v119
	v_mul_f32_e32 v119, 0x3fb8aa3b, v119
	v_mul_f32_e32 v118, 0x3d372713, v110
	v_exp_f32_e32 v120, v119
	v_mul_f32_e32 v119, 0x3d372713, v111
	v_mul_f32_e32 v118, v110, v118
	v_mul_f32_e32 v119, v111, v119
	v_fma_f32 v118, v110, v118, v110
	v_fma_f32 v119, v111, v119, v111
	v_mul_f32_e32 v118, 0xbfcc422a, v118
	v_mul_f32_e32 v119, 0xbfcc422a, v119
	v_mul_f32_e32 v118, 0x3fb8aa3b, v118
	v_mul_f32_e32 v119, 0x3fb8aa3b, v119
	v_exp_f32_e32 v118, v118
	v_exp_f32_e32 v119, v119
	v_or_b32_e32 v116, 16, v142
	v_ashrrev_i32_e32 v117, 31, v116
	v_lshlrev_b64 v[116:117], 14, v[116:117]
	v_pk_add_f32 v[118:119], v[118:119], 1.0 op_sel_hi:[1,0]
	s_nop 0
	s_nop 0
	v_rcp_f32_e32 v121, v119
	s_nop 0
	v_mul_f32_e32 v119, v111, v121
	s_nop 0
	v_rcp_f32_e32 v111, v118
	s_nop 0
	v_mul_f32_e32 v118, v110, v111
	v_mul_f32_e32 v110, 0x3d372713, v107
	v_mul_f32_e32 v110, v107, v110
	v_fma_f32 v110, v107, v110, v107
	v_mul_f32_e32 v110, 0xbfcc422a, v110
	v_mul_f32_e32 v110, 0x3fb8aa3b, v110
	v_exp_f32_e32 v121, v110
	s_nop 0
	v_pk_add_f32 v[110:111], v[120:121], 1.0 op_sel_hi:[1,0]
	s_nop 0
	s_nop 0
	v_rcp_f32_e32 v120, v111
	s_nop 0
	v_mul_f32_e32 v120, v107, v120
	s_nop 0
	v_rcp_f32_e32 v107, v110
	s_nop 0
	v_mul_f32_e32 v121, v106, v107
	v_mul_f32_e32 v107, 0x3d372713, v108
	v_mul_f32_e32 v107, v108, v107
	v_fma_f32 v107, v108, v107, v108
	v_mul_f32_e32 v107, 0xbfcc422a, v107
	v_mul_f32_e32 v107, 0x3fb8aa3b, v107
	v_mul_f32_e32 v106, 0x3d372713, v112
	v_exp_f32_e32 v110, v107
	v_mul_f32_e32 v107, 0x3d372713, v113
	v_mul_f32_e32 v106, v112, v106
	v_mul_f32_e32 v107, v113, v107
	v_fma_f32 v106, v112, v106, v112
	v_fma_f32 v107, v113, v107, v113
	v_mul_f32_e32 v106, 0xbfcc422a, v106
	v_mul_f32_e32 v107, 0xbfcc422a, v107
	v_mul_f32_e32 v106, 0x3fb8aa3b, v106
	v_mul_f32_e32 v107, 0x3fb8aa3b, v107
	v_exp_f32_e32 v106, v106
	v_exp_f32_e32 v107, v107
	s_nop 0
	v_pk_add_f32 v[106:107], v[106:107], 1.0 op_sel_hi:[1,0]
	s_nop 0
	s_nop 0
	v_rcp_f32_e32 v111, v107
	s_nop 0
	v_mul_f32_e32 v113, v113, v111
	s_nop 0
	v_rcp_f32_e32 v107, v106
	s_nop 0
	v_mul_f32_e32 v112, v112, v107
	v_mul_f32_e32 v106, 0x3d372713, v109
	v_mul_f32_e32 v106, v109, v106
	v_fma_f32 v106, v109, v106, v109
	v_mul_f32_e32 v106, 0xbfcc422a, v106
	v_mul_f32_e32 v106, 0x3fb8aa3b, v106
	v_exp_f32_e32 v111, v106
	s_nop 0
	v_pk_add_f32 v[106:107], v[110:111], 1.0 op_sel_hi:[1,0]
	s_nop 0
	s_nop 0
	v_rcp_f32_e32 v110, v107
	s_nop 0
	v_mul_f32_e32 v107, v109, v110
	s_nop 0
	v_rcp_f32_e32 v109, v106
	s_nop 0
	v_mul_f32_e32 v106, v108, v109
	v_cvt_pk_bf16_f32 v111, v106, v107
	v_lshl_add_u64 v[106:107], s[0:1], 0, v[116:117]
	v_cvt_pk_bf16_f32 v109, v112, v113
	v_lshl_add_u64 v[112:113], v[106:107], 0, v[124:125]
	v_lshl_add_u64 v[112:113], v[112:113], 0, s[10:11]
	v_cvt_pk_bf16_f32 v108, v118, v119
	v_cvt_pk_bf16_f32 v110, v121, v120
	v_lshl_add_u64 v[112:113], v[112:113], 0, v[48:49]
	global_store_dwordx4 v[112:113], v[108:111], off
	s_nop 1
	v_mul_f32_e32 v109, 0x3d372713, v98
	v_mul_f32_e32 v109, v98, v109
	v_fma_f32 v109, v98, v109, v98
	v_mul_f32_e32 v109, 0xbfcc422a, v109
	v_mul_f32_e32 v109, 0x3fb8aa3b, v109
	v_mul_f32_e32 v108, 0x3d372713, v102
	v_exp_f32_e32 v110, v109
	v_mul_f32_e32 v109, 0x3d372713, v103
	v_mul_f32_e32 v108, v102, v108
	v_mul_f32_e32 v109, v103, v109
	v_fma_f32 v108, v102, v108, v102
	v_fma_f32 v109, v103, v109, v103
	v_mul_f32_e32 v108, 0xbfcc422a, v108
	v_mul_f32_e32 v109, 0xbfcc422a, v109
	v_mul_f32_e32 v108, 0x3fb8aa3b, v108
	v_mul_f32_e32 v109, 0x3fb8aa3b, v109
	v_exp_f32_e32 v108, v108
	v_exp_f32_e32 v109, v109
	s_nop 0
	v_pk_add_f32 v[108:109], v[108:109], 1.0 op_sel_hi:[1,0]
	s_nop 0
	s_nop 0
	v_rcp_f32_e32 v111, v109
	s_nop 0
	v_mul_f32_e32 v109, v103, v111
	s_nop 0
	v_rcp_f32_e32 v103, v108
	s_nop 0
	v_mul_f32_e32 v108, v102, v103
	v_mul_f32_e32 v102, 0x3d372713, v99
	v_mul_f32_e32 v102, v99, v102
	v_fma_f32 v102, v99, v102, v99
	v_mul_f32_e32 v102, 0xbfcc422a, v102
	v_mul_f32_e32 v102, 0x3fb8aa3b, v102
	v_exp_f32_e32 v111, v102
	s_nop 0
	v_pk_add_f32 v[102:103], v[110:111], 1.0 op_sel_hi:[1,0]
	s_nop 0
	s_nop 0
	v_rcp_f32_e32 v110, v103
	s_nop 0
	v_mul_f32_e32 v110, v99, v110
	s_nop 0
	v_rcp_f32_e32 v99, v102
	s_nop 0
	v_mul_f32_e32 v111, v98, v99
	v_mul_f32_e32 v99, 0x3d372713, v100
	v_mul_f32_e32 v99, v100, v99
	v_fma_f32 v99, v100, v99, v100
	v_mul_f32_e32 v99, 0xbfcc422a, v99
	v_mul_f32_e32 v99, 0x3fb8aa3b, v99
	v_mul_f32_e32 v98, 0x3d372713, v104
	v_exp_f32_e32 v102, v99
	v_mul_f32_e32 v99, 0x3d372713, v105
	v_mul_f32_e32 v98, v104, v98
	v_mul_f32_e32 v99, v105, v99
	v_fma_f32 v98, v104, v98, v104
	v_fma_f32 v99, v105, v99, v105
	v_mul_f32_e32 v98, 0xbfcc422a, v98
	v_mul_f32_e32 v99, 0xbfcc422a, v99
	v_mul_f32_e32 v98, 0x3fb8aa3b, v98
	v_mul_f32_e32 v99, 0x3fb8aa3b, v99
	v_exp_f32_e32 v98, v98
	v_exp_f32_e32 v99, v99
	s_nop 0
	v_pk_add_f32 v[98:99], v[98:99], 1.0 op_sel_hi:[1,0]
	s_nop 0
	s_nop 0
	v_rcp_f32_e32 v103, v99
	s_nop 0
	v_mul_f32_e32 v105, v105, v103
	s_nop 0
	v_rcp_f32_e32 v99, v98
	s_nop 0
	v_mul_f32_e32 v104, v104, v99
	v_mul_f32_e32 v98, 0x3d372713, v101
	v_mul_f32_e32 v98, v101, v98
	v_fma_f32 v98, v101, v98, v101
	v_mul_f32_e32 v98, 0xbfcc422a, v98
	v_mul_f32_e32 v98, 0x3fb8aa3b, v98
	v_exp_f32_e32 v103, v98
	s_nop 0
	v_pk_add_f32 v[98:99], v[102:103], 1.0 op_sel_hi:[1,0]
	s_nop 0
	s_nop 0
	v_rcp_f32_e32 v102, v99
	s_nop 0
	v_mul_f32_e32 v101, v101, v102
	s_nop 0
	v_rcp_f32_e32 v99, v98
	s_nop 0
	v_mul_f32_e32 v102, v100, v99
	v_cvt_pk_bf16_f32 v101, v102, v101
	v_lshl_add_u64 v[102:103], v[106:107], 0, v[114:115]
	v_lshl_add_u64 v[102:103], v[102:103], 0, s[10:11]
	v_cvt_pk_bf16_f32 v98, v108, v109
	v_cvt_pk_bf16_f32 v99, v104, v105
	v_cvt_pk_bf16_f32 v100, v111, v110
	v_lshl_add_u64 v[102:103], v[102:103], 0, v[48:49]
	global_store_dwordx4 v[102:103], v[98:101], off
	s_nop 1
	v_mul_f32_e32 v101, 0x3d372713, v90
	v_mul_f32_e32 v101, v90, v101
	v_fma_f32 v101, v90, v101, v90
	v_mul_f32_e32 v101, 0xbfcc422a, v101
	v_mul_f32_e32 v101, 0x3fb8aa3b, v101
	v_mul_f32_e32 v100, 0x3d372713, v94
	v_exp_f32_e32 v102, v101
	v_mul_f32_e32 v101, 0x3d372713, v95
	v_mul_f32_e32 v100, v94, v100
	v_mul_f32_e32 v101, v95, v101
	v_fma_f32 v100, v94, v100, v94
	v_fma_f32 v101, v95, v101, v95
	v_mul_f32_e32 v100, 0xbfcc422a, v100
	v_mul_f32_e32 v101, 0xbfcc422a, v101
	v_mul_f32_e32 v100, 0x3fb8aa3b, v100
	v_mul_f32_e32 v101, 0x3fb8aa3b, v101
	v_exp_f32_e32 v100, v100
	v_exp_f32_e32 v101, v101
	v_or_b32_e32 v98, 32, v142
	v_ashrrev_i32_e32 v99, 31, v98
	v_lshlrev_b64 v[98:99], 14, v[98:99]
	v_pk_add_f32 v[100:101], v[100:101], 1.0 op_sel_hi:[1,0]
	s_nop 0
	s_nop 0
	v_rcp_f32_e32 v103, v101
	s_nop 0
	v_mul_f32_e32 v101, v95, v103
	s_nop 0
	v_rcp_f32_e32 v95, v100
	s_nop 0
	v_mul_f32_e32 v100, v94, v95
	v_mul_f32_e32 v94, 0x3d372713, v91
	v_mul_f32_e32 v94, v91, v94
	v_fma_f32 v94, v91, v94, v91
	v_mul_f32_e32 v94, 0xbfcc422a, v94
	v_mul_f32_e32 v94, 0x3fb8aa3b, v94
	v_exp_f32_e32 v103, v94
	s_nop 0
	v_pk_add_f32 v[94:95], v[102:103], 1.0 op_sel_hi:[1,0]
	s_nop 0
	s_nop 0
	v_rcp_f32_e32 v102, v95
	s_nop 0
	v_mul_f32_e32 v102, v91, v102
	s_nop 0
	v_rcp_f32_e32 v91, v94
	s_nop 0
	v_mul_f32_e32 v103, v90, v91
	v_mul_f32_e32 v91, 0x3d372713, v92
	v_mul_f32_e32 v91, v92, v91
	v_fma_f32 v91, v92, v91, v92
	v_mul_f32_e32 v91, 0xbfcc422a, v91
	v_mul_f32_e32 v91, 0x3fb8aa3b, v91
	v_mul_f32_e32 v90, 0x3d372713, v96
	v_exp_f32_e32 v94, v91
	v_mul_f32_e32 v91, 0x3d372713, v97
	v_mul_f32_e32 v90, v96, v90
	v_mul_f32_e32 v91, v97, v91
	v_fma_f32 v90, v96, v90, v96
	v_fma_f32 v91, v97, v91, v97
	v_mul_f32_e32 v90, 0xbfcc422a, v90
	v_mul_f32_e32 v91, 0xbfcc422a, v91
	v_mul_f32_e32 v90, 0x3fb8aa3b, v90
	v_mul_f32_e32 v91, 0x3fb8aa3b, v91
	v_exp_f32_e32 v90, v90
	v_exp_f32_e32 v91, v91
	s_nop 0
	v_pk_add_f32 v[90:91], v[90:91], 1.0 op_sel_hi:[1,0]
	s_nop 0
	s_nop 0
	v_rcp_f32_e32 v95, v91
	s_nop 0
	v_mul_f32_e32 v97, v97, v95
	s_nop 0
	v_rcp_f32_e32 v91, v90
	s_nop 0
	v_mul_f32_e32 v96, v96, v91
	v_mul_f32_e32 v90, 0x3d372713, v93
	v_mul_f32_e32 v90, v93, v90
	v_fma_f32 v90, v93, v90, v93
	v_mul_f32_e32 v90, 0xbfcc422a, v90
	v_mul_f32_e32 v90, 0x3fb8aa3b, v90
	v_exp_f32_e32 v95, v90
	s_nop 0
	v_pk_add_f32 v[90:91], v[94:95], 1.0 op_sel_hi:[1,0]
	s_nop 0
	s_nop 0
	v_rcp_f32_e32 v94, v91
	s_nop 0
	v_mul_f32_e32 v91, v93, v94
	s_nop 0
	v_rcp_f32_e32 v93, v90
	s_nop 0
	v_mul_f32_e32 v90, v92, v93
	v_cvt_pk_bf16_f32 v95, v90, v91
	v_lshl_add_u64 v[90:91], s[0:1], 0, v[98:99]
	v_cvt_pk_bf16_f32 v93, v96, v97
	v_lshl_add_u64 v[96:97], v[90:91], 0, v[124:125]
	v_lshl_add_u64 v[96:97], v[96:97], 0, s[10:11]
	v_cvt_pk_bf16_f32 v92, v100, v101
	v_cvt_pk_bf16_f32 v94, v103, v102
	v_lshl_add_u64 v[96:97], v[96:97], 0, v[48:49]
	global_store_dwordx4 v[96:97], v[92:95], off
	s_nop 1
	v_mul_f32_e32 v93, 0x3d372713, v82
	v_mul_f32_e32 v93, v82, v93
	v_fma_f32 v93, v82, v93, v82
	v_mul_f32_e32 v93, 0xbfcc422a, v93
	v_mul_f32_e32 v93, 0x3fb8aa3b, v93
	v_mul_f32_e32 v92, 0x3d372713, v86
	v_exp_f32_e32 v94, v93
	v_mul_f32_e32 v93, 0x3d372713, v87
	v_mul_f32_e32 v92, v86, v92
	v_mul_f32_e32 v93, v87, v93
	v_fma_f32 v92, v86, v92, v86
	v_fma_f32 v93, v87, v93, v87
	v_mul_f32_e32 v92, 0xbfcc422a, v92
	v_mul_f32_e32 v93, 0xbfcc422a, v93
	v_mul_f32_e32 v92, 0x3fb8aa3b, v92
	v_mul_f32_e32 v93, 0x3fb8aa3b, v93
	v_exp_f32_e32 v92, v92
	v_exp_f32_e32 v93, v93
	s_nop 0
	v_pk_add_f32 v[92:93], v[92:93], 1.0 op_sel_hi:[1,0]
	s_nop 0
	s_nop 0
	v_rcp_f32_e32 v95, v93
	s_nop 0
	v_mul_f32_e32 v93, v87, v95
	s_nop 0
	v_rcp_f32_e32 v87, v92
	s_nop 0
	v_mul_f32_e32 v92, v86, v87
	v_mul_f32_e32 v86, 0x3d372713, v83
	v_mul_f32_e32 v86, v83, v86
	v_fma_f32 v86, v83, v86, v83
	v_mul_f32_e32 v86, 0xbfcc422a, v86
	v_mul_f32_e32 v86, 0x3fb8aa3b, v86
	v_exp_f32_e32 v95, v86
	s_nop 0
	v_pk_add_f32 v[86:87], v[94:95], 1.0 op_sel_hi:[1,0]
	s_nop 0
	s_nop 0
	v_rcp_f32_e32 v94, v87
	s_nop 0
	v_mul_f32_e32 v94, v83, v94
	s_nop 0
	v_rcp_f32_e32 v83, v86
	s_nop 0
	v_mul_f32_e32 v95, v82, v83
	v_mul_f32_e32 v83, 0x3d372713, v84
	v_mul_f32_e32 v83, v84, v83
	v_fma_f32 v83, v84, v83, v84
	v_mul_f32_e32 v83, 0xbfcc422a, v83
	v_mul_f32_e32 v83, 0x3fb8aa3b, v83
	v_mul_f32_e32 v82, 0x3d372713, v88
	v_exp_f32_e32 v86, v83
	v_mul_f32_e32 v83, 0x3d372713, v89
	v_mul_f32_e32 v82, v88, v82
	v_mul_f32_e32 v83, v89, v83
	v_fma_f32 v82, v88, v82, v88
	v_fma_f32 v83, v89, v83, v89
	v_mul_f32_e32 v82, 0xbfcc422a, v82
	v_mul_f32_e32 v83, 0xbfcc422a, v83
	v_mul_f32_e32 v82, 0x3fb8aa3b, v82
	v_mul_f32_e32 v83, 0x3fb8aa3b, v83
	v_exp_f32_e32 v82, v82
	v_exp_f32_e32 v83, v83
	s_nop 0
	v_pk_add_f32 v[82:83], v[82:83], 1.0 op_sel_hi:[1,0]
	s_nop 0
	s_nop 0
	v_rcp_f32_e32 v87, v83
	s_nop 0
	v_mul_f32_e32 v89, v89, v87
	s_nop 0
	v_rcp_f32_e32 v83, v82
	s_nop 0
	v_mul_f32_e32 v88, v88, v83
	v_mul_f32_e32 v82, 0x3d372713, v85
	v_mul_f32_e32 v82, v85, v82
	v_fma_f32 v82, v85, v82, v85
	v_mul_f32_e32 v82, 0xbfcc422a, v82
	v_mul_f32_e32 v82, 0x3fb8aa3b, v82
	v_exp_f32_e32 v87, v82
	s_nop 0
	v_pk_add_f32 v[82:83], v[86:87], 1.0 op_sel_hi:[1,0]
	s_nop 0
	s_nop 0
	v_rcp_f32_e32 v86, v83
	s_nop 0
	v_mul_f32_e32 v85, v85, v86
	s_nop 0
	v_rcp_f32_e32 v83, v82
	s_nop 0
	v_mul_f32_e32 v86, v84, v83
	v_cvt_pk_bf16_f32 v85, v86, v85
	v_lshl_add_u64 v[86:87], v[90:91], 0, v[114:115]
	v_lshl_add_u64 v[86:87], v[86:87], 0, s[10:11]
	v_cvt_pk_bf16_f32 v82, v92, v93
	v_cvt_pk_bf16_f32 v83, v88, v89
	v_cvt_pk_bf16_f32 v84, v95, v94
	v_lshl_add_u64 v[86:87], v[86:87], 0, v[48:49]
	global_store_dwordx4 v[86:87], v[82:85], off
	s_nop 1
	v_mul_f32_e32 v85, 0x3d372713, v74
	v_mul_f32_e32 v85, v74, v85
	v_fma_f32 v85, v74, v85, v74
	v_mul_f32_e32 v85, 0xbfcc422a, v85
	v_mul_f32_e32 v85, 0x3fb8aa3b, v85
	v_mul_f32_e32 v84, 0x3d372713, v78
	v_exp_f32_e32 v86, v85
	v_mul_f32_e32 v85, 0x3d372713, v79
	v_mul_f32_e32 v84, v78, v84
	v_mul_f32_e32 v85, v79, v85
	v_fma_f32 v84, v78, v84, v78
	v_fma_f32 v85, v79, v85, v79
	v_mul_f32_e32 v84, 0xbfcc422a, v84
	v_mul_f32_e32 v85, 0xbfcc422a, v85
	v_mul_f32_e32 v84, 0x3fb8aa3b, v84
	v_mul_f32_e32 v85, 0x3fb8aa3b, v85
	v_exp_f32_e32 v84, v84
	v_exp_f32_e32 v85, v85
	v_or_b32_e32 v82, 48, v142
	v_ashrrev_i32_e32 v83, 31, v82
	v_lshlrev_b64 v[82:83], 14, v[82:83]
	v_pk_add_f32 v[84:85], v[84:85], 1.0 op_sel_hi:[1,0]
	s_nop 0
	s_nop 0
	v_rcp_f32_e32 v87, v85
	s_nop 0
	v_mul_f32_e32 v85, v79, v87
	s_nop 0
	v_rcp_f32_e32 v79, v84
	s_nop 0
	v_mul_f32_e32 v84, v78, v79
	v_mul_f32_e32 v78, 0x3d372713, v75
	v_mul_f32_e32 v78, v75, v78
	v_fma_f32 v78, v75, v78, v75
	v_mul_f32_e32 v78, 0xbfcc422a, v78
	v_mul_f32_e32 v78, 0x3fb8aa3b, v78
	v_exp_f32_e32 v87, v78
	s_nop 0
	v_pk_add_f32 v[78:79], v[86:87], 1.0 op_sel_hi:[1,0]
	s_nop 0
	s_nop 0
	v_rcp_f32_e32 v86, v79
	s_nop 0
	v_mul_f32_e32 v86, v75, v86
	s_nop 0
	v_rcp_f32_e32 v75, v78
	s_nop 0
	v_mul_f32_e32 v87, v74, v75
	v_mul_f32_e32 v75, 0x3d372713, v76
	v_mul_f32_e32 v75, v76, v75
	v_fma_f32 v75, v76, v75, v76
	v_mul_f32_e32 v75, 0xbfcc422a, v75
	v_mul_f32_e32 v75, 0x3fb8aa3b, v75
	v_mul_f32_e32 v74, 0x3d372713, v80
	v_exp_f32_e32 v78, v75
	v_mul_f32_e32 v75, 0x3d372713, v81
	v_mul_f32_e32 v74, v80, v74
	v_mul_f32_e32 v75, v81, v75
	v_fma_f32 v74, v80, v74, v80
	v_fma_f32 v75, v81, v75, v81
	v_mul_f32_e32 v74, 0xbfcc422a, v74
	v_mul_f32_e32 v75, 0xbfcc422a, v75
	v_mul_f32_e32 v74, 0x3fb8aa3b, v74
	v_mul_f32_e32 v75, 0x3fb8aa3b, v75
	v_exp_f32_e32 v74, v74
	v_exp_f32_e32 v75, v75
	s_nop 0
	v_pk_add_f32 v[74:75], v[74:75], 1.0 op_sel_hi:[1,0]
	s_nop 0
	s_nop 0
	v_rcp_f32_e32 v79, v75
	s_nop 0
	v_mul_f32_e32 v81, v81, v79
	s_nop 0
	v_rcp_f32_e32 v75, v74
	s_nop 0
	v_mul_f32_e32 v80, v80, v75
	v_mul_f32_e32 v74, 0x3d372713, v77
	v_mul_f32_e32 v74, v77, v74
	v_fma_f32 v74, v77, v74, v77
	v_mul_f32_e32 v74, 0xbfcc422a, v74
	v_mul_f32_e32 v74, 0x3fb8aa3b, v74
	v_exp_f32_e32 v79, v74
	s_nop 0
	v_pk_add_f32 v[74:75], v[78:79], 1.0 op_sel_hi:[1,0]
	s_nop 0
	s_nop 0
	v_rcp_f32_e32 v78, v75
	s_nop 0
	v_mul_f32_e32 v75, v77, v78
	s_nop 0
	v_rcp_f32_e32 v77, v74
	s_nop 0
	v_mul_f32_e32 v74, v76, v77
	v_cvt_pk_bf16_f32 v79, v74, v75
	v_lshl_add_u64 v[74:75], s[0:1], 0, v[82:83]
	v_cvt_pk_bf16_f32 v77, v80, v81
	v_lshl_add_u64 v[80:81], v[74:75], 0, v[124:125]
	v_lshl_add_u64 v[80:81], v[80:81], 0, s[10:11]
	v_cvt_pk_bf16_f32 v76, v84, v85
	v_cvt_pk_bf16_f32 v78, v87, v86
	v_lshl_add_u64 v[80:81], v[80:81], 0, v[48:49]
	global_store_dwordx4 v[80:81], v[76:79], off
	s_nop 1
	v_mul_f32_e32 v77, 0x3d372713, v66
	v_mul_f32_e32 v77, v66, v77
	v_fma_f32 v77, v66, v77, v66
	v_mul_f32_e32 v77, 0xbfcc422a, v77
	v_mul_f32_e32 v77, 0x3fb8aa3b, v77
	v_mul_f32_e32 v76, 0x3d372713, v70
	v_exp_f32_e32 v78, v77
	v_mul_f32_e32 v77, 0x3d372713, v71
	v_mul_f32_e32 v76, v70, v76
	v_mul_f32_e32 v77, v71, v77
	v_fma_f32 v76, v70, v76, v70
	v_fma_f32 v77, v71, v77, v71
	v_mul_f32_e32 v76, 0xbfcc422a, v76
	v_mul_f32_e32 v77, 0xbfcc422a, v77
	v_mul_f32_e32 v76, 0x3fb8aa3b, v76
	v_mul_f32_e32 v77, 0x3fb8aa3b, v77
	v_exp_f32_e32 v76, v76
	v_exp_f32_e32 v77, v77
	s_nop 0
	v_pk_add_f32 v[76:77], v[76:77], 1.0 op_sel_hi:[1,0]
	s_nop 0
	s_nop 0
	v_rcp_f32_e32 v79, v77
	s_nop 0
	v_mul_f32_e32 v77, v71, v79
	s_nop 0
	v_rcp_f32_e32 v71, v76
	s_nop 0
	v_mul_f32_e32 v76, v70, v71
	v_mul_f32_e32 v70, 0x3d372713, v67
	v_mul_f32_e32 v70, v67, v70
	v_fma_f32 v70, v67, v70, v67
	v_mul_f32_e32 v70, 0xbfcc422a, v70
	v_mul_f32_e32 v70, 0x3fb8aa3b, v70
	v_exp_f32_e32 v79, v70
	s_nop 0
	v_pk_add_f32 v[70:71], v[78:79], 1.0 op_sel_hi:[1,0]
	s_nop 0
	s_nop 0
	v_rcp_f32_e32 v78, v71
	s_nop 0
	v_mul_f32_e32 v78, v67, v78
	s_nop 0
	v_rcp_f32_e32 v67, v70
	s_nop 0
	v_mul_f32_e32 v79, v66, v67
	v_mul_f32_e32 v67, 0x3d372713, v68
	v_mul_f32_e32 v67, v68, v67
	v_fma_f32 v67, v68, v67, v68
	v_mul_f32_e32 v67, 0xbfcc422a, v67
	v_mul_f32_e32 v67, 0x3fb8aa3b, v67
	v_mul_f32_e32 v66, 0x3d372713, v72
	v_exp_f32_e32 v70, v67
	v_mul_f32_e32 v67, 0x3d372713, v73
	v_mul_f32_e32 v66, v72, v66
	v_mul_f32_e32 v67, v73, v67
	v_fma_f32 v66, v72, v66, v72
	v_fma_f32 v67, v73, v67, v73
	v_mul_f32_e32 v66, 0xbfcc422a, v66
	v_mul_f32_e32 v67, 0xbfcc422a, v67
	v_mul_f32_e32 v66, 0x3fb8aa3b, v66
	v_mul_f32_e32 v67, 0x3fb8aa3b, v67
	v_exp_f32_e32 v66, v66
	v_exp_f32_e32 v67, v67
	s_nop 0
	v_pk_add_f32 v[66:67], v[66:67], 1.0 op_sel_hi:[1,0]
	s_nop 0
	s_nop 0
	v_rcp_f32_e32 v71, v67
	s_nop 0
	v_mul_f32_e32 v73, v73, v71
	s_nop 0
	v_rcp_f32_e32 v67, v66
	s_nop 0
	v_mul_f32_e32 v72, v72, v67
	v_mul_f32_e32 v66, 0x3d372713, v69
	v_mul_f32_e32 v66, v69, v66
	v_fma_f32 v66, v69, v66, v69
	v_mul_f32_e32 v66, 0xbfcc422a, v66
	v_mul_f32_e32 v66, 0x3fb8aa3b, v66
	v_exp_f32_e32 v71, v66
	s_nop 0
	v_pk_add_f32 v[66:67], v[70:71], 1.0 op_sel_hi:[1,0]
	s_nop 0
	s_nop 0
	v_rcp_f32_e32 v70, v67
	s_nop 0
	v_mul_f32_e32 v69, v69, v70
	s_nop 0
	v_rcp_f32_e32 v67, v66
	s_nop 0
	v_mul_f32_e32 v70, v68, v67
	v_cvt_pk_bf16_f32 v69, v70, v69
	v_lshl_add_u64 v[70:71], v[74:75], 0, v[114:115]
	v_lshl_add_u64 v[70:71], v[70:71], 0, s[10:11]
	v_cvt_pk_bf16_f32 v66, v76, v77
	v_cvt_pk_bf16_f32 v67, v72, v73
	v_cvt_pk_bf16_f32 v68, v79, v78
	v_lshl_add_u64 v[70:71], v[70:71], 0, v[48:49]
	global_store_dwordx4 v[70:71], v[66:69], off
	s_nop 1
	v_mul_f32_e32 v67, 0x3d372713, v58
	v_mul_f32_e32 v67, v58, v67
	v_fma_f32 v67, v58, v67, v58
	v_mul_f32_e32 v67, 0xbfcc422a, v67
	v_mul_f32_e32 v67, 0x3fb8aa3b, v67
	v_mul_f32_e32 v66, 0x3d372713, v62
	v_exp_f32_e32 v68, v67
	v_mul_f32_e32 v67, 0x3d372713, v63
	v_mul_f32_e32 v66, v62, v66
	v_mul_f32_e32 v67, v63, v67
	v_fma_f32 v66, v62, v66, v62
	v_fma_f32 v67, v63, v67, v63
	v_mul_f32_e32 v66, 0xbfcc422a, v66
	v_mul_f32_e32 v67, 0xbfcc422a, v67
	v_mul_f32_e32 v66, 0x3fb8aa3b, v66
	v_mul_f32_e32 v67, 0x3fb8aa3b, v67
	v_exp_f32_e32 v66, v66
	v_exp_f32_e32 v67, v67
	s_nop 0
	v_pk_add_f32 v[66:67], v[66:67], 1.0 op_sel_hi:[1,0]
	s_nop 0
	s_nop 0
	v_rcp_f32_e32 v69, v67
	s_nop 0
	v_mul_f32_e32 v67, v63, v69
	s_nop 0
	v_rcp_f32_e32 v63, v66
	s_nop 0
	v_mul_f32_e32 v66, v62, v63
	v_mul_f32_e32 v62, 0x3d372713, v59
	v_mul_f32_e32 v62, v59, v62
	v_fma_f32 v62, v59, v62, v59
	v_mul_f32_e32 v62, 0xbfcc422a, v62
	v_mul_f32_e32 v62, 0x3fb8aa3b, v62
	v_exp_f32_e32 v69, v62
	s_nop 0
	v_pk_add_f32 v[62:63], v[68:69], 1.0 op_sel_hi:[1,0]
	s_nop 0
	s_nop 0
	v_rcp_f32_e32 v68, v63
	s_nop 0
	v_mul_f32_e32 v68, v59, v68
	s_nop 0
	v_rcp_f32_e32 v59, v62
	s_nop 0
	v_mul_f32_e32 v69, v58, v59
	v_mul_f32_e32 v59, 0x3d372713, v60
	v_mul_f32_e32 v59, v60, v59
	v_fma_f32 v59, v60, v59, v60
	v_mul_f32_e32 v59, 0xbfcc422a, v59
	v_mul_f32_e32 v59, 0x3fb8aa3b, v59
	v_mul_f32_e32 v58, 0x3d372713, v64
	v_exp_f32_e32 v62, v59
	v_mul_f32_e32 v59, 0x3d372713, v65
	v_mul_f32_e32 v58, v64, v58
	v_mul_f32_e32 v59, v65, v59
	v_fma_f32 v58, v64, v58, v64
	v_fma_f32 v59, v65, v59, v65
	v_mul_f32_e32 v58, 0xbfcc422a, v58
	v_mul_f32_e32 v59, 0xbfcc422a, v59
	v_mul_f32_e32 v58, 0x3fb8aa3b, v58
	v_mul_f32_e32 v59, 0x3fb8aa3b, v59
	v_exp_f32_e32 v58, v58
	v_exp_f32_e32 v59, v59
	s_nop 0
	v_pk_add_f32 v[58:59], v[58:59], 1.0 op_sel_hi:[1,0]
	s_nop 0
	s_nop 0
	v_rcp_f32_e32 v63, v59
	s_nop 0
	v_mul_f32_e32 v65, v65, v63
	s_nop 0
	v_rcp_f32_e32 v59, v58
	s_nop 0
	v_mul_f32_e32 v64, v64, v59
	v_mul_f32_e32 v58, 0x3d372713, v61
	v_mul_f32_e32 v58, v61, v58
	v_fma_f32 v58, v61, v58, v61
	v_mul_f32_e32 v58, 0xbfcc422a, v58
	v_mul_f32_e32 v58, 0x3fb8aa3b, v58
	v_exp_f32_e32 v63, v58
	s_nop 0
	v_pk_add_f32 v[58:59], v[62:63], 1.0 op_sel_hi:[1,0]
	s_nop 0
	s_nop 0
	v_rcp_f32_e32 v62, v59
	s_nop 0
	v_mul_f32_e32 v59, v61, v62
	s_mov_b64 s[12:13], 0x200000
	v_rcp_f32_e32 v61, v58
	s_nop 0
	v_mul_f32_e32 v58, v60, v61
	v_cvt_pk_bf16_f32 v63, v58, v59
	v_lshl_add_u64 v[58:59], v[122:123], 0, s[12:13]
	v_cvt_pk_bf16_f32 v61, v64, v65
	v_lshl_add_u64 v[64:65], v[58:59], 0, v[124:125]
	v_lshl_add_u64 v[64:65], v[64:65], 0, s[10:11]
	v_cvt_pk_bf16_f32 v60, v66, v67
	v_cvt_pk_bf16_f32 v62, v69, v68
	v_lshl_add_u64 v[64:65], v[64:65], 0, v[48:49]
	global_store_dwordx4 v[64:65], v[60:63], off
	s_nop 1
	v_mul_f32_e32 v61, 0x3d372713, v50
	v_mul_f32_e32 v61, v50, v61
	v_fma_f32 v61, v50, v61, v50
	v_mul_f32_e32 v61, 0xbfcc422a, v61
	v_mul_f32_e32 v61, 0x3fb8aa3b, v61
	v_mul_f32_e32 v60, 0x3d372713, v54
	v_exp_f32_e32 v62, v61
	v_mul_f32_e32 v61, 0x3d372713, v55
	v_mul_f32_e32 v60, v54, v60
	v_mul_f32_e32 v61, v55, v61
	v_fma_f32 v60, v54, v60, v54
	v_fma_f32 v61, v55, v61, v55
	v_mul_f32_e32 v60, 0xbfcc422a, v60
	v_mul_f32_e32 v61, 0xbfcc422a, v61
	v_mul_f32_e32 v60, 0x3fb8aa3b, v60
	v_mul_f32_e32 v61, 0x3fb8aa3b, v61
	v_exp_f32_e32 v60, v60
	v_exp_f32_e32 v61, v61
	s_nop 0
	v_pk_add_f32 v[60:61], v[60:61], 1.0 op_sel_hi:[1,0]
	s_nop 0
	s_nop 0
	v_rcp_f32_e32 v63, v61
	s_nop 0
	v_mul_f32_e32 v61, v55, v63
	s_nop 0
	v_rcp_f32_e32 v55, v60
	s_nop 0
	v_mul_f32_e32 v60, v54, v55
	v_mul_f32_e32 v54, 0x3d372713, v51
	v_mul_f32_e32 v54, v51, v54
	v_fma_f32 v54, v51, v54, v51
	v_mul_f32_e32 v54, 0xbfcc422a, v54
	v_mul_f32_e32 v54, 0x3fb8aa3b, v54
	v_exp_f32_e32 v63, v54
	s_nop 0
	v_pk_add_f32 v[54:55], v[62:63], 1.0 op_sel_hi:[1,0]
	s_nop 0
	s_nop 0
	v_rcp_f32_e32 v62, v55
	s_nop 0
	v_mul_f32_e32 v62, v51, v62
	s_nop 0
	v_rcp_f32_e32 v51, v54
	s_nop 0
	v_mul_f32_e32 v63, v50, v51
	v_mul_f32_e32 v51, 0x3d372713, v52
	v_mul_f32_e32 v51, v52, v51
	v_fma_f32 v51, v52, v51, v52
	v_mul_f32_e32 v51, 0xbfcc422a, v51
	v_mul_f32_e32 v51, 0x3fb8aa3b, v51
	v_mul_f32_e32 v50, 0x3d372713, v56
	v_exp_f32_e32 v54, v51
	v_mul_f32_e32 v51, 0x3d372713, v57
	v_mul_f32_e32 v50, v56, v50
	v_mul_f32_e32 v51, v57, v51
	v_fma_f32 v50, v56, v50, v56
	v_fma_f32 v51, v57, v51, v57
	v_mul_f32_e32 v50, 0xbfcc422a, v50
	v_mul_f32_e32 v51, 0xbfcc422a, v51
	v_mul_f32_e32 v50, 0x3fb8aa3b, v50
	v_mul_f32_e32 v51, 0x3fb8aa3b, v51
	v_exp_f32_e32 v50, v50
	v_exp_f32_e32 v51, v51
	s_nop 0
	v_pk_add_f32 v[50:51], v[50:51], 1.0 op_sel_hi:[1,0]
	s_nop 0
	s_nop 0
	v_rcp_f32_e32 v55, v51
	s_nop 0
	v_mul_f32_e32 v57, v57, v55
	s_nop 0
	v_rcp_f32_e32 v51, v50
	s_nop 0
	v_mul_f32_e32 v56, v56, v51
	v_mul_f32_e32 v50, 0x3d372713, v53
	v_mul_f32_e32 v50, v53, v50
	v_fma_f32 v50, v53, v50, v53
	v_mul_f32_e32 v50, 0xbfcc422a, v50
	v_mul_f32_e32 v50, 0x3fb8aa3b, v50
	v_exp_f32_e32 v55, v50
	s_nop 0
	v_pk_add_f32 v[50:51], v[54:55], 1.0 op_sel_hi:[1,0]
	s_nop 0
	s_nop 0
	v_rcp_f32_e32 v54, v51
	s_nop 0
	v_mul_f32_e32 v53, v53, v54
	s_nop 0
	v_rcp_f32_e32 v51, v50
	s_nop 0
	v_mul_f32_e32 v54, v52, v51
	v_cvt_pk_bf16_f32 v53, v54, v53
	v_lshl_add_u64 v[54:55], v[58:59], 0, v[114:115]
	v_lshl_add_u64 v[54:55], v[54:55], 0, s[10:11]
	v_cvt_pk_bf16_f32 v50, v60, v61
	v_cvt_pk_bf16_f32 v51, v56, v57
	v_cvt_pk_bf16_f32 v52, v63, v62
	v_lshl_add_u64 v[54:55], v[54:55], 0, v[48:49]
	global_store_dwordx4 v[54:55], v[50:53], off
	s_nop 1
	v_mul_f32_e32 v51, 0x3d372713, v40
	v_mul_f32_e32 v51, v40, v51
	v_fma_f32 v51, v40, v51, v40
	v_mul_f32_e32 v51, 0xbfcc422a, v51
	v_mul_f32_e32 v51, 0x3fb8aa3b, v51
	v_mul_f32_e32 v50, 0x3d372713, v44
	v_exp_f32_e32 v52, v51
	v_mul_f32_e32 v51, 0x3d372713, v45
	v_mul_f32_e32 v50, v44, v50
	v_mul_f32_e32 v51, v45, v51
	v_fma_f32 v50, v44, v50, v44
	v_fma_f32 v51, v45, v51, v45
	v_mul_f32_e32 v50, 0xbfcc422a, v50
	v_mul_f32_e32 v51, 0xbfcc422a, v51
	v_mul_f32_e32 v50, 0x3fb8aa3b, v50
	v_mul_f32_e32 v51, 0x3fb8aa3b, v51
	v_exp_f32_e32 v50, v50
	v_exp_f32_e32 v51, v51
	s_nop 0
	v_pk_add_f32 v[50:51], v[50:51], 1.0 op_sel_hi:[1,0]
	s_nop 0
	s_nop 0
	v_rcp_f32_e32 v53, v51
	s_nop 0
	v_mul_f32_e32 v51, v45, v53
	s_nop 0
	v_rcp_f32_e32 v45, v50
	s_nop 0
	v_mul_f32_e32 v50, v44, v45
	v_mul_f32_e32 v44, 0x3d372713, v41
	v_mul_f32_e32 v44, v41, v44
	v_fma_f32 v44, v41, v44, v41
	v_mul_f32_e32 v44, 0xbfcc422a, v44
	v_mul_f32_e32 v44, 0x3fb8aa3b, v44
	v_exp_f32_e32 v53, v44
	s_nop 0
	v_pk_add_f32 v[44:45], v[52:53], 1.0 op_sel_hi:[1,0]
	s_nop 0
	s_nop 0
	v_rcp_f32_e32 v52, v45
	s_nop 0
	v_mul_f32_e32 v52, v41, v52
	s_nop 0
	v_rcp_f32_e32 v41, v44
	s_nop 0
	v_mul_f32_e32 v53, v40, v41
	v_mul_f32_e32 v41, 0x3d372713, v42
	v_mul_f32_e32 v41, v42, v41
	v_fma_f32 v41, v42, v41, v42
	v_mul_f32_e32 v41, 0xbfcc422a, v41
	v_mul_f32_e32 v41, 0x3fb8aa3b, v41
	v_mul_f32_e32 v40, 0x3d372713, v46
	v_exp_f32_e32 v44, v41
	v_mul_f32_e32 v41, 0x3d372713, v47
	v_mul_f32_e32 v40, v46, v40
	v_mul_f32_e32 v41, v47, v41
	v_fma_f32 v40, v46, v40, v46
	v_fma_f32 v41, v47, v41, v47
	v_mul_f32_e32 v40, 0xbfcc422a, v40
	v_mul_f32_e32 v41, 0xbfcc422a, v41
	v_mul_f32_e32 v40, 0x3fb8aa3b, v40
	v_mul_f32_e32 v41, 0x3fb8aa3b, v41
	v_exp_f32_e32 v40, v40
	v_exp_f32_e32 v41, v41
	s_nop 0
	v_pk_add_f32 v[40:41], v[40:41], 1.0 op_sel_hi:[1,0]
	s_nop 0
	s_nop 0
	v_rcp_f32_e32 v45, v41
	s_nop 0
	v_mul_f32_e32 v47, v47, v45
	s_nop 0
	v_rcp_f32_e32 v41, v40
	s_nop 0
	v_mul_f32_e32 v46, v46, v41
	v_mul_f32_e32 v40, 0x3d372713, v43
	v_mul_f32_e32 v40, v43, v40
	v_fma_f32 v40, v43, v40, v43
	v_mul_f32_e32 v40, 0xbfcc422a, v40
	v_mul_f32_e32 v40, 0x3fb8aa3b, v40
	v_exp_f32_e32 v45, v40
	s_nop 0
	v_pk_add_f32 v[40:41], v[44:45], 1.0 op_sel_hi:[1,0]
	s_nop 0
	s_nop 0
	v_rcp_f32_e32 v44, v41
	s_nop 0
	v_mul_f32_e32 v41, v43, v44
	s_mov_b64 s[12:13], 0x240000
	v_rcp_f32_e32 v43, v40
	s_nop 0
	v_mul_f32_e32 v40, v42, v43
	v_cvt_pk_bf16_f32 v45, v40, v41
	v_lshl_add_u64 v[40:41], v[122:123], 0, s[12:13]
	v_cvt_pk_bf16_f32 v43, v46, v47
	v_lshl_add_u64 v[46:47], v[40:41], 0, v[124:125]
	v_lshl_add_u64 v[46:47], v[46:47], 0, s[10:11]
	v_cvt_pk_bf16_f32 v42, v50, v51
	v_cvt_pk_bf16_f32 v44, v53, v52
	v_lshl_add_u64 v[46:47], v[46:47], 0, v[48:49]
	global_store_dwordx4 v[46:47], v[42:45], off
	s_nop 1
	v_mul_f32_e32 v43, 0x3d372713, v32
	v_mul_f32_e32 v43, v32, v43
	v_fma_f32 v43, v32, v43, v32
	v_mul_f32_e32 v43, 0xbfcc422a, v43
	v_mul_f32_e32 v43, 0x3fb8aa3b, v43
	v_mul_f32_e32 v42, 0x3d372713, v36
	v_exp_f32_e32 v44, v43
	v_mul_f32_e32 v43, 0x3d372713, v37
	v_mul_f32_e32 v42, v36, v42
	v_mul_f32_e32 v43, v37, v43
	v_fma_f32 v42, v36, v42, v36
	v_fma_f32 v43, v37, v43, v37
	v_mul_f32_e32 v42, 0xbfcc422a, v42
	v_mul_f32_e32 v43, 0xbfcc422a, v43
	v_mul_f32_e32 v42, 0x3fb8aa3b, v42
	v_mul_f32_e32 v43, 0x3fb8aa3b, v43
	v_exp_f32_e32 v42, v42
	v_exp_f32_e32 v43, v43
	s_nop 0
	v_pk_add_f32 v[42:43], v[42:43], 1.0 op_sel_hi:[1,0]
	s_nop 0
	s_nop 0
	v_rcp_f32_e32 v45, v43
	s_nop 0
	v_mul_f32_e32 v43, v37, v45
	s_nop 0
	v_rcp_f32_e32 v37, v42
	s_nop 0
	v_mul_f32_e32 v42, v36, v37
	v_mul_f32_e32 v36, 0x3d372713, v33
	v_mul_f32_e32 v36, v33, v36
	v_fma_f32 v36, v33, v36, v33
	v_mul_f32_e32 v36, 0xbfcc422a, v36
	v_mul_f32_e32 v36, 0x3fb8aa3b, v36
	v_exp_f32_e32 v45, v36
	s_nop 0
	v_pk_add_f32 v[36:37], v[44:45], 1.0 op_sel_hi:[1,0]
	s_nop 0
	s_nop 0
	v_rcp_f32_e32 v44, v37
	s_nop 0
	v_mul_f32_e32 v44, v33, v44
	s_nop 0
	v_rcp_f32_e32 v33, v36
	s_nop 0
	v_mul_f32_e32 v45, v32, v33
	v_mul_f32_e32 v33, 0x3d372713, v34
	v_mul_f32_e32 v33, v34, v33
	v_fma_f32 v33, v34, v33, v34
	v_mul_f32_e32 v33, 0xbfcc422a, v33
	v_mul_f32_e32 v33, 0x3fb8aa3b, v33
	v_mul_f32_e32 v32, 0x3d372713, v38
	v_exp_f32_e32 v36, v33
	v_mul_f32_e32 v33, 0x3d372713, v39
	v_mul_f32_e32 v32, v38, v32
	v_mul_f32_e32 v33, v39, v33
	v_fma_f32 v32, v38, v32, v38
	v_fma_f32 v33, v39, v33, v39
	v_mul_f32_e32 v32, 0xbfcc422a, v32
	v_mul_f32_e32 v33, 0xbfcc422a, v33
	v_mul_f32_e32 v32, 0x3fb8aa3b, v32
	v_mul_f32_e32 v33, 0x3fb8aa3b, v33
	v_exp_f32_e32 v32, v32
	v_exp_f32_e32 v33, v33
	s_nop 0
	v_pk_add_f32 v[32:33], v[32:33], 1.0 op_sel_hi:[1,0]
	s_nop 0
	s_nop 0
	v_rcp_f32_e32 v37, v33
	s_nop 0
	v_mul_f32_e32 v39, v39, v37
	s_nop 0
	v_rcp_f32_e32 v33, v32
	s_nop 0
	v_mul_f32_e32 v38, v38, v33
	v_mul_f32_e32 v32, 0x3d372713, v35
	v_mul_f32_e32 v32, v35, v32
	v_fma_f32 v32, v35, v32, v35
	v_mul_f32_e32 v32, 0xbfcc422a, v32
	v_mul_f32_e32 v32, 0x3fb8aa3b, v32
	v_exp_f32_e32 v37, v32
	s_nop 0
	v_pk_add_f32 v[32:33], v[36:37], 1.0 op_sel_hi:[1,0]
	s_nop 0
	s_nop 0
	v_rcp_f32_e32 v36, v33
	s_nop 0
	v_mul_f32_e32 v35, v35, v36
	s_nop 0
	v_rcp_f32_e32 v33, v32
	s_nop 0
	v_mul_f32_e32 v36, v34, v33
	v_cvt_pk_bf16_f32 v35, v36, v35
	v_lshl_add_u64 v[36:37], v[40:41], 0, v[114:115]
	v_lshl_add_u64 v[36:37], v[36:37], 0, s[10:11]
	v_cvt_pk_bf16_f32 v32, v42, v43
	v_cvt_pk_bf16_f32 v33, v38, v39
	v_cvt_pk_bf16_f32 v34, v45, v44
	v_lshl_add_u64 v[36:37], v[36:37], 0, v[48:49]
	global_store_dwordx4 v[36:37], v[32:35], off
	s_nop 1
	v_mul_f32_e32 v33, 0x3d372713, v24
	v_mul_f32_e32 v33, v24, v33
	v_fma_f32 v33, v24, v33, v24
	v_mul_f32_e32 v33, 0xbfcc422a, v33
	v_mul_f32_e32 v33, 0x3fb8aa3b, v33
	v_mul_f32_e32 v32, 0x3d372713, v28
	v_exp_f32_e32 v34, v33
	v_mul_f32_e32 v33, 0x3d372713, v29
	v_mul_f32_e32 v32, v28, v32
	v_mul_f32_e32 v33, v29, v33
	v_fma_f32 v32, v28, v32, v28
	v_fma_f32 v33, v29, v33, v29
	v_mul_f32_e32 v32, 0xbfcc422a, v32
	v_mul_f32_e32 v33, 0xbfcc422a, v33
	v_mul_f32_e32 v32, 0x3fb8aa3b, v32
	v_mul_f32_e32 v33, 0x3fb8aa3b, v33
	v_exp_f32_e32 v32, v32
	v_exp_f32_e32 v33, v33
	s_nop 0
	v_pk_add_f32 v[32:33], v[32:33], 1.0 op_sel_hi:[1,0]
	s_nop 0
	s_nop 0
	v_rcp_f32_e32 v35, v33
	s_nop 0
	v_mul_f32_e32 v33, v29, v35
	s_nop 0
	v_rcp_f32_e32 v29, v32
	s_nop 0
	v_mul_f32_e32 v32, v28, v29
	v_mul_f32_e32 v28, 0x3d372713, v25
	v_mul_f32_e32 v28, v25, v28
	v_fma_f32 v28, v25, v28, v25
	v_mul_f32_e32 v28, 0xbfcc422a, v28
	v_mul_f32_e32 v28, 0x3fb8aa3b, v28
	v_exp_f32_e32 v35, v28
	s_nop 0
	v_pk_add_f32 v[28:29], v[34:35], 1.0 op_sel_hi:[1,0]
	s_nop 0
	s_nop 0
	v_rcp_f32_e32 v34, v29
	s_nop 0
	v_mul_f32_e32 v34, v25, v34
	s_nop 0
	v_rcp_f32_e32 v25, v28
	s_nop 0
	v_mul_f32_e32 v35, v24, v25
	v_mul_f32_e32 v25, 0x3d372713, v26
	v_mul_f32_e32 v25, v26, v25
	v_fma_f32 v25, v26, v25, v26
	v_mul_f32_e32 v25, 0xbfcc422a, v25
	v_mul_f32_e32 v25, 0x3fb8aa3b, v25
	v_mul_f32_e32 v24, 0x3d372713, v30
	v_exp_f32_e32 v28, v25
	v_mul_f32_e32 v25, 0x3d372713, v31
	v_mul_f32_e32 v24, v30, v24
	v_mul_f32_e32 v25, v31, v25
	v_fma_f32 v24, v30, v24, v30
	v_fma_f32 v25, v31, v25, v31
	v_mul_f32_e32 v24, 0xbfcc422a, v24
	v_mul_f32_e32 v25, 0xbfcc422a, v25
	v_mul_f32_e32 v24, 0x3fb8aa3b, v24
	v_mul_f32_e32 v25, 0x3fb8aa3b, v25
	v_exp_f32_e32 v24, v24
	v_exp_f32_e32 v25, v25
	s_nop 0
	v_pk_add_f32 v[24:25], v[24:25], 1.0 op_sel_hi:[1,0]
	s_nop 0
	s_nop 0
	v_rcp_f32_e32 v29, v25
	s_nop 0
	v_mul_f32_e32 v31, v31, v29
	s_nop 0
	v_rcp_f32_e32 v25, v24
	s_nop 0
	v_mul_f32_e32 v30, v30, v25
	v_mul_f32_e32 v24, 0x3d372713, v27
	v_mul_f32_e32 v24, v27, v24
	v_fma_f32 v24, v27, v24, v27
	v_mul_f32_e32 v24, 0xbfcc422a, v24
	v_mul_f32_e32 v24, 0x3fb8aa3b, v24
	v_exp_f32_e32 v29, v24
	s_nop 0
	v_pk_add_f32 v[24:25], v[28:29], 1.0 op_sel_hi:[1,0]
	s_nop 0
	s_nop 0
	v_rcp_f32_e32 v28, v25
	s_nop 0
	v_mul_f32_e32 v25, v27, v28
	s_mov_b64 s[12:13], 0x280000
	v_rcp_f32_e32 v27, v24
	s_nop 0
	v_mul_f32_e32 v24, v26, v27
	v_cvt_pk_bf16_f32 v29, v24, v25
	v_lshl_add_u64 v[24:25], v[122:123], 0, s[12:13]
	v_cvt_pk_bf16_f32 v27, v30, v31
	v_lshl_add_u64 v[30:31], v[24:25], 0, v[124:125]
	v_lshl_add_u64 v[30:31], v[30:31], 0, s[10:11]
	v_cvt_pk_bf16_f32 v26, v32, v33
	v_cvt_pk_bf16_f32 v28, v35, v34
	v_lshl_add_u64 v[30:31], v[30:31], 0, v[48:49]
	global_store_dwordx4 v[30:31], v[26:29], off
	s_nop 1
	v_mul_f32_e32 v27, 0x3d372713, v16
	v_mul_f32_e32 v27, v16, v27
	v_fma_f32 v27, v16, v27, v16
	v_mul_f32_e32 v27, 0xbfcc422a, v27
	v_mul_f32_e32 v27, 0x3fb8aa3b, v27
	v_mul_f32_e32 v26, 0x3d372713, v20
	v_exp_f32_e32 v28, v27
	v_mul_f32_e32 v27, 0x3d372713, v21
	v_mul_f32_e32 v26, v20, v26
	v_mul_f32_e32 v27, v21, v27
	v_fma_f32 v26, v20, v26, v20
	v_fma_f32 v27, v21, v27, v21
	v_mul_f32_e32 v26, 0xbfcc422a, v26
	v_mul_f32_e32 v27, 0xbfcc422a, v27
	v_mul_f32_e32 v26, 0x3fb8aa3b, v26
	v_mul_f32_e32 v27, 0x3fb8aa3b, v27
	v_exp_f32_e32 v26, v26
	v_exp_f32_e32 v27, v27
	s_nop 0
	v_pk_add_f32 v[26:27], v[26:27], 1.0 op_sel_hi:[1,0]
	s_nop 0
	s_nop 0
	v_rcp_f32_e32 v29, v27
	s_nop 0
	v_mul_f32_e32 v27, v21, v29
	s_nop 0
	v_rcp_f32_e32 v21, v26
	s_nop 0
	v_mul_f32_e32 v26, v20, v21
	v_mul_f32_e32 v20, 0x3d372713, v17
	v_mul_f32_e32 v20, v17, v20
	v_fma_f32 v20, v17, v20, v17
	v_mul_f32_e32 v20, 0xbfcc422a, v20
	v_mul_f32_e32 v20, 0x3fb8aa3b, v20
	v_exp_f32_e32 v29, v20
	s_nop 0
	v_pk_add_f32 v[20:21], v[28:29], 1.0 op_sel_hi:[1,0]
	s_nop 0
	s_nop 0
	v_rcp_f32_e32 v28, v21
	s_nop 0
	v_mul_f32_e32 v28, v17, v28
	s_nop 0
	v_rcp_f32_e32 v17, v20
	s_nop 0
	v_mul_f32_e32 v29, v16, v17
	v_mul_f32_e32 v17, 0x3d372713, v18
	v_mul_f32_e32 v17, v18, v17
	v_fma_f32 v17, v18, v17, v18
	v_mul_f32_e32 v17, 0xbfcc422a, v17
	v_mul_f32_e32 v17, 0x3fb8aa3b, v17
	v_mul_f32_e32 v16, 0x3d372713, v22
	v_exp_f32_e32 v20, v17
	v_mul_f32_e32 v17, 0x3d372713, v23
	v_mul_f32_e32 v16, v22, v16
	v_mul_f32_e32 v17, v23, v17
	v_fma_f32 v16, v22, v16, v22
	v_fma_f32 v17, v23, v17, v23
	v_mul_f32_e32 v16, 0xbfcc422a, v16
	v_mul_f32_e32 v17, 0xbfcc422a, v17
	v_mul_f32_e32 v16, 0x3fb8aa3b, v16
	v_mul_f32_e32 v17, 0x3fb8aa3b, v17
	v_exp_f32_e32 v16, v16
	v_exp_f32_e32 v17, v17
	s_nop 0
	v_pk_add_f32 v[16:17], v[16:17], 1.0 op_sel_hi:[1,0]
	s_nop 0
	s_nop 0
	v_rcp_f32_e32 v21, v17
	s_nop 0
	v_mul_f32_e32 v23, v23, v21
	s_nop 0
	v_rcp_f32_e32 v17, v16
	s_nop 0
	v_mul_f32_e32 v22, v22, v17
	v_mul_f32_e32 v16, 0x3d372713, v19
	v_mul_f32_e32 v16, v19, v16
	v_fma_f32 v16, v19, v16, v19
	v_mul_f32_e32 v16, 0xbfcc422a, v16
	v_mul_f32_e32 v16, 0x3fb8aa3b, v16
	v_exp_f32_e32 v21, v16
	s_nop 0
	v_pk_add_f32 v[16:17], v[20:21], 1.0 op_sel_hi:[1,0]
	s_nop 0
	s_nop 0
	v_rcp_f32_e32 v20, v17
	s_nop 0
	v_mul_f32_e32 v19, v19, v20
	s_nop 0
	v_rcp_f32_e32 v17, v16
	s_nop 0
	v_mul_f32_e32 v20, v18, v17
	v_cvt_pk_bf16_f32 v19, v20, v19
	v_lshl_add_u64 v[20:21], v[24:25], 0, v[114:115]
	v_lshl_add_u64 v[20:21], v[20:21], 0, s[10:11]
	v_cvt_pk_bf16_f32 v16, v26, v27
	v_cvt_pk_bf16_f32 v17, v22, v23
	v_cvt_pk_bf16_f32 v18, v29, v28
	v_lshl_add_u64 v[20:21], v[20:21], 0, v[48:49]
	global_store_dwordx4 v[20:21], v[16:19], off
	s_nop 1
	v_mul_f32_e32 v17, 0x3d372713, v8
	v_mul_f32_e32 v17, v8, v17
	v_fma_f32 v17, v8, v17, v8
	v_mul_f32_e32 v17, 0xbfcc422a, v17
	v_mul_f32_e32 v17, 0x3fb8aa3b, v17
	v_mul_f32_e32 v16, 0x3d372713, v12
	v_exp_f32_e32 v18, v17
	v_mul_f32_e32 v17, 0x3d372713, v13
	v_mul_f32_e32 v16, v12, v16
	v_mul_f32_e32 v17, v13, v17
	v_fma_f32 v16, v12, v16, v12
	v_fma_f32 v17, v13, v17, v13
	v_mul_f32_e32 v16, 0xbfcc422a, v16
	v_mul_f32_e32 v17, 0xbfcc422a, v17
	v_mul_f32_e32 v16, 0x3fb8aa3b, v16
	v_mul_f32_e32 v17, 0x3fb8aa3b, v17
	v_exp_f32_e32 v16, v16
	v_exp_f32_e32 v17, v17
	s_nop 0
	v_pk_add_f32 v[16:17], v[16:17], 1.0 op_sel_hi:[1,0]
	s_nop 0
	s_nop 0
	v_rcp_f32_e32 v19, v17
	s_nop 0
	v_mul_f32_e32 v17, v13, v19
	s_nop 0
	v_rcp_f32_e32 v13, v16
	s_nop 0
	v_mul_f32_e32 v16, v12, v13
	v_mul_f32_e32 v12, 0x3d372713, v9
	v_mul_f32_e32 v12, v9, v12
	v_fma_f32 v12, v9, v12, v9
	v_mul_f32_e32 v12, 0xbfcc422a, v12
	v_mul_f32_e32 v12, 0x3fb8aa3b, v12
	v_exp_f32_e32 v19, v12
	s_nop 0
	v_pk_add_f32 v[12:13], v[18:19], 1.0 op_sel_hi:[1,0]
	s_nop 0
	s_nop 0
	v_rcp_f32_e32 v18, v13
	s_nop 0
	v_mul_f32_e32 v18, v9, v18
	s_nop 0
	v_rcp_f32_e32 v9, v12
	s_nop 0
	v_mul_f32_e32 v19, v8, v9
	v_mul_f32_e32 v9, 0x3d372713, v10
	v_mul_f32_e32 v9, v10, v9
	v_fma_f32 v9, v10, v9, v10
	v_mul_f32_e32 v9, 0xbfcc422a, v9
	v_mul_f32_e32 v9, 0x3fb8aa3b, v9
	v_mul_f32_e32 v8, 0x3d372713, v14
	v_exp_f32_e32 v12, v9
	v_mul_f32_e32 v9, 0x3d372713, v15
	v_mul_f32_e32 v8, v14, v8
	v_mul_f32_e32 v9, v15, v9
	v_fma_f32 v8, v14, v8, v14
	v_fma_f32 v9, v15, v9, v15
	v_mul_f32_e32 v8, 0xbfcc422a, v8
	v_mul_f32_e32 v9, 0xbfcc422a, v9
	v_mul_f32_e32 v8, 0x3fb8aa3b, v8
	v_mul_f32_e32 v9, 0x3fb8aa3b, v9
	v_exp_f32_e32 v8, v8
	v_exp_f32_e32 v9, v9
	s_nop 0
	v_pk_add_f32 v[8:9], v[8:9], 1.0 op_sel_hi:[1,0]
	s_nop 0
	s_nop 0
	v_rcp_f32_e32 v13, v9
	s_nop 0
	v_mul_f32_e32 v15, v15, v13
	s_nop 0
	v_rcp_f32_e32 v9, v8
	s_nop 0
	v_mul_f32_e32 v14, v14, v9
	v_mul_f32_e32 v8, 0x3d372713, v11
	v_mul_f32_e32 v8, v11, v8
	v_fma_f32 v8, v11, v8, v11
	v_mul_f32_e32 v8, 0xbfcc422a, v8
	v_mul_f32_e32 v8, 0x3fb8aa3b, v8
	v_exp_f32_e32 v13, v8
	s_nop 0
	v_pk_add_f32 v[8:9], v[12:13], 1.0 op_sel_hi:[1,0]
	s_nop 0
	s_nop 0
	v_rcp_f32_e32 v12, v9
	s_nop 0
	v_mul_f32_e32 v9, v11, v12
	s_mov_b64 s[12:13], 0x2c0000
	v_rcp_f32_e32 v11, v8
	s_nop 0
	v_mul_f32_e32 v8, v10, v11
	v_cvt_pk_bf16_f32 v13, v8, v9
	v_lshl_add_u64 v[8:9], v[122:123], 0, s[12:13]
	v_cvt_pk_bf16_f32 v11, v14, v15
	v_lshl_add_u64 v[14:15], v[8:9], 0, v[124:125]
	v_lshl_add_u64 v[14:15], v[14:15], 0, s[10:11]
	v_cvt_pk_bf16_f32 v10, v16, v17
	v_cvt_pk_bf16_f32 v12, v19, v18
	v_lshl_add_u64 v[14:15], v[14:15], 0, v[48:49]
	global_store_dwordx4 v[14:15], v[10:13], off
	s_nop 1
	v_mul_f32_e32 v11, 0x3d372713, v0
	v_mul_f32_e32 v11, v0, v11
	v_fma_f32 v11, v0, v11, v0
	v_mul_f32_e32 v11, 0xbfcc422a, v11
	v_mul_f32_e32 v11, 0x3fb8aa3b, v11
	v_mul_f32_e32 v10, 0x3d372713, v4
	v_exp_f32_e32 v12, v11
	v_mul_f32_e32 v11, 0x3d372713, v5
	v_mul_f32_e32 v10, v4, v10
	v_mul_f32_e32 v11, v5, v11
	v_fma_f32 v10, v4, v10, v4
	v_fma_f32 v11, v5, v11, v5
	v_mul_f32_e32 v10, 0xbfcc422a, v10
	v_mul_f32_e32 v11, 0xbfcc422a, v11
	v_mul_f32_e32 v10, 0x3fb8aa3b, v10
	v_mul_f32_e32 v11, 0x3fb8aa3b, v11
	v_exp_f32_e32 v10, v10
	v_exp_f32_e32 v11, v11
	s_nop 0
	v_pk_add_f32 v[10:11], v[10:11], 1.0 op_sel_hi:[1,0]
	s_nop 0
	s_nop 0
	v_rcp_f32_e32 v13, v11
	s_nop 0
	v_mul_f32_e32 v11, v5, v13
	s_nop 0
	v_rcp_f32_e32 v5, v10
	s_nop 0
	v_mul_f32_e32 v10, v4, v5
	v_mul_f32_e32 v4, 0x3d372713, v1
	v_mul_f32_e32 v4, v1, v4
	v_fma_f32 v4, v1, v4, v1
	v_mul_f32_e32 v4, 0xbfcc422a, v4
	v_mul_f32_e32 v4, 0x3fb8aa3b, v4
	v_exp_f32_e32 v13, v4
	s_nop 0
	v_pk_add_f32 v[4:5], v[12:13], 1.0 op_sel_hi:[1,0]
	s_nop 0
	s_nop 0
	v_rcp_f32_e32 v12, v5
	s_nop 0
	v_mul_f32_e32 v12, v1, v12
	s_nop 0
	v_rcp_f32_e32 v1, v4
	s_nop 0
	v_mul_f32_e32 v13, v0, v1
	v_mul_f32_e32 v1, 0x3d372713, v2
	v_mul_f32_e32 v1, v2, v1
	v_fma_f32 v1, v2, v1, v2
	v_mul_f32_e32 v1, 0xbfcc422a, v1
	v_mul_f32_e32 v1, 0x3fb8aa3b, v1
	v_mul_f32_e32 v0, 0x3d372713, v6
	v_exp_f32_e32 v4, v1
	v_mul_f32_e32 v1, 0x3d372713, v7
	v_mul_f32_e32 v0, v6, v0
	v_mul_f32_e32 v1, v7, v1
	v_fma_f32 v0, v6, v0, v6
	v_fma_f32 v1, v7, v1, v7
	v_mul_f32_e32 v0, 0xbfcc422a, v0
	v_mul_f32_e32 v1, 0xbfcc422a, v1
	v_mul_f32_e32 v0, 0x3fb8aa3b, v0
	v_mul_f32_e32 v1, 0x3fb8aa3b, v1
	v_exp_f32_e32 v0, v0
	v_exp_f32_e32 v1, v1
	s_nop 0
	v_pk_add_f32 v[0:1], v[0:1], 1.0 op_sel_hi:[1,0]
	s_nop 0
	s_nop 0
	v_rcp_f32_e32 v5, v1
	s_nop 0
	v_mul_f32_e32 v7, v7, v5
	s_nop 0
	v_rcp_f32_e32 v1, v0
	s_nop 0
	v_mul_f32_e32 v6, v6, v1
	v_mul_f32_e32 v0, 0x3d372713, v3
	v_mul_f32_e32 v0, v3, v0
	v_fma_f32 v0, v3, v0, v3
	v_mul_f32_e32 v0, 0xbfcc422a, v0
	v_mul_f32_e32 v0, 0x3fb8aa3b, v0
	v_exp_f32_e32 v5, v0
	s_nop 0
	v_pk_add_f32 v[0:1], v[4:5], 1.0 op_sel_hi:[1,0]
	s_nop 0
	s_nop 0
	v_rcp_f32_e32 v4, v1
	s_nop 0
	v_mul_f32_e32 v3, v3, v4
	s_mov_b64 s[12:13], s[6:7]
	v_rcp_f32_e32 v1, v0
	s_nop 0
	v_mul_f32_e32 v4, v2, v1
	v_cvt_pk_bf16_f32 v3, v4, v3
	v_lshl_add_u64 v[4:5], v[8:9], 0, v[114:115]
	v_lshl_add_u64 v[4:5], v[4:5], 0, s[10:11]
	v_cvt_pk_bf16_f32 v0, v10, v11
	v_cvt_pk_bf16_f32 v1, v6, v7
	v_cvt_pk_bf16_f32 v2, v13, v12
	v_lshl_add_u64 v[4:5], v[4:5], 0, v[48:49]
	s_and_b64 vcc, exec, s[8:9]
	s_mov_b64 s[10:11], s[4:5]
	global_store_dwordx4 v[4:5], v[0:3], off
	s_cbranch_vccz .LBB0_819
	s_waitcnt vmcnt(0)
	s_cmpk_gt_u32 s18, 0xff
	s_cbranch_scc1 .LBB0_826
	s_barrier

.LBB0_1056:
	s_add_i32 s56, s28, 2
	s_add_u32 s29, s24, 0xfffc0080
	s_addc_u32 s30, s25, -1
	s_add_i32 s57, 0, 0x10000
	v_add_u32_e32 v142, s57, v216
	ds_read_b128 v[130:133], v142
	ds_read_b128 v[134:137], v142 offset:1024
	ds_read_b128 v[138:141], v142 offset:2048
	ds_read_b128 v[142:145], v142 offset:3072
	s_cmp_eq_u32 s17, s28
	s_cselect_b32 s28, s22, s19
	s_cselect_b32 s31, s21, s30
	s_cselect_b32 s30, s20, s29
	s_cselect_b32 s29, s23, s27
	s_add_i32 m0, s39, 0xc000
	ds_read_b128 v[146:149], v217
	ds_read_b128 v[150:153], v217 offset:1024
	ds_read_b128 v[154:157], v217 offset:2048
	ds_read_b128 v[158:161], v217 offset:3072
	ds_read_b128 v[162:165], v217 offset:4096
	ds_read_b128 v[166:169], v217 offset:5120
	ds_read_b128 v[170:173], v217 offset:6144
	ds_read_b128 v[174:177], v217 offset:7168
	global_load_lds_dwordx4 v204, s[24:25]
	s_add_i32 m0, s39, 0xe000
	s_nop 0
	global_load_lds_dwordx4 v206, s[24:25]
	s_waitcnt lgkmcnt(8)
	s_barrier
	s_waitcnt lgkmcnt(0)
	s_setprio 1
	s_waitcnt lgkmcnt(0)
	v_mfma_f32_16x16x32_bf16 v[126:129], v[130:133], v[146:149], v[126:129]
	v_mfma_f32_16x16x32_bf16 v[122:125], v[138:141], v[146:149], v[122:125]
	v_mfma_f32_16x16x32_bf16 v[118:121], v[130:133], v[154:157], v[118:121]
	v_mfma_f32_16x16x32_bf16 v[114:117], v[138:141], v[154:157], v[114:117]
	v_mfma_f32_16x16x32_bf16 v[102:105], v[130:133], v[162:165], v[102:105]
	v_mfma_f32_16x16x32_bf16 v[98:101], v[138:141], v[162:165], v[98:101]
	v_mfma_f32_16x16x32_bf16 v[86:89], v[130:133], v[170:173], v[86:89]
	v_mfma_f32_16x16x32_bf16 v[82:85], v[138:141], v[170:173], v[82:85]
	v_mfma_f32_16x16x32_bf16 v[126:129], v[134:137], v[150:153], v[126:129]
	v_mfma_f32_16x16x32_bf16 v[122:125], v[142:145], v[150:153], v[122:125]
	v_mfma_f32_16x16x32_bf16 v[118:121], v[134:137], v[158:161], v[118:121]
	v_mfma_f32_16x16x32_bf16 v[114:117], v[142:145], v[158:161], v[114:117]
	v_mfma_f32_16x16x32_bf16 v[102:105], v[134:137], v[166:169], v[102:105]
	v_mfma_f32_16x16x32_bf16 v[98:101], v[142:145], v[166:169], v[98:101]
	v_mfma_f32_16x16x32_bf16 v[86:89], v[134:137], v[174:177], v[86:89]
	v_mfma_f32_16x16x32_bf16 v[82:85], v[142:145], v[174:177], v[82:85]
	s_setprio 0
	s_barrier
	s_add_i32 s60, 0, 0x14000
	s_add_i32 s57, s57, s38
	v_add_u32_e32 v190, s60, v216
	s_mov_b32 m0, s57
	ds_read_b128 v[178:181], v190
	ds_read_b128 v[182:185], v190 offset:1024
	ds_read_b128 v[186:189], v190 offset:2048
	ds_read_b128 v[190:193], v190 offset:3072
	global_load_lds_dwordx4 v48, s[28:29]
	s_add_i32 m0, s57, 0x2000
	s_nop 0
	global_load_lds_dwordx4 v202, s[28:29]
	s_barrier
	s_waitcnt lgkmcnt(0)
	s_setprio 1
	s_waitcnt lgkmcnt(0)
	v_mfma_f32_16x16x32_bf16 v[110:113], v[178:181], v[146:149], v[110:113]
	v_mfma_f32_16x16x32_bf16 v[106:109], v[186:189], v[146:149], v[106:109]
	v_mfma_f32_16x16x32_bf16 v[94:97], v[178:181], v[154:157], v[94:97]
	v_mfma_f32_16x16x32_bf16 v[90:93], v[186:189], v[154:157], v[90:93]
	v_mfma_f32_16x16x32_bf16 v[78:81], v[178:181], v[162:165], v[78:81]
	v_mfma_f32_16x16x32_bf16 v[74:77], v[186:189], v[162:165], v[74:77]
	v_mfma_f32_16x16x32_bf16 v[70:73], v[178:181], v[170:173], v[70:73]
	v_mfma_f32_16x16x32_bf16 v[66:69], v[186:189], v[170:173], v[66:69]
	v_mfma_f32_16x16x32_bf16 v[110:113], v[182:185], v[150:153], v[110:113]
	v_mfma_f32_16x16x32_bf16 v[106:109], v[190:193], v[150:153], v[106:109]
	v_mfma_f32_16x16x32_bf16 v[94:97], v[182:185], v[158:161], v[94:97]
	v_mfma_f32_16x16x32_bf16 v[90:93], v[190:193], v[158:161], v[90:93]
	v_mfma_f32_16x16x32_bf16 v[78:81], v[182:185], v[166:169], v[78:81]
	v_mfma_f32_16x16x32_bf16 v[74:77], v[190:193], v[166:169], v[74:77]
	v_mfma_f32_16x16x32_bf16 v[70:73], v[182:185], v[174:177], v[70:73]
	v_mfma_f32_16x16x32_bf16 v[66:69], v[190:193], v[174:177], v[66:69]
	s_setprio 0
	s_mov_b32 m0, s39
	v_lshl_add_u64 v[212:213], s[30:31], 0, v[198:199]
	s_barrier
	ds_read_b128 v[146:149], v217 offset:16384
	ds_read_b128 v[150:153], v217 offset:17408
	ds_read_b128 v[154:157], v217 offset:18432
	ds_read_b128 v[158:161], v217 offset:19456
	ds_read_b128 v[162:165], v217 offset:20480
	ds_read_b128 v[166:169], v217 offset:21504
	ds_read_b128 v[170:173], v217 offset:22528
	ds_read_b128 v[174:177], v217 offset:23552
	global_load_lds_dwordx4 v[212:213], off
	v_lshl_add_u64 v[218:219], s[30:31], 0, v[200:201]
	s_mov_b32 m0, s40
	s_nop 0
	global_load_lds_dwordx4 v[218:219], off
	s_barrier
	s_waitcnt lgkmcnt(0)
	s_setprio 1
	s_waitcnt lgkmcnt(0)
	v_mfma_f32_16x16x32_bf16 v[62:65], v[130:133], v[146:149], v[62:65]
	v_mfma_f32_16x16x32_bf16 v[58:61], v[138:141], v[146:149], v[58:61]
	v_mfma_f32_16x16x32_bf16 v[54:57], v[130:133], v[154:157], v[54:57]
	v_mfma_f32_16x16x32_bf16 v[50:53], v[138:141], v[154:157], v[50:53]
	v_mfma_f32_16x16x32_bf16 v[36:39], v[130:133], v[162:165], v[36:39]
	v_mfma_f32_16x16x32_bf16 v[32:35], v[138:141], v[162:165], v[32:35]
	v_mfma_f32_16x16x32_bf16 v[20:23], v[130:133], v[170:173], v[20:23]
	v_mfma_f32_16x16x32_bf16 v[16:19], v[138:141], v[170:173], v[16:19]
	v_mfma_f32_16x16x32_bf16 v[62:65], v[134:137], v[150:153], v[62:65]
	v_mfma_f32_16x16x32_bf16 v[58:61], v[142:145], v[150:153], v[58:61]
	v_mfma_f32_16x16x32_bf16 v[54:57], v[134:137], v[158:161], v[54:57]
	v_mfma_f32_16x16x32_bf16 v[50:53], v[142:145], v[158:161], v[50:53]
	v_mfma_f32_16x16x32_bf16 v[36:39], v[134:137], v[166:169], v[36:39]
	v_mfma_f32_16x16x32_bf16 v[32:35], v[142:145], v[166:169], v[32:35]
	v_mfma_f32_16x16x32_bf16 v[20:23], v[134:137], v[174:177], v[20:23]
	v_mfma_f32_16x16x32_bf16 v[16:19], v[142:145], v[174:177], v[16:19]
	s_setprio 0
	s_barrier
	s_add_u32 s58, s28, 0x40000
	s_addc_u32 s59, s29, 0
	s_add_i32 s57, s60, s38
	s_mov_b32 m0, s57
	s_nop 0
	global_load_lds_dwordx4 v48, s[58:59]
	s_add_i32 m0, s57, 0x2000
	s_nop 0
	global_load_lds_dwordx4 v202, s[58:59]
	s_waitcnt vmcnt(6)
	s_barrier
	s_setprio 1
	v_mfma_f32_16x16x32_bf16 v[44:47], v[178:181], v[146:149], v[44:47]
	v_mfma_f32_16x16x32_bf16 v[40:43], v[186:189], v[146:149], v[40:43]
	v_mfma_f32_16x16x32_bf16 v[28:31], v[178:181], v[154:157], v[28:31]
	v_mfma_f32_16x16x32_bf16 v[24:27], v[186:189], v[154:157], v[24:27]
	v_mfma_f32_16x16x32_bf16 v[12:15], v[178:181], v[162:165], v[12:15]
	v_mfma_f32_16x16x32_bf16 v[8:11], v[186:189], v[162:165], v[8:11]
	v_mfma_f32_16x16x32_bf16 v[4:7], v[178:181], v[170:173], v[4:7]
	v_mfma_f32_16x16x32_bf16 v[0:3], v[186:189], v[170:173], v[0:3]
	v_mfma_f32_16x16x32_bf16 v[44:47], v[182:185], v[150:153], v[44:47]
	v_mfma_f32_16x16x32_bf16 v[40:43], v[190:193], v[150:153], v[40:43]
	v_mfma_f32_16x16x32_bf16 v[28:31], v[182:185], v[158:161], v[28:31]
	v_mfma_f32_16x16x32_bf16 v[24:27], v[190:193], v[158:161], v[24:27]
	v_mfma_f32_16x16x32_bf16 v[12:15], v[182:185], v[166:169], v[12:15]
	v_mfma_f32_16x16x32_bf16 v[8:11], v[190:193], v[166:169], v[8:11]
	v_mfma_f32_16x16x32_bf16 v[4:7], v[182:185], v[174:177], v[4:7]
	v_mfma_f32_16x16x32_bf16 v[0:3], v[190:193], v[174:177], v[0:3]
	s_setprio 0
	s_add_i32 s57, 0, 0x18000
	v_add_u32_e32 v142, s57, v216
	s_barrier
	ds_read_b128 v[130:133], v142
	ds_read_b128 v[134:137], v142 offset:1024
	ds_read_b128 v[138:141], v142 offset:2048
	ds_read_b128 v[142:145], v142 offset:3072
	s_add_u32 s30, s30, 0x40000
	s_addc_u32 s31, s31, 0
	s_mov_b32 m0, s41
	ds_read_b128 v[146:149], v217 offset:32768
	ds_read_b128 v[150:153], v217 offset:33792
	ds_read_b128 v[154:157], v217 offset:34816
	ds_read_b128 v[158:161], v217 offset:35840
	ds_read_b128 v[162:165], v217 offset:36864
	ds_read_b128 v[166:169], v217 offset:37888
	ds_read_b128 v[170:173], v217 offset:38912
	ds_read_b128 v[174:177], v217 offset:39936
	global_load_lds_dwordx4 v198, s[30:31]
	s_mov_b32 m0, s42
	s_nop 0
	global_load_lds_dwordx4 v200, s[30:31]
	s_waitcnt lgkmcnt(8)
	s_barrier
	s_waitcnt lgkmcnt(0)
	s_setprio 1
	s_waitcnt lgkmcnt(0)
	v_mfma_f32_16x16x32_bf16 v[126:129], v[130:133], v[146:149], v[126:129]
	v_mfma_f32_16x16x32_bf16 v[122:125], v[138:141], v[146:149], v[122:125]
	v_mfma_f32_16x16x32_bf16 v[118:121], v[130:133], v[154:157], v[118:121]
	v_mfma_f32_16x16x32_bf16 v[114:117], v[138:141], v[154:157], v[114:117]
	v_mfma_f32_16x16x32_bf16 v[102:105], v[130:133], v[162:165], v[102:105]
	v_mfma_f32_16x16x32_bf16 v[98:101], v[138:141], v[162:165], v[98:101]
	v_mfma_f32_16x16x32_bf16 v[86:89], v[130:133], v[170:173], v[86:89]
	v_mfma_f32_16x16x32_bf16 v[82:85], v[138:141], v[170:173], v[82:85]
	v_mfma_f32_16x16x32_bf16 v[126:129], v[134:137], v[150:153], v[126:129]
	v_mfma_f32_16x16x32_bf16 v[122:125], v[142:145], v[150:153], v[122:125]
	v_mfma_f32_16x16x32_bf16 v[118:121], v[134:137], v[158:161], v[118:121]
	v_mfma_f32_16x16x32_bf16 v[114:117], v[142:145], v[158:161], v[114:117]
	v_mfma_f32_16x16x32_bf16 v[102:105], v[134:137], v[166:169], v[102:105]
	v_mfma_f32_16x16x32_bf16 v[98:101], v[142:145], v[166:169], v[98:101]
	v_mfma_f32_16x16x32_bf16 v[86:89], v[134:137], v[174:177], v[86:89]
	v_mfma_f32_16x16x32_bf16 v[82:85], v[142:145], v[174:177], v[82:85]
	s_setprio 0
	s_barrier
	s_add_i32 s30, 0, 0x1c000
	s_add_i32 s31, s57, s38
	v_add_u32_e32 v190, s30, v216
	s_add_u32 s58, s28, s66
	s_addc_u32 s59, s29, s67
	s_mov_b32 m0, s31
	ds_read_b128 v[178:181], v190
	ds_read_b128 v[182:185], v190 offset:1024
	ds_read_b128 v[186:189], v190 offset:2048
	ds_read_b128 v[190:193], v190 offset:3072
	global_load_lds_dwordx4 v48, s[58:59]
	s_add_u32 s58, s28, s66
	s_addc_u32 s59, s29, s67
	s_add_i32 m0, s31, 0x2000
	s_nop 0
	global_load_lds_dwordx4 v202, s[58:59]
	s_barrier
	s_waitcnt lgkmcnt(0)
	s_setprio 1
	s_waitcnt lgkmcnt(0)
	v_mfma_f32_16x16x32_bf16 v[110:113], v[178:181], v[146:149], v[110:113]
	v_mfma_f32_16x16x32_bf16 v[106:109], v[186:189], v[146:149], v[106:109]
	v_mfma_f32_16x16x32_bf16 v[94:97], v[178:181], v[154:157], v[94:97]
	v_mfma_f32_16x16x32_bf16 v[90:93], v[186:189], v[154:157], v[90:93]
	v_mfma_f32_16x16x32_bf16 v[78:81], v[178:181], v[162:165], v[78:81]
	v_mfma_f32_16x16x32_bf16 v[74:77], v[186:189], v[162:165], v[74:77]
	v_mfma_f32_16x16x32_bf16 v[70:73], v[178:181], v[170:173], v[70:73]
	v_mfma_f32_16x16x32_bf16 v[66:69], v[186:189], v[170:173], v[66:69]
	v_mfma_f32_16x16x32_bf16 v[110:113], v[182:185], v[150:153], v[110:113]
	v_mfma_f32_16x16x32_bf16 v[106:109], v[190:193], v[150:153], v[106:109]
	v_mfma_f32_16x16x32_bf16 v[94:97], v[182:185], v[158:161], v[94:97]
	v_mfma_f32_16x16x32_bf16 v[90:93], v[190:193], v[158:161], v[90:93]
	v_mfma_f32_16x16x32_bf16 v[78:81], v[182:185], v[166:169], v[78:81]
	v_mfma_f32_16x16x32_bf16 v[74:77], v[190:193], v[166:169], v[74:77]
	v_mfma_f32_16x16x32_bf16 v[70:73], v[182:185], v[174:177], v[70:73]
	v_mfma_f32_16x16x32_bf16 v[66:69], v[190:193], v[174:177], v[66:69]
	s_setprio 0
	s_mov_b32 m0, s49
	v_lshl_add_u64 v[208:209], v[212:213], 0, s[66:67]
	s_barrier
	ds_read_b128 v[146:149], v217 offset:49152
	ds_read_b128 v[150:153], v217 offset:50176
	ds_read_b128 v[154:157], v217 offset:51200
	ds_read_b128 v[158:161], v217 offset:52224
	ds_read_b128 v[162:165], v217 offset:53248
	ds_read_b128 v[166:169], v217 offset:54272
	ds_read_b128 v[170:173], v217 offset:55296
	ds_read_b128 v[174:177], v217 offset:56320
	global_load_lds_dwordx4 v[208:209], off
	v_lshl_add_u64 v[208:209], v[218:219], 0, s[66:67]
	s_mov_b32 m0, s50
	s_nop 0
	global_load_lds_dwordx4 v[208:209], off
	s_barrier
	s_waitcnt lgkmcnt(0)
	s_setprio 1
	s_waitcnt lgkmcnt(0)
	v_mfma_f32_16x16x32_bf16 v[62:65], v[130:133], v[146:149], v[62:65]
	v_mfma_f32_16x16x32_bf16 v[58:61], v[138:141], v[146:149], v[58:61]
	v_mfma_f32_16x16x32_bf16 v[54:57], v[130:133], v[154:157], v[54:57]
	v_mfma_f32_16x16x32_bf16 v[50:53], v[138:141], v[154:157], v[50:53]
	v_mfma_f32_16x16x32_bf16 v[36:39], v[130:133], v[162:165], v[36:39]
	v_mfma_f32_16x16x32_bf16 v[32:35], v[138:141], v[162:165], v[32:35]
	v_mfma_f32_16x16x32_bf16 v[20:23], v[130:133], v[170:173], v[20:23]
	v_mfma_f32_16x16x32_bf16 v[16:19], v[138:141], v[170:173], v[16:19]
	v_mfma_f32_16x16x32_bf16 v[62:65], v[134:137], v[150:153], v[62:65]
	v_mfma_f32_16x16x32_bf16 v[58:61], v[142:145], v[150:153], v[58:61]
	v_mfma_f32_16x16x32_bf16 v[54:57], v[134:137], v[158:161], v[54:57]
	v_mfma_f32_16x16x32_bf16 v[50:53], v[142:145], v[158:161], v[50:53]
	v_mfma_f32_16x16x32_bf16 v[36:39], v[134:137], v[166:169], v[36:39]
	v_mfma_f32_16x16x32_bf16 v[32:35], v[142:145], v[166:169], v[32:35]
	v_mfma_f32_16x16x32_bf16 v[20:23], v[134:137], v[174:177], v[20:23]
	v_mfma_f32_16x16x32_bf16 v[16:19], v[142:145], v[174:177], v[16:19]
	s_setprio 0
	s_barrier
	s_add_u32 s28, s28, 0x40080
	s_addc_u32 s29, s29, 0
	s_add_i32 s30, s30, s38
	s_mov_b32 m0, s30
	s_nop 0
	global_load_lds_dwordx4 v48, s[28:29]
	s_add_i32 m0, s30, 0x2000
	s_nop 0
	global_load_lds_dwordx4 v202, s[28:29]
	s_waitcnt vmcnt(6)
	s_barrier
	s_setprio 1
	v_mfma_f32_16x16x32_bf16 v[44:47], v[178:181], v[146:149], v[44:47]
	v_mfma_f32_16x16x32_bf16 v[40:43], v[186:189], v[146:149], v[40:43]
	v_mfma_f32_16x16x32_bf16 v[28:31], v[178:181], v[154:157], v[28:31]
	v_mfma_f32_16x16x32_bf16 v[24:27], v[186:189], v[154:157], v[24:27]
	v_mfma_f32_16x16x32_bf16 v[12:15], v[178:181], v[162:165], v[12:15]
	v_mfma_f32_16x16x32_bf16 v[8:11], v[186:189], v[162:165], v[8:11]
	v_mfma_f32_16x16x32_bf16 v[4:7], v[178:181], v[170:173], v[4:7]
	v_mfma_f32_16x16x32_bf16 v[0:3], v[186:189], v[170:173], v[0:3]
	v_mfma_f32_16x16x32_bf16 v[44:47], v[182:185], v[150:153], v[44:47]
	v_mfma_f32_16x16x32_bf16 v[40:43], v[190:193], v[150:153], v[40:43]
	v_mfma_f32_16x16x32_bf16 v[28:31], v[182:185], v[158:161], v[28:31]
	v_mfma_f32_16x16x32_bf16 v[24:27], v[190:193], v[158:161], v[24:27]
	v_mfma_f32_16x16x32_bf16 v[12:15], v[182:185], v[166:169], v[12:15]
	v_mfma_f32_16x16x32_bf16 v[8:11], v[190:193], v[166:169], v[8:11]
	v_mfma_f32_16x16x32_bf16 v[4:7], v[182:185], v[174:177], v[4:7]
	v_mfma_f32_16x16x32_bf16 v[0:3], v[190:193], v[174:177], v[0:3]
	s_setprio 0
	s_add_u32 s24, s24, 0x100
	s_addc_u32 s25, s25, 0
	s_add_u32 s19, s19, 0x100
	s_addc_u32 s27, s27, 0
	s_cmp_ge_i32 s56, s1
	s_mov_b32 s28, s56
	s_barrier
	s_cbranch_scc0 .LBB0_1056
	v_mov_b32_e32 v130, v214
	v_mov_b32_e32 v131, v215
	s_bitcmp1_b32 s55, 0
	v_add_u32_e32 v134, s47, v130
	v_lshlrev_b32_e32 v130, 8, v134
	v_lshl_add_u32 v132, v131, 3, s48
	v_ashrrev_i32_e32 v131, 31, v130
	v_lshl_add_u64 v[130:131], v[130:131], 1, s[12:13]
	v_ashrrev_i32_e32 v133, 31, v132
	s_cselect_b64 s[28:29], -1, 0
	v_lshlrev_b32_e32 v208, 9, v215
	v_lshl_add_u32 v208, v214, 4, v208
	v_lshl_add_u32 v208, s47, 9, v208
	v_lshl_add_u32 v208, s48, 6, v208
	v_mov_b32_e32 v209, 0
	v_lshl_add_u64 v[208:209], v[208:209], 0, s[12:13]
	s_mov_b64 s[24:25], -1
	s_and_b64 vcc, exec, s[28:29]
	s_mov_b32 s57, s81
	s_cbranch_vccz .LBB0_1093
	s_mov_b64 s[24:25], 0x20000
	v_lshl_add_u64 v[130:131], v[208:209], 0, s[24:25]
	s_and_b32 s1, s55, -2
	s_mov_b64 s[24:25], 0x100
	s_cmp_lg_u32 s1, 4
	v_mov_b64_e32 v[210:211], v[130:131]
	s_cbranch_scc1 .LBB0_1060
	v_lshl_add_u32 v134, s26, 8, v134
	v_ashrrev_i32_e32 v135, 31, v134
	v_lshlrev_b64 v[134:135], 11, v[134:135]
	s_lshl_b32 s0, s0, 8
	v_lshl_add_u64 v[134:135], s[14:15], 0, v[134:135]
	s_ashr_i32 s1, s0, 31
	v_lshl_add_u64 v[134:135], s[0:1], 1, v[134:135]
	v_lshl_add_u64 v[210:211], v[132:133], 1, v[134:135]
	s_mov_b64 s[24:25], 0x400

.LBB0_1202:
	s_add_u32 s28, s26, 0xfffc0080
	s_addc_u32 s29, s27, -1
	s_add_i32 s49, 0, 0x10000
	v_add_u32_e32 v142, s49, v170
	ds_read_b128 v[130:133], v142
	ds_read_b128 v[134:137], v142 offset:1024
	ds_read_b128 v[138:141], v142 offset:2048
	ds_read_b128 v[142:145], v142 offset:3072
	s_cmp_eq_u32 s25, 12
	s_cselect_b32 s31, s19, s29
	s_cselect_b32 s30, s18, s28
	s_cselect_b32 s29, s21, s17
	s_cselect_b32 s28, s20, s15
	v_lshl_add_u64 v[190:191], s[26:27], 0, v[150:151]
	s_add_i32 m0, s23, 0xc000
	ds_read_b128 v[154:157], v172
	ds_read_b128 v[158:161], v172 offset:1024
	ds_read_b128 v[162:165], v172 offset:2048
	ds_read_b128 v[166:169], v172 offset:3072
	ds_read_b128 v[174:177], v172 offset:4096
	ds_read_b128 v[178:181], v172 offset:5120
	ds_read_b128 v[182:185], v172 offset:6144
	ds_read_b128 v[186:189], v172 offset:7168
	global_load_lds_dwordx4 v[190:191], off
	v_lshl_add_u64 v[190:191], s[26:27], 0, v[152:153]
	s_add_i32 m0, s23, 0xe000
	s_nop 0
	global_load_lds_dwordx4 v[190:191], off
	s_waitcnt lgkmcnt(8)
	s_barrier
	s_waitcnt lgkmcnt(0)
	s_setprio 1
	s_waitcnt lgkmcnt(0)
	v_mfma_f32_16x16x32_bf16 v[126:129], v[130:133], v[154:157], v[126:129]
	v_mfma_f32_16x16x32_bf16 v[122:125], v[138:141], v[154:157], v[122:125]
	v_mfma_f32_16x16x32_bf16 v[114:117], v[130:133], v[162:165], v[114:117]
	v_mfma_f32_16x16x32_bf16 v[106:109], v[138:141], v[162:165], v[106:109]
	v_mfma_f32_16x16x32_bf16 v[94:97], v[130:133], v[174:177], v[94:97]
	v_mfma_f32_16x16x32_bf16 v[90:93], v[138:141], v[174:177], v[90:93]
	v_mfma_f32_16x16x32_bf16 v[82:85], v[130:133], v[182:185], v[82:85]
	v_mfma_f32_16x16x32_bf16 v[74:77], v[138:141], v[182:185], v[74:77]
	v_mfma_f32_16x16x32_bf16 v[126:129], v[134:137], v[158:161], v[126:129]
	v_mfma_f32_16x16x32_bf16 v[122:125], v[142:145], v[158:161], v[122:125]
	v_mfma_f32_16x16x32_bf16 v[114:117], v[134:137], v[166:169], v[114:117]
	v_mfma_f32_16x16x32_bf16 v[106:109], v[142:145], v[166:169], v[106:109]
	v_mfma_f32_16x16x32_bf16 v[94:97], v[134:137], v[178:181], v[94:97]
	v_mfma_f32_16x16x32_bf16 v[90:93], v[142:145], v[178:181], v[90:93]
	v_mfma_f32_16x16x32_bf16 v[82:85], v[134:137], v[186:189], v[82:85]
	v_mfma_f32_16x16x32_bf16 v[74:77], v[142:145], v[186:189], v[74:77]
	s_setprio 0
	s_barrier
	s_add_i32 s52, 0, 0x14000
	s_add_i32 s49, s49, s35
	v_add_u32_e32 v173, s52, v170
	s_mov_b32 m0, s49
	ds_read_b128 v[190:193], v173
	ds_read_b128 v[198:201], v173 offset:1024
	ds_read_b128 v[202:205], v173 offset:2048
	ds_read_b128 v[206:209], v173 offset:3072
	global_load_lds_dwordx4 v48, s[28:29]
	v_lshl_add_u64 v[212:213], s[28:29], 0, v[146:147]
	s_add_i32 m0, s49, 0x2000
	s_nop 0
	global_load_lds_dwordx4 v[212:213], off
	s_barrier
	s_waitcnt lgkmcnt(0)
	s_setprio 1
	s_waitcnt lgkmcnt(0)
	v_mfma_f32_16x16x32_bf16 v[118:121], v[190:193], v[154:157], v[118:121]
	v_mfma_f32_16x16x32_bf16 v[110:113], v[202:205], v[154:157], v[110:113]
	v_mfma_f32_16x16x32_bf16 v[102:105], v[190:193], v[162:165], v[102:105]
	v_mfma_f32_16x16x32_bf16 v[98:101], v[202:205], v[162:165], v[98:101]
	v_mfma_f32_16x16x32_bf16 v[86:89], v[190:193], v[174:177], v[86:89]
	v_mfma_f32_16x16x32_bf16 v[78:81], v[202:205], v[174:177], v[78:81]
	v_mfma_f32_16x16x32_bf16 v[70:73], v[190:193], v[182:185], v[70:73]
	v_mfma_f32_16x16x32_bf16 v[66:69], v[202:205], v[182:185], v[66:69]
	v_mfma_f32_16x16x32_bf16 v[118:121], v[198:201], v[158:161], v[118:121]
	v_mfma_f32_16x16x32_bf16 v[110:113], v[206:209], v[158:161], v[110:113]
	v_mfma_f32_16x16x32_bf16 v[102:105], v[198:201], v[166:169], v[102:105]
	v_mfma_f32_16x16x32_bf16 v[98:101], v[206:209], v[166:169], v[98:101]
	v_mfma_f32_16x16x32_bf16 v[86:89], v[198:201], v[178:181], v[86:89]
	v_mfma_f32_16x16x32_bf16 v[78:81], v[206:209], v[178:181], v[78:81]
	v_mfma_f32_16x16x32_bf16 v[70:73], v[198:201], v[186:189], v[70:73]
	v_mfma_f32_16x16x32_bf16 v[66:69], v[206:209], v[186:189], v[66:69]
	s_setprio 0
	s_mov_b32 m0, s23
	v_lshl_add_u64 v[214:215], s[30:31], 0, v[48:49]
	s_barrier
	ds_read_b128 v[154:157], v172 offset:16384
	ds_read_b128 v[158:161], v172 offset:17408
	ds_read_b128 v[162:165], v172 offset:18432
	ds_read_b128 v[166:169], v172 offset:19456
	ds_read_b128 v[174:177], v172 offset:20480
	ds_read_b128 v[178:181], v172 offset:21504
	ds_read_b128 v[182:185], v172 offset:22528
	ds_read_b128 v[186:189], v172 offset:23552
	global_load_lds_dwordx4 v[214:215], off
	v_lshl_add_u64 v[216:217], s[30:31], 0, v[146:147]
	s_mov_b32 m0, s41
	s_nop 0
	global_load_lds_dwordx4 v[216:217], off
	s_barrier
	s_waitcnt lgkmcnt(0)
	s_setprio 1
	s_waitcnt lgkmcnt(0)
	v_mfma_f32_16x16x32_bf16 v[62:65], v[130:133], v[154:157], v[62:65]
	v_mfma_f32_16x16x32_bf16 v[58:61], v[138:141], v[154:157], v[58:61]
	v_mfma_f32_16x16x32_bf16 v[50:53], v[130:133], v[162:165], v[50:53]
	v_mfma_f32_16x16x32_bf16 v[40:43], v[138:141], v[162:165], v[40:43]
	v_mfma_f32_16x16x32_bf16 v[32:35], v[130:133], v[174:177], v[32:35]
	v_mfma_f32_16x16x32_bf16 v[24:27], v[138:141], v[174:177], v[24:27]
	v_mfma_f32_16x16x32_bf16 v[16:19], v[130:133], v[182:185], v[16:19]
	v_mfma_f32_16x16x32_bf16 v[8:11], v[138:141], v[182:185], v[8:11]
	v_mfma_f32_16x16x32_bf16 v[62:65], v[134:137], v[158:161], v[62:65]
	v_mfma_f32_16x16x32_bf16 v[58:61], v[142:145], v[158:161], v[58:61]
	v_mfma_f32_16x16x32_bf16 v[50:53], v[134:137], v[166:169], v[50:53]
	v_mfma_f32_16x16x32_bf16 v[40:43], v[142:145], v[166:169], v[40:43]
	v_mfma_f32_16x16x32_bf16 v[32:35], v[134:137], v[178:181], v[32:35]
	v_mfma_f32_16x16x32_bf16 v[24:27], v[142:145], v[178:181], v[24:27]
	v_mfma_f32_16x16x32_bf16 v[16:19], v[134:137], v[186:189], v[16:19]
	v_mfma_f32_16x16x32_bf16 v[8:11], v[142:145], v[186:189], v[8:11]
	s_setprio 0
	s_barrier
	s_add_u32 s50, s28, 0x40000
	s_addc_u32 s51, s29, 0
	s_add_i32 s49, s52, s35
	s_mov_b32 m0, s49
	s_nop 0
	global_load_lds_dwordx4 v48, s[50:51]
	v_lshl_add_u64 v[130:131], s[50:51], 0, v[146:147]
	s_add_i32 m0, s49, 0x2000
	s_nop 0
	global_load_lds_dwordx4 v[130:131], off
	s_waitcnt vmcnt(6)
	s_barrier
	s_setprio 1
	v_mfma_f32_16x16x32_bf16 v[54:57], v[190:193], v[154:157], v[54:57]
	v_mfma_f32_16x16x32_bf16 v[44:47], v[202:205], v[154:157], v[44:47]
	v_mfma_f32_16x16x32_bf16 v[36:39], v[190:193], v[162:165], v[36:39]
	v_mfma_f32_16x16x32_bf16 v[28:31], v[202:205], v[162:165], v[28:31]
	v_mfma_f32_16x16x32_bf16 v[20:23], v[190:193], v[174:177], v[20:23]
	v_mfma_f32_16x16x32_bf16 v[12:15], v[202:205], v[174:177], v[12:15]
	v_mfma_f32_16x16x32_bf16 v[4:7], v[190:193], v[182:185], v[4:7]
	v_mfma_f32_16x16x32_bf16 v[0:3], v[202:205], v[182:185], v[0:3]
	v_mfma_f32_16x16x32_bf16 v[54:57], v[198:201], v[158:161], v[54:57]
	v_mfma_f32_16x16x32_bf16 v[44:47], v[206:209], v[158:161], v[44:47]
	v_mfma_f32_16x16x32_bf16 v[36:39], v[198:201], v[166:169], v[36:39]
	v_mfma_f32_16x16x32_bf16 v[28:31], v[206:209], v[166:169], v[28:31]
	v_mfma_f32_16x16x32_bf16 v[20:23], v[198:201], v[178:181], v[20:23]
	v_mfma_f32_16x16x32_bf16 v[12:15], v[206:209], v[178:181], v[12:15]
	v_mfma_f32_16x16x32_bf16 v[4:7], v[198:201], v[186:189], v[4:7]
	v_mfma_f32_16x16x32_bf16 v[0:3], v[206:209], v[186:189], v[0:3]
	s_setprio 0
	s_add_i32 s49, 0, 0x18000
	v_add_u32_e32 v142, s49, v170
	s_barrier
	ds_read_b128 v[130:133], v142
	ds_read_b128 v[134:137], v142 offset:1024
	ds_read_b128 v[138:141], v142 offset:2048
	ds_read_b128 v[142:145], v142 offset:3072
	s_add_u32 s30, s30, 0x40000
	s_addc_u32 s31, s31, 0
	s_mov_b32 m0, s42
	ds_read_b128 v[154:157], v172 offset:32768
	ds_read_b128 v[158:161], v172 offset:33792
	ds_read_b128 v[162:165], v172 offset:34816
	ds_read_b128 v[166:169], v172 offset:35840
	ds_read_b128 v[174:177], v172 offset:36864
	ds_read_b128 v[178:181], v172 offset:37888
	ds_read_b128 v[182:185], v172 offset:38912
	ds_read_b128 v[186:189], v172 offset:39936
	global_load_lds_dwordx4 v48, s[30:31]
	v_lshl_add_u64 v[190:191], s[30:31], 0, v[146:147]
	s_mov_b32 m0, s43
	s_nop 0
	global_load_lds_dwordx4 v[190:191], off
	s_waitcnt lgkmcnt(8)
	s_barrier
	s_waitcnt lgkmcnt(0)
	s_setprio 1
	s_waitcnt lgkmcnt(0)
	v_mfma_f32_16x16x32_bf16 v[126:129], v[130:133], v[154:157], v[126:129]
	v_mfma_f32_16x16x32_bf16 v[122:125], v[138:141], v[154:157], v[122:125]
	v_mfma_f32_16x16x32_bf16 v[114:117], v[130:133], v[162:165], v[114:117]
	v_mfma_f32_16x16x32_bf16 v[106:109], v[138:141], v[162:165], v[106:109]
	v_mfma_f32_16x16x32_bf16 v[94:97], v[130:133], v[174:177], v[94:97]
	v_mfma_f32_16x16x32_bf16 v[90:93], v[138:141], v[174:177], v[90:93]
	v_mfma_f32_16x16x32_bf16 v[82:85], v[130:133], v[182:185], v[82:85]
	v_mfma_f32_16x16x32_bf16 v[74:77], v[138:141], v[182:185], v[74:77]
	v_mfma_f32_16x16x32_bf16 v[126:129], v[134:137], v[158:161], v[126:129]
	v_mfma_f32_16x16x32_bf16 v[122:125], v[142:145], v[158:161], v[122:125]
	v_mfma_f32_16x16x32_bf16 v[114:117], v[134:137], v[166:169], v[114:117]
	v_mfma_f32_16x16x32_bf16 v[106:109], v[142:145], v[166:169], v[106:109]
	v_mfma_f32_16x16x32_bf16 v[94:97], v[134:137], v[178:181], v[94:97]
	v_mfma_f32_16x16x32_bf16 v[90:93], v[142:145], v[178:181], v[90:93]
	v_mfma_f32_16x16x32_bf16 v[82:85], v[134:137], v[186:189], v[82:85]
	v_mfma_f32_16x16x32_bf16 v[74:77], v[142:145], v[186:189], v[74:77]
	s_setprio 0
	s_barrier
	s_add_i32 s30, 0, 0x1c000
	s_add_i32 s31, s49, s35
	v_add_u32_e32 v173, s30, v170
	s_add_u32 s52, s28, s66
	s_addc_u32 s53, s29, s67
	s_mov_b32 m0, s31
	ds_read_b128 v[190:193], v173
	ds_read_b128 v[198:201], v173 offset:1024
	ds_read_b128 v[202:205], v173 offset:2048
	ds_read_b128 v[206:209], v173 offset:3072
	global_load_lds_dwordx4 v48, s[52:53]
	v_lshl_add_u64 v[210:211], v[212:213], 0, s[66:67]
	s_add_i32 m0, s31, 0x2000
	s_nop 0
	global_load_lds_dwordx4 v[210:211], off
	s_barrier
	s_waitcnt lgkmcnt(0)
	s_setprio 1
	s_waitcnt lgkmcnt(0)
	v_mfma_f32_16x16x32_bf16 v[118:121], v[190:193], v[154:157], v[118:121]
	v_mfma_f32_16x16x32_bf16 v[110:113], v[202:205], v[154:157], v[110:113]
	v_mfma_f32_16x16x32_bf16 v[102:105], v[190:193], v[162:165], v[102:105]
	v_mfma_f32_16x16x32_bf16 v[98:101], v[202:205], v[162:165], v[98:101]
	v_mfma_f32_16x16x32_bf16 v[86:89], v[190:193], v[174:177], v[86:89]
	v_mfma_f32_16x16x32_bf16 v[78:81], v[202:205], v[174:177], v[78:81]
	v_mfma_f32_16x16x32_bf16 v[70:73], v[190:193], v[182:185], v[70:73]
	v_mfma_f32_16x16x32_bf16 v[66:69], v[202:205], v[182:185], v[66:69]
	v_mfma_f32_16x16x32_bf16 v[118:121], v[198:201], v[158:161], v[118:121]
	v_mfma_f32_16x16x32_bf16 v[110:113], v[206:209], v[158:161], v[110:113]
	v_mfma_f32_16x16x32_bf16 v[102:105], v[198:201], v[166:169], v[102:105]
	v_mfma_f32_16x16x32_bf16 v[98:101], v[206:209], v[166:169], v[98:101]
	v_mfma_f32_16x16x32_bf16 v[86:89], v[198:201], v[178:181], v[86:89]
	v_mfma_f32_16x16x32_bf16 v[78:81], v[206:209], v[178:181], v[78:81]
	v_mfma_f32_16x16x32_bf16 v[70:73], v[198:201], v[186:189], v[70:73]
	v_mfma_f32_16x16x32_bf16 v[66:69], v[206:209], v[186:189], v[66:69]
	s_setprio 0
	s_mov_b32 m0, s46
	v_lshl_add_u64 v[210:211], v[214:215], 0, s[66:67]
	s_barrier
	ds_read_b128 v[154:157], v172 offset:49152
	ds_read_b128 v[158:161], v172 offset:50176
	ds_read_b128 v[162:165], v172 offset:51200
	ds_read_b128 v[166:169], v172 offset:52224
	ds_read_b128 v[174:177], v172 offset:53248
	ds_read_b128 v[178:181], v172 offset:54272
	ds_read_b128 v[182:185], v172 offset:55296
	ds_read_b128 v[186:189], v172 offset:56320
	global_load_lds_dwordx4 v[210:211], off
	v_lshl_add_u64 v[210:211], v[216:217], 0, s[66:67]
	s_mov_b32 m0, s47
	s_nop 0
	global_load_lds_dwordx4 v[210:211], off
	s_barrier
	s_waitcnt lgkmcnt(0)
	s_setprio 1
	s_waitcnt lgkmcnt(0)
	v_mfma_f32_16x16x32_bf16 v[62:65], v[130:133], v[154:157], v[62:65]
	v_mfma_f32_16x16x32_bf16 v[58:61], v[138:141], v[154:157], v[58:61]
	v_mfma_f32_16x16x32_bf16 v[50:53], v[130:133], v[162:165], v[50:53]
	v_mfma_f32_16x16x32_bf16 v[40:43], v[138:141], v[162:165], v[40:43]
	v_mfma_f32_16x16x32_bf16 v[32:35], v[130:133], v[174:177], v[32:35]
	v_mfma_f32_16x16x32_bf16 v[24:27], v[138:141], v[174:177], v[24:27]
	v_mfma_f32_16x16x32_bf16 v[16:19], v[130:133], v[182:185], v[16:19]
	v_mfma_f32_16x16x32_bf16 v[8:11], v[138:141], v[182:185], v[8:11]
	v_mfma_f32_16x16x32_bf16 v[62:65], v[134:137], v[158:161], v[62:65]
	v_mfma_f32_16x16x32_bf16 v[58:61], v[142:145], v[158:161], v[58:61]
	v_mfma_f32_16x16x32_bf16 v[50:53], v[134:137], v[166:169], v[50:53]
	v_mfma_f32_16x16x32_bf16 v[40:43], v[142:145], v[166:169], v[40:43]
	v_mfma_f32_16x16x32_bf16 v[32:35], v[134:137], v[178:181], v[32:35]
	v_mfma_f32_16x16x32_bf16 v[24:27], v[142:145], v[178:181], v[24:27]
	v_mfma_f32_16x16x32_bf16 v[16:19], v[134:137], v[186:189], v[16:19]
	v_mfma_f32_16x16x32_bf16 v[8:11], v[142:145], v[186:189], v[8:11]
	s_setprio 0
	s_barrier
	s_add_u32 s28, s28, 0x40080
	s_addc_u32 s29, s29, 0
	s_add_i32 s30, s30, s35
	s_mov_b32 m0, s30
	s_nop 0
	global_load_lds_dwordx4 v48, s[28:29]
	v_lshl_add_u64 v[130:131], s[28:29], 0, v[146:147]
	s_add_i32 m0, s30, 0x2000
	s_nop 0
	global_load_lds_dwordx4 v[130:131], off
	s_waitcnt vmcnt(6)
	s_barrier
	s_setprio 1
	v_mfma_f32_16x16x32_bf16 v[54:57], v[190:193], v[154:157], v[54:57]
	v_mfma_f32_16x16x32_bf16 v[44:47], v[202:205], v[154:157], v[44:47]
	v_mfma_f32_16x16x32_bf16 v[36:39], v[190:193], v[162:165], v[36:39]
	v_mfma_f32_16x16x32_bf16 v[28:31], v[202:205], v[162:165], v[28:31]
	v_mfma_f32_16x16x32_bf16 v[20:23], v[190:193], v[174:177], v[20:23]
	v_mfma_f32_16x16x32_bf16 v[12:15], v[202:205], v[174:177], v[12:15]
	v_mfma_f32_16x16x32_bf16 v[4:7], v[190:193], v[182:185], v[4:7]
	v_mfma_f32_16x16x32_bf16 v[0:3], v[202:205], v[182:185], v[0:3]
	v_mfma_f32_16x16x32_bf16 v[54:57], v[198:201], v[158:161], v[54:57]
	v_mfma_f32_16x16x32_bf16 v[44:47], v[206:209], v[158:161], v[44:47]
	v_mfma_f32_16x16x32_bf16 v[36:39], v[198:201], v[166:169], v[36:39]
	v_mfma_f32_16x16x32_bf16 v[28:31], v[206:209], v[166:169], v[28:31]
	v_mfma_f32_16x16x32_bf16 v[20:23], v[198:201], v[178:181], v[20:23]
	v_mfma_f32_16x16x32_bf16 v[12:15], v[206:209], v[178:181], v[12:15]
	v_mfma_f32_16x16x32_bf16 v[4:7], v[198:201], v[186:189], v[4:7]
	v_mfma_f32_16x16x32_bf16 v[0:3], v[206:209], v[186:189], v[0:3]
	s_setprio 0
	s_add_i32 s25, s25, 2
	s_add_u32 s26, s26, 0x100
	s_addc_u32 s27, s27, 0
	s_add_u32 s15, s15, 0x100
	s_addc_u32 s17, s17, 0
	s_cmp_gt_u32 s25, 13
	s_barrier
	s_cbranch_scc0 .LBB0_1202
	s_mul_hi_i32 s15, s24, 0x38e38e39
	s_lshr_b32 s17, s15, 31
	s_ashr_i32 s15, s15, 1
	s_add_i32 s15, s15, s17
	s_mul_i32 s17, s15, -9
	s_sub_i32 s25, 0, s24
	s_cmp_eq_u32 s17, s25
	s_mov_b64 s[26:27], 0x30000
	s_cbranch_scc1 .LBB0_1198
	s_mul_hi_i32 s27, s15, 0x1800
	s_mul_i32 s26, s15, 0x1800
	s_branch .LBB0_1198

.LBB0_1219:
	s_add_u32 s26, s24, 0xfffc0080
	s_addc_u32 s27, s25, -1
	s_add_i32 s31, 0, 0x10000
	v_add_u32_e32 v142, s31, v208
	ds_read_b128 v[130:133], v142
	ds_read_b128 v[134:137], v142 offset:1024
	ds_read_b128 v[138:141], v142 offset:2048
	ds_read_b128 v[142:145], v142 offset:3072
	s_cmp_eq_u32 s30, 12
	s_cselect_b32 s29, s19, s27
	s_cselect_b32 s28, s18, s26
	s_cselect_b32 s27, s21, s17
	s_cselect_b32 s26, s20, s15
	s_add_i32 m0, s41, 0xc000
	ds_read_b128 v[146:149], v210
	ds_read_b128 v[150:153], v210 offset:1024
	ds_read_b128 v[154:157], v210 offset:2048
	ds_read_b128 v[158:161], v210 offset:3072
	ds_read_b128 v[162:165], v210 offset:4096
	ds_read_b128 v[166:169], v210 offset:5120
	ds_read_b128 v[170:173], v210 offset:6144
	ds_read_b128 v[174:177], v210 offset:7168
	global_load_lds_dwordx4 v200, s[24:25]
	s_add_i32 m0, s41, 0xe000
	s_nop 0
	global_load_lds_dwordx4 v202, s[24:25]
	s_waitcnt lgkmcnt(8)
	s_barrier
	s_waitcnt lgkmcnt(0)
	s_setprio 1
	s_waitcnt lgkmcnt(0)
	v_mfma_f32_16x16x32_bf16 v[126:129], v[130:133], v[146:149], v[126:129]
	v_mfma_f32_16x16x32_bf16 v[122:125], v[138:141], v[146:149], v[122:125]
	v_mfma_f32_16x16x32_bf16 v[118:121], v[130:133], v[154:157], v[118:121]
	v_mfma_f32_16x16x32_bf16 v[106:109], v[138:141], v[154:157], v[106:109]
	v_mfma_f32_16x16x32_bf16 v[94:97], v[130:133], v[162:165], v[94:97]
	v_mfma_f32_16x16x32_bf16 v[90:93], v[138:141], v[162:165], v[90:93]
	v_mfma_f32_16x16x32_bf16 v[86:89], v[130:133], v[170:173], v[86:89]
	v_mfma_f32_16x16x32_bf16 v[74:77], v[138:141], v[170:173], v[74:77]
	v_mfma_f32_16x16x32_bf16 v[126:129], v[134:137], v[150:153], v[126:129]
	v_mfma_f32_16x16x32_bf16 v[122:125], v[142:145], v[150:153], v[122:125]
	v_mfma_f32_16x16x32_bf16 v[118:121], v[134:137], v[158:161], v[118:121]
	v_mfma_f32_16x16x32_bf16 v[106:109], v[142:145], v[158:161], v[106:109]
	v_mfma_f32_16x16x32_bf16 v[94:97], v[134:137], v[166:169], v[94:97]
	v_mfma_f32_16x16x32_bf16 v[90:93], v[142:145], v[166:169], v[90:93]
	v_mfma_f32_16x16x32_bf16 v[86:89], v[134:137], v[174:177], v[86:89]
	v_mfma_f32_16x16x32_bf16 v[74:77], v[142:145], v[174:177], v[74:77]
	s_setprio 0
	s_barrier
	s_add_i32 s50, 0, 0x14000
	s_add_i32 s31, s31, s40
	v_add_u32_e32 v204, s50, v208
	s_mov_b32 m0, s31
	ds_read_b128 v[178:181], v204
	ds_read_b128 v[182:185], v204 offset:1024
	ds_read_b128 v[186:189], v204 offset:2048
	ds_read_b128 v[204:207], v204 offset:3072
	global_load_lds_dwordx4 v48, s[26:27]
	s_add_i32 m0, s31, 0x2000
	s_nop 0
	global_load_lds_dwordx4 v190, s[26:27]
	s_barrier
	s_waitcnt lgkmcnt(0)
	s_setprio 1
	s_waitcnt lgkmcnt(0)
	v_mfma_f32_16x16x32_bf16 v[114:117], v[178:181], v[146:149], v[114:117]
	v_mfma_f32_16x16x32_bf16 v[110:113], v[186:189], v[146:149], v[110:113]
	v_mfma_f32_16x16x32_bf16 v[102:105], v[178:181], v[154:157], v[102:105]
	v_mfma_f32_16x16x32_bf16 v[98:101], v[186:189], v[154:157], v[98:101]
	v_mfma_f32_16x16x32_bf16 v[82:85], v[178:181], v[162:165], v[82:85]
	v_mfma_f32_16x16x32_bf16 v[78:81], v[186:189], v[162:165], v[78:81]
	v_mfma_f32_16x16x32_bf16 v[70:73], v[178:181], v[170:173], v[70:73]
	v_mfma_f32_16x16x32_bf16 v[66:69], v[186:189], v[170:173], v[66:69]
	v_mfma_f32_16x16x32_bf16 v[114:117], v[182:185], v[150:153], v[114:117]
	v_mfma_f32_16x16x32_bf16 v[110:113], v[204:207], v[150:153], v[110:113]
	v_mfma_f32_16x16x32_bf16 v[102:105], v[182:185], v[158:161], v[102:105]
	v_mfma_f32_16x16x32_bf16 v[98:101], v[204:207], v[158:161], v[98:101]
	v_mfma_f32_16x16x32_bf16 v[82:85], v[182:185], v[166:169], v[82:85]
	v_mfma_f32_16x16x32_bf16 v[78:81], v[204:207], v[166:169], v[78:81]
	v_mfma_f32_16x16x32_bf16 v[70:73], v[182:185], v[174:177], v[70:73]
	v_mfma_f32_16x16x32_bf16 v[66:69], v[204:207], v[174:177], v[66:69]
	s_setprio 0
	s_mov_b32 m0, s41
	v_lshl_add_u64 v[216:217], s[28:29], 0, v[48:49]
	s_barrier
	ds_read_b128 v[146:149], v210 offset:16384
	ds_read_b128 v[150:153], v210 offset:17408
	ds_read_b128 v[154:157], v210 offset:18432
	ds_read_b128 v[158:161], v210 offset:19456
	ds_read_b128 v[162:165], v210 offset:20480
	ds_read_b128 v[166:169], v210 offset:21504
	ds_read_b128 v[170:173], v210 offset:22528
	ds_read_b128 v[174:177], v210 offset:23552
	global_load_lds_dwordx4 v[216:217], off
	v_lshl_add_u64 v[218:219], s[28:29], 0, v[190:191]
	s_mov_b32 m0, s42
	s_nop 0
	global_load_lds_dwordx4 v[218:219], off
	s_barrier
	s_waitcnt lgkmcnt(0)
	s_setprio 1
	s_waitcnt lgkmcnt(0)
	v_mfma_f32_16x16x32_bf16 v[62:65], v[130:133], v[146:149], v[62:65]
	v_mfma_f32_16x16x32_bf16 v[58:61], v[138:141], v[146:149], v[58:61]
	v_mfma_f32_16x16x32_bf16 v[54:57], v[130:133], v[154:157], v[54:57]
	v_mfma_f32_16x16x32_bf16 v[40:43], v[138:141], v[154:157], v[40:43]
	v_mfma_f32_16x16x32_bf16 v[36:39], v[130:133], v[162:165], v[36:39]
	v_mfma_f32_16x16x32_bf16 v[24:27], v[138:141], v[162:165], v[24:27]
	v_mfma_f32_16x16x32_bf16 v[20:23], v[130:133], v[170:173], v[20:23]
	v_mfma_f32_16x16x32_bf16 v[8:11], v[138:141], v[170:173], v[8:11]
	v_mfma_f32_16x16x32_bf16 v[62:65], v[134:137], v[150:153], v[62:65]
	v_mfma_f32_16x16x32_bf16 v[58:61], v[142:145], v[150:153], v[58:61]
	v_mfma_f32_16x16x32_bf16 v[54:57], v[134:137], v[158:161], v[54:57]
	v_mfma_f32_16x16x32_bf16 v[40:43], v[142:145], v[158:161], v[40:43]
	v_mfma_f32_16x16x32_bf16 v[36:39], v[134:137], v[166:169], v[36:39]
	v_mfma_f32_16x16x32_bf16 v[24:27], v[142:145], v[166:169], v[24:27]
	v_mfma_f32_16x16x32_bf16 v[20:23], v[134:137], v[174:177], v[20:23]
	v_mfma_f32_16x16x32_bf16 v[8:11], v[142:145], v[174:177], v[8:11]
	s_setprio 0
	s_barrier
	s_add_u32 s34, s26, 0x40000
	s_addc_u32 s35, s27, 0
	s_add_i32 s31, s50, s40
	s_mov_b32 m0, s31
	s_nop 0
	global_load_lds_dwordx4 v48, s[34:35]
	s_add_i32 m0, s31, 0x2000
	s_nop 0
	global_load_lds_dwordx4 v190, s[34:35]
	s_waitcnt vmcnt(6)
	s_barrier
	s_setprio 1
	v_mfma_f32_16x16x32_bf16 v[50:53], v[178:181], v[146:149], v[50:53]
	v_mfma_f32_16x16x32_bf16 v[44:47], v[186:189], v[146:149], v[44:47]
	v_mfma_f32_16x16x32_bf16 v[32:35], v[178:181], v[154:157], v[32:35]
	v_mfma_f32_16x16x32_bf16 v[28:31], v[186:189], v[154:157], v[28:31]
	v_mfma_f32_16x16x32_bf16 v[16:19], v[178:181], v[162:165], v[16:19]
	v_mfma_f32_16x16x32_bf16 v[12:15], v[186:189], v[162:165], v[12:15]
	v_mfma_f32_16x16x32_bf16 v[4:7], v[178:181], v[170:173], v[4:7]
	v_mfma_f32_16x16x32_bf16 v[0:3], v[186:189], v[170:173], v[0:3]
	v_mfma_f32_16x16x32_bf16 v[50:53], v[182:185], v[150:153], v[50:53]
	v_mfma_f32_16x16x32_bf16 v[44:47], v[204:207], v[150:153], v[44:47]
	v_mfma_f32_16x16x32_bf16 v[32:35], v[182:185], v[158:161], v[32:35]
	v_mfma_f32_16x16x32_bf16 v[28:31], v[204:207], v[158:161], v[28:31]
	v_mfma_f32_16x16x32_bf16 v[16:19], v[182:185], v[166:169], v[16:19]
	v_mfma_f32_16x16x32_bf16 v[12:15], v[204:207], v[166:169], v[12:15]
	v_mfma_f32_16x16x32_bf16 v[4:7], v[182:185], v[174:177], v[4:7]
	v_mfma_f32_16x16x32_bf16 v[0:3], v[204:207], v[174:177], v[0:3]
	s_setprio 0
	s_add_i32 s31, 0, 0x18000
	v_add_u32_e32 v142, s31, v208
	s_barrier
	ds_read_b128 v[130:133], v142
	ds_read_b128 v[134:137], v142 offset:1024
	ds_read_b128 v[138:141], v142 offset:2048
	ds_read_b128 v[142:145], v142 offset:3072
	s_add_u32 s28, s28, 0x40000
	s_addc_u32 s29, s29, 0
	s_mov_b32 m0, s43
	ds_read_b128 v[146:149], v210 offset:32768
	ds_read_b128 v[150:153], v210 offset:33792
	ds_read_b128 v[154:157], v210 offset:34816
	ds_read_b128 v[158:161], v210 offset:35840
	ds_read_b128 v[162:165], v210 offset:36864
	ds_read_b128 v[166:169], v210 offset:37888
	ds_read_b128 v[170:173], v210 offset:38912
	ds_read_b128 v[174:177], v210 offset:39936
	global_load_lds_dwordx4 v48, s[28:29]
	s_mov_b32 m0, s44
	s_nop 0
	global_load_lds_dwordx4 v190, s[28:29]
	s_waitcnt lgkmcnt(8)
	s_barrier
	s_waitcnt lgkmcnt(0)
	s_setprio 1
	s_waitcnt lgkmcnt(0)
	v_mfma_f32_16x16x32_bf16 v[126:129], v[130:133], v[146:149], v[126:129]
	v_mfma_f32_16x16x32_bf16 v[122:125], v[138:141], v[146:149], v[122:125]
	v_mfma_f32_16x16x32_bf16 v[118:121], v[130:133], v[154:157], v[118:121]
	v_mfma_f32_16x16x32_bf16 v[106:109], v[138:141], v[154:157], v[106:109]
	v_mfma_f32_16x16x32_bf16 v[94:97], v[130:133], v[162:165], v[94:97]
	v_mfma_f32_16x16x32_bf16 v[90:93], v[138:141], v[162:165], v[90:93]
	v_mfma_f32_16x16x32_bf16 v[86:89], v[130:133], v[170:173], v[86:89]
	v_mfma_f32_16x16x32_bf16 v[74:77], v[138:141], v[170:173], v[74:77]
	v_mfma_f32_16x16x32_bf16 v[126:129], v[134:137], v[150:153], v[126:129]
	v_mfma_f32_16x16x32_bf16 v[122:125], v[142:145], v[150:153], v[122:125]
	v_mfma_f32_16x16x32_bf16 v[118:121], v[134:137], v[158:161], v[118:121]
	v_mfma_f32_16x16x32_bf16 v[106:109], v[142:145], v[158:161], v[106:109]
	v_mfma_f32_16x16x32_bf16 v[94:97], v[134:137], v[166:169], v[94:97]
	v_mfma_f32_16x16x32_bf16 v[90:93], v[142:145], v[166:169], v[90:93]
	v_mfma_f32_16x16x32_bf16 v[86:89], v[134:137], v[174:177], v[86:89]
	v_mfma_f32_16x16x32_bf16 v[74:77], v[142:145], v[174:177], v[74:77]
	s_setprio 0
	s_barrier
	s_add_i32 s28, 0, 0x1c000
	s_add_i32 s29, s31, s40
	v_add_u32_e32 v204, s28, v208
	s_add_u32 s52, s26, s66
	s_addc_u32 s53, s27, s67
	s_mov_b32 m0, s29
	ds_read_b128 v[178:181], v204
	ds_read_b128 v[182:185], v204 offset:1024
	ds_read_b128 v[186:189], v204 offset:2048
	ds_read_b128 v[204:207], v204 offset:3072
	global_load_lds_dwordx4 v48, s[52:53]
	s_add_u32 s52, s26, s66
	s_addc_u32 s53, s27, s67
	s_add_i32 m0, s29, 0x2000
	s_nop 0
	global_load_lds_dwordx4 v190, s[52:53]
	s_barrier
	s_waitcnt lgkmcnt(0)
	s_setprio 1
	s_waitcnt lgkmcnt(0)
	v_mfma_f32_16x16x32_bf16 v[114:117], v[178:181], v[146:149], v[114:117]
	v_mfma_f32_16x16x32_bf16 v[110:113], v[186:189], v[146:149], v[110:113]
	v_mfma_f32_16x16x32_bf16 v[102:105], v[178:181], v[154:157], v[102:105]
	v_mfma_f32_16x16x32_bf16 v[98:101], v[186:189], v[154:157], v[98:101]
	v_mfma_f32_16x16x32_bf16 v[82:85], v[178:181], v[162:165], v[82:85]
	v_mfma_f32_16x16x32_bf16 v[78:81], v[186:189], v[162:165], v[78:81]
	v_mfma_f32_16x16x32_bf16 v[70:73], v[178:181], v[170:173], v[70:73]
	v_mfma_f32_16x16x32_bf16 v[66:69], v[186:189], v[170:173], v[66:69]
	v_mfma_f32_16x16x32_bf16 v[114:117], v[182:185], v[150:153], v[114:117]
	v_mfma_f32_16x16x32_bf16 v[110:113], v[204:207], v[150:153], v[110:113]
	v_mfma_f32_16x16x32_bf16 v[102:105], v[182:185], v[158:161], v[102:105]
	v_mfma_f32_16x16x32_bf16 v[98:101], v[204:207], v[158:161], v[98:101]
	v_mfma_f32_16x16x32_bf16 v[82:85], v[182:185], v[166:169], v[82:85]
	v_mfma_f32_16x16x32_bf16 v[78:81], v[204:207], v[166:169], v[78:81]
	v_mfma_f32_16x16x32_bf16 v[70:73], v[182:185], v[174:177], v[70:73]
	v_mfma_f32_16x16x32_bf16 v[66:69], v[204:207], v[174:177], v[66:69]
	s_setprio 0
	s_mov_b32 m0, s47
	v_lshl_add_u64 v[212:213], v[216:217], 0, s[66:67]
	s_barrier
	ds_read_b128 v[146:149], v210 offset:49152
	ds_read_b128 v[150:153], v210 offset:50176
	ds_read_b128 v[154:157], v210 offset:51200
	ds_read_b128 v[158:161], v210 offset:52224
	ds_read_b128 v[162:165], v210 offset:53248
	ds_read_b128 v[166:169], v210 offset:54272
	ds_read_b128 v[170:173], v210 offset:55296
	ds_read_b128 v[174:177], v210 offset:56320
	global_load_lds_dwordx4 v[212:213], off
	v_lshl_add_u64 v[212:213], v[218:219], 0, s[66:67]
	s_mov_b32 m0, s48
	s_nop 0
	global_load_lds_dwordx4 v[212:213], off
	s_barrier
	s_waitcnt lgkmcnt(0)
	s_setprio 1
	s_waitcnt lgkmcnt(0)
	v_mfma_f32_16x16x32_bf16 v[62:65], v[130:133], v[146:149], v[62:65]
	v_mfma_f32_16x16x32_bf16 v[58:61], v[138:141], v[146:149], v[58:61]
	v_mfma_f32_16x16x32_bf16 v[54:57], v[130:133], v[154:157], v[54:57]
	v_mfma_f32_16x16x32_bf16 v[40:43], v[138:141], v[154:157], v[40:43]
	v_mfma_f32_16x16x32_bf16 v[36:39], v[130:133], v[162:165], v[36:39]
	v_mfma_f32_16x16x32_bf16 v[24:27], v[138:141], v[162:165], v[24:27]
	v_mfma_f32_16x16x32_bf16 v[20:23], v[130:133], v[170:173], v[20:23]
	v_mfma_f32_16x16x32_bf16 v[8:11], v[138:141], v[170:173], v[8:11]
	v_mfma_f32_16x16x32_bf16 v[62:65], v[134:137], v[150:153], v[62:65]
	v_mfma_f32_16x16x32_bf16 v[58:61], v[142:145], v[150:153], v[58:61]
	v_mfma_f32_16x16x32_bf16 v[54:57], v[134:137], v[158:161], v[54:57]
	v_mfma_f32_16x16x32_bf16 v[40:43], v[142:145], v[158:161], v[40:43]
	v_mfma_f32_16x16x32_bf16 v[36:39], v[134:137], v[166:169], v[36:39]
	v_mfma_f32_16x16x32_bf16 v[24:27], v[142:145], v[166:169], v[24:27]
	v_mfma_f32_16x16x32_bf16 v[20:23], v[134:137], v[174:177], v[20:23]
	v_mfma_f32_16x16x32_bf16 v[8:11], v[142:145], v[174:177], v[8:11]
	s_setprio 0
	s_barrier
	s_add_u32 s26, s26, 0x40080
	s_addc_u32 s27, s27, 0
	s_add_i32 s28, s28, s40
	s_mov_b32 m0, s28
	s_nop 0
	global_load_lds_dwordx4 v48, s[26:27]
	s_add_i32 m0, s28, 0x2000
	s_nop 0
	global_load_lds_dwordx4 v190, s[26:27]
	s_waitcnt vmcnt(6)
	s_barrier
	s_setprio 1
	v_mfma_f32_16x16x32_bf16 v[50:53], v[178:181], v[146:149], v[50:53]
	v_mfma_f32_16x16x32_bf16 v[44:47], v[186:189], v[146:149], v[44:47]
	v_mfma_f32_16x16x32_bf16 v[32:35], v[178:181], v[154:157], v[32:35]
	v_mfma_f32_16x16x32_bf16 v[28:31], v[186:189], v[154:157], v[28:31]
	v_mfma_f32_16x16x32_bf16 v[16:19], v[178:181], v[162:165], v[16:19]
	v_mfma_f32_16x16x32_bf16 v[12:15], v[186:189], v[162:165], v[12:15]
	v_mfma_f32_16x16x32_bf16 v[4:7], v[178:181], v[170:173], v[4:7]
	v_mfma_f32_16x16x32_bf16 v[0:3], v[186:189], v[170:173], v[0:3]
	v_mfma_f32_16x16x32_bf16 v[50:53], v[182:185], v[150:153], v[50:53]
	v_mfma_f32_16x16x32_bf16 v[44:47], v[204:207], v[150:153], v[44:47]
	v_mfma_f32_16x16x32_bf16 v[32:35], v[182:185], v[158:161], v[32:35]
	v_mfma_f32_16x16x32_bf16 v[28:31], v[204:207], v[158:161], v[28:31]
	v_mfma_f32_16x16x32_bf16 v[16:19], v[182:185], v[166:169], v[16:19]
	v_mfma_f32_16x16x32_bf16 v[12:15], v[204:207], v[166:169], v[12:15]
	v_mfma_f32_16x16x32_bf16 v[4:7], v[182:185], v[174:177], v[4:7]
	v_mfma_f32_16x16x32_bf16 v[0:3], v[204:207], v[174:177], v[0:3]
	s_setprio 0
	s_add_i32 s30, s30, 2
	s_add_u32 s24, s24, 0x100
	s_addc_u32 s25, s25, 0
	s_add_u32 s15, s15, 0x100
	s_addc_u32 s17, s17, 0
	s_cmp_gt_u32 s30, 13
	s_barrier
	s_cbranch_scc0 .LBB0_1219
	s_mul_hi_i32 s15, s22, 0x38e38e39
	s_lshr_b32 s17, s15, 31
	s_ashr_i32 s15, s15, 1
	s_add_i32 s24, s15, s17
	s_mul_i32 s15, s24, -9
	s_add_i32 s28, s15, s22
	s_cmp_eq_u32 s28, 0
	s_cselect_b64 s[26:27], -1, 0
	s_ashr_i32 s25, s24, 31
	s_cmp_lg_u32 s28, 0
	s_cbranch_scc0 .LBB0_1222
	s_ashr_i32 s29, s28, 31
	s_lshl_b64 s[28:29], s[28:29], 18
	s_lshl_b64 s[30:31], s[24:25], 21
	s_add_u32 s15, s28, s30
	s_addc_u32 s17, s29, s31
	s_add_u32 s28, s15, 0xfffc0000
	s_addc_u32 s29, s17, -1
	s_mov_b64 s[30:31], s[6:7]
	s_cbranch_execnz .LBB0_1215
	s_branch .LBB0_1214

.LBB0_1356:
	s_add_u32 s28, s26, 0xfffc0080
	s_addc_u32 s29, s27, -1
	s_add_i32 s46, 0, 0x10000
	v_add_u32_e32 v140, s46, v143
	ds_read_b128 v[146:149], v140
	ds_read_b128 v[150:153], v140 offset:1024
	ds_read_b128 v[154:157], v140 offset:2048
	ds_read_b128 v[158:161], v140 offset:3072
	s_cmp_eq_u32 s45, 12
	s_cselect_b32 s31, s19, s29
	s_cselect_b32 s30, s18, s28
	s_cselect_b32 s29, s21, s17
	s_cselect_b32 s28, s20, s15
	s_add_i32 m0, s23, 0xc000
	ds_read_b128 v[162:165], v145
	ds_read_b128 v[166:169], v145 offset:1024
	ds_read_b128 v[170:173], v145 offset:2048
	ds_read_b128 v[174:177], v145 offset:3072
	ds_read_b128 v[178:181], v145 offset:4096
	ds_read_b128 v[182:185], v145 offset:5120
	ds_read_b128 v[186:189], v145 offset:6144
	ds_read_b128 v[190:193], v145 offset:7168
	global_load_lds_dwordx4 v136, s[26:27]
	s_add_i32 m0, s23, 0xe000
	s_nop 0
	global_load_lds_dwordx4 v138, s[26:27]
	s_waitcnt lgkmcnt(8)
	s_barrier
	s_waitcnt lgkmcnt(0)
	s_setprio 1
	s_waitcnt lgkmcnt(0)
	v_mfma_f32_16x16x32_bf16 v[126:129], v[146:149], v[162:165], v[126:129]
	v_mfma_f32_16x16x32_bf16 v[118:121], v[154:157], v[162:165], v[118:121]
	v_mfma_f32_16x16x32_bf16 v[110:113], v[146:149], v[170:173], v[110:113]
	v_mfma_f32_16x16x32_bf16 v[102:105], v[154:157], v[170:173], v[102:105]
	v_mfma_f32_16x16x32_bf16 v[94:97], v[146:149], v[178:181], v[94:97]
	v_mfma_f32_16x16x32_bf16 v[86:89], v[154:157], v[178:181], v[86:89]
	v_mfma_f32_16x16x32_bf16 v[78:81], v[146:149], v[186:189], v[78:81]
	v_mfma_f32_16x16x32_bf16 v[70:73], v[154:157], v[186:189], v[70:73]
	v_mfma_f32_16x16x32_bf16 v[126:129], v[150:153], v[166:169], v[126:129]
	v_mfma_f32_16x16x32_bf16 v[118:121], v[158:161], v[166:169], v[118:121]
	v_mfma_f32_16x16x32_bf16 v[110:113], v[150:153], v[174:177], v[110:113]
	v_mfma_f32_16x16x32_bf16 v[102:105], v[158:161], v[174:177], v[102:105]
	v_mfma_f32_16x16x32_bf16 v[94:97], v[150:153], v[182:185], v[94:97]
	v_mfma_f32_16x16x32_bf16 v[86:89], v[158:161], v[182:185], v[86:89]
	v_mfma_f32_16x16x32_bf16 v[78:81], v[150:153], v[190:193], v[78:81]
	v_mfma_f32_16x16x32_bf16 v[70:73], v[158:161], v[190:193], v[70:73]
	s_setprio 0
	s_barrier
	s_add_i32 s48, 0, 0x14000
	v_add_u32_e32 v140, s48, v143
	s_add_i32 s46, s46, s37
	ds_read_b128 v[198:201], v140
	ds_read_b128 v[202:205], v140 offset:1024
	ds_read_b128 v[206:209], v140 offset:2048
	ds_read_b128 v[210:213], v140 offset:3072
	s_mov_b32 m0, s46
	global_load_lds_dwordx4 v48, s[28:29]
	s_add_i32 m0, s46, 0x2000
	s_nop 0
	global_load_lds_dwordx4 v130, s[28:29]
	s_barrier
	s_waitcnt lgkmcnt(0)
	s_setprio 1
	s_waitcnt lgkmcnt(0)
	v_mfma_f32_16x16x32_bf16 v[122:125], v[198:201], v[162:165], v[122:125]
	v_mfma_f32_16x16x32_bf16 v[114:117], v[206:209], v[162:165], v[114:117]
	v_mfma_f32_16x16x32_bf16 v[106:109], v[198:201], v[170:173], v[106:109]
	v_mfma_f32_16x16x32_bf16 v[98:101], v[206:209], v[170:173], v[98:101]
	v_mfma_f32_16x16x32_bf16 v[90:93], v[198:201], v[178:181], v[90:93]
	v_mfma_f32_16x16x32_bf16 v[82:85], v[206:209], v[178:181], v[82:85]
	v_mfma_f32_16x16x32_bf16 v[74:77], v[198:201], v[186:189], v[74:77]
	v_mfma_f32_16x16x32_bf16 v[66:69], v[206:209], v[186:189], v[66:69]
	v_mfma_f32_16x16x32_bf16 v[122:125], v[202:205], v[166:169], v[122:125]
	v_mfma_f32_16x16x32_bf16 v[114:117], v[210:213], v[166:169], v[114:117]
	v_mfma_f32_16x16x32_bf16 v[106:109], v[202:205], v[174:177], v[106:109]
	v_mfma_f32_16x16x32_bf16 v[98:101], v[210:213], v[174:177], v[98:101]
	v_mfma_f32_16x16x32_bf16 v[90:93], v[202:205], v[182:185], v[90:93]
	v_mfma_f32_16x16x32_bf16 v[82:85], v[210:213], v[182:185], v[82:85]
	v_mfma_f32_16x16x32_bf16 v[74:77], v[202:205], v[190:193], v[74:77]
	v_mfma_f32_16x16x32_bf16 v[66:69], v[210:213], v[190:193], v[66:69]
	s_setprio 0
	s_mov_b32 m0, s23
	v_lshl_add_u64 v[216:217], s[30:31], 0, v[134:135]
	s_barrier
	ds_read_b128 v[162:165], v145 offset:16384
	ds_read_b128 v[166:169], v145 offset:17408
	ds_read_b128 v[170:173], v145 offset:18432
	ds_read_b128 v[174:177], v145 offset:19456
	ds_read_b128 v[178:181], v145 offset:20480
	ds_read_b128 v[182:185], v145 offset:21504
	ds_read_b128 v[186:189], v145 offset:22528
	ds_read_b128 v[190:193], v145 offset:23552
	global_load_lds_dwordx4 v[216:217], off
	v_lshl_add_u64 v[218:219], s[30:31], 0, v[132:133]
	s_mov_b32 m0, s25
	s_nop 0
	global_load_lds_dwordx4 v[218:219], off
	s_barrier
	s_waitcnt lgkmcnt(0)
	s_setprio 1
	s_waitcnt lgkmcnt(0)
	v_mfma_f32_16x16x32_bf16 v[62:65], v[146:149], v[162:165], v[62:65]
	v_mfma_f32_16x16x32_bf16 v[54:57], v[154:157], v[162:165], v[54:57]
	v_mfma_f32_16x16x32_bf16 v[44:47], v[146:149], v[170:173], v[44:47]
	v_mfma_f32_16x16x32_bf16 v[36:39], v[154:157], v[170:173], v[36:39]
	v_mfma_f32_16x16x32_bf16 v[28:31], v[146:149], v[178:181], v[28:31]
	v_mfma_f32_16x16x32_bf16 v[20:23], v[154:157], v[178:181], v[20:23]
	v_mfma_f32_16x16x32_bf16 v[12:15], v[146:149], v[186:189], v[12:15]
	v_mfma_f32_16x16x32_bf16 v[4:7], v[154:157], v[186:189], v[4:7]
	v_mfma_f32_16x16x32_bf16 v[62:65], v[150:153], v[166:169], v[62:65]
	v_mfma_f32_16x16x32_bf16 v[54:57], v[158:161], v[166:169], v[54:57]
	v_mfma_f32_16x16x32_bf16 v[44:47], v[150:153], v[174:177], v[44:47]
	v_mfma_f32_16x16x32_bf16 v[36:39], v[158:161], v[174:177], v[36:39]
	v_mfma_f32_16x16x32_bf16 v[28:31], v[150:153], v[182:185], v[28:31]
	v_mfma_f32_16x16x32_bf16 v[20:23], v[158:161], v[182:185], v[20:23]
	v_mfma_f32_16x16x32_bf16 v[12:15], v[150:153], v[190:193], v[12:15]
	v_mfma_f32_16x16x32_bf16 v[4:7], v[158:161], v[190:193], v[4:7]
	s_setprio 0
	s_barrier
	s_add_u32 s46, s28, 0x40000
	s_addc_u32 s47, s29, 0
	s_add_i32 s48, s48, s37
	v_lshl_add_u64 v[146:147], s[46:47], 0, v[48:49]
	s_mov_b32 m0, s48
	s_nop 0
	global_load_lds_dwordx4 v[146:147], off
	v_lshl_add_u64 v[146:147], s[46:47], 0, v[130:131]
	s_add_i32 m0, s48, 0x2000
	s_nop 0
	global_load_lds_dwordx4 v[146:147], off
	s_waitcnt vmcnt(6)
	s_barrier
	s_setprio 1
	v_mfma_f32_16x16x32_bf16 v[58:61], v[198:201], v[162:165], v[58:61]
	v_mfma_f32_16x16x32_bf16 v[50:53], v[206:209], v[162:165], v[50:53]
	v_mfma_f32_16x16x32_bf16 v[40:43], v[198:201], v[170:173], v[40:43]
	v_mfma_f32_16x16x32_bf16 v[32:35], v[206:209], v[170:173], v[32:35]
	v_mfma_f32_16x16x32_bf16 v[24:27], v[198:201], v[178:181], v[24:27]
	v_mfma_f32_16x16x32_bf16 v[16:19], v[206:209], v[178:181], v[16:19]
	v_mfma_f32_16x16x32_bf16 v[8:11], v[198:201], v[186:189], v[8:11]
	v_mfma_f32_16x16x32_bf16 v[0:3], v[206:209], v[186:189], v[0:3]
	v_mfma_f32_16x16x32_bf16 v[58:61], v[202:205], v[166:169], v[58:61]
	v_mfma_f32_16x16x32_bf16 v[50:53], v[210:213], v[166:169], v[50:53]
	v_mfma_f32_16x16x32_bf16 v[40:43], v[202:205], v[174:177], v[40:43]
	v_mfma_f32_16x16x32_bf16 v[32:35], v[210:213], v[174:177], v[32:35]
	v_mfma_f32_16x16x32_bf16 v[24:27], v[202:205], v[182:185], v[24:27]
	v_mfma_f32_16x16x32_bf16 v[16:19], v[210:213], v[182:185], v[16:19]
	v_mfma_f32_16x16x32_bf16 v[8:11], v[202:205], v[190:193], v[8:11]
	v_mfma_f32_16x16x32_bf16 v[0:3], v[210:213], v[190:193], v[0:3]
	s_setprio 0
	s_add_i32 s46, 0, 0x18000
	v_add_u32_e32 v158, s46, v143
	s_barrier
	ds_read_b128 v[146:149], v158
	ds_read_b128 v[150:153], v158 offset:1024
	ds_read_b128 v[154:157], v158 offset:2048
	ds_read_b128 v[158:161], v158 offset:3072
	s_add_u32 s30, s30, 0x40000
	s_addc_u32 s31, s31, 0
	s_mov_b32 m0, s40
	ds_read_b128 v[162:165], v145 offset:32768
	ds_read_b128 v[166:169], v145 offset:33792
	ds_read_b128 v[170:173], v145 offset:34816
	ds_read_b128 v[174:177], v145 offset:35840
	ds_read_b128 v[178:181], v145 offset:36864
	ds_read_b128 v[182:185], v145 offset:37888
	ds_read_b128 v[186:189], v145 offset:38912
	ds_read_b128 v[190:193], v145 offset:39936
	global_load_lds_dwordx4 v134, s[30:31]
	s_mov_b32 m0, s41
	s_nop 0
	global_load_lds_dwordx4 v132, s[30:31]
	s_waitcnt lgkmcnt(8)
	s_barrier
	s_waitcnt lgkmcnt(0)
	s_setprio 1
	s_waitcnt lgkmcnt(0)
	v_mfma_f32_16x16x32_bf16 v[126:129], v[146:149], v[162:165], v[126:129]
	v_mfma_f32_16x16x32_bf16 v[118:121], v[154:157], v[162:165], v[118:121]
	v_mfma_f32_16x16x32_bf16 v[110:113], v[146:149], v[170:173], v[110:113]
	v_mfma_f32_16x16x32_bf16 v[102:105], v[154:157], v[170:173], v[102:105]
	v_mfma_f32_16x16x32_bf16 v[94:97], v[146:149], v[178:181], v[94:97]
	v_mfma_f32_16x16x32_bf16 v[86:89], v[154:157], v[178:181], v[86:89]
	v_mfma_f32_16x16x32_bf16 v[78:81], v[146:149], v[186:189], v[78:81]
	v_mfma_f32_16x16x32_bf16 v[70:73], v[154:157], v[186:189], v[70:73]
	v_mfma_f32_16x16x32_bf16 v[126:129], v[150:153], v[166:169], v[126:129]
	v_mfma_f32_16x16x32_bf16 v[118:121], v[158:161], v[166:169], v[118:121]
	v_mfma_f32_16x16x32_bf16 v[110:113], v[150:153], v[174:177], v[110:113]
	v_mfma_f32_16x16x32_bf16 v[102:105], v[158:161], v[174:177], v[102:105]
	v_mfma_f32_16x16x32_bf16 v[94:97], v[150:153], v[182:185], v[94:97]
	v_mfma_f32_16x16x32_bf16 v[86:89], v[158:161], v[182:185], v[86:89]
	v_mfma_f32_16x16x32_bf16 v[78:81], v[150:153], v[190:193], v[78:81]
	v_mfma_f32_16x16x32_bf16 v[70:73], v[158:161], v[190:193], v[70:73]
	s_setprio 0
	s_barrier
	s_add_i32 s30, 0, 0x1c000
	s_add_i32 s31, s46, s37
	v_add_u32_e32 v210, s30, v143
	s_add_u32 s46, s28, s66
	s_addc_u32 s47, s29, s67
	s_mov_b32 m0, s31
	ds_read_b128 v[198:201], v210
	ds_read_b128 v[202:205], v210 offset:1024
	ds_read_b128 v[206:209], v210 offset:2048
	ds_read_b128 v[210:213], v210 offset:3072
	global_load_lds_dwordx4 v48, s[46:47]
	s_add_u32 s46, s28, s66
	s_addc_u32 s47, s29, s67
	s_add_i32 m0, s31, 0x2000
	s_nop 0
	global_load_lds_dwordx4 v130, s[46:47]
	s_barrier
	s_waitcnt lgkmcnt(0)
	s_setprio 1
	s_waitcnt lgkmcnt(0)
	v_mfma_f32_16x16x32_bf16 v[122:125], v[198:201], v[162:165], v[122:125]
	v_mfma_f32_16x16x32_bf16 v[114:117], v[206:209], v[162:165], v[114:117]
	v_mfma_f32_16x16x32_bf16 v[106:109], v[198:201], v[170:173], v[106:109]
	v_mfma_f32_16x16x32_bf16 v[98:101], v[206:209], v[170:173], v[98:101]
	v_mfma_f32_16x16x32_bf16 v[90:93], v[198:201], v[178:181], v[90:93]
	v_mfma_f32_16x16x32_bf16 v[82:85], v[206:209], v[178:181], v[82:85]
	v_mfma_f32_16x16x32_bf16 v[74:77], v[198:201], v[186:189], v[74:77]
	v_mfma_f32_16x16x32_bf16 v[66:69], v[206:209], v[186:189], v[66:69]
	v_mfma_f32_16x16x32_bf16 v[122:125], v[202:205], v[166:169], v[122:125]
	v_mfma_f32_16x16x32_bf16 v[114:117], v[210:213], v[166:169], v[114:117]
	v_mfma_f32_16x16x32_bf16 v[106:109], v[202:205], v[174:177], v[106:109]
	v_mfma_f32_16x16x32_bf16 v[98:101], v[210:213], v[174:177], v[98:101]
	v_mfma_f32_16x16x32_bf16 v[90:93], v[202:205], v[182:185], v[90:93]
	v_mfma_f32_16x16x32_bf16 v[82:85], v[210:213], v[182:185], v[82:85]
	v_mfma_f32_16x16x32_bf16 v[74:77], v[202:205], v[190:193], v[74:77]
	v_mfma_f32_16x16x32_bf16 v[66:69], v[210:213], v[190:193], v[66:69]
	s_setprio 0
	s_mov_b32 m0, s42
	v_lshl_add_u64 v[140:141], v[216:217], 0, s[66:67]
	s_barrier
	ds_read_b128 v[162:165], v145 offset:49152
	ds_read_b128 v[166:169], v145 offset:50176
	ds_read_b128 v[170:173], v145 offset:51200
	ds_read_b128 v[174:177], v145 offset:52224
	ds_read_b128 v[178:181], v145 offset:53248
	ds_read_b128 v[182:185], v145 offset:54272
	ds_read_b128 v[186:189], v145 offset:55296
	ds_read_b128 v[190:193], v145 offset:56320
	global_load_lds_dwordx4 v[140:141], off
	v_lshl_add_u64 v[140:141], v[218:219], 0, s[66:67]
	s_mov_b32 m0, s43
	s_nop 0
	global_load_lds_dwordx4 v[140:141], off
	s_barrier
	s_waitcnt lgkmcnt(0)
	s_setprio 1
	s_waitcnt lgkmcnt(0)
	v_mfma_f32_16x16x32_bf16 v[62:65], v[146:149], v[162:165], v[62:65]
	v_mfma_f32_16x16x32_bf16 v[54:57], v[154:157], v[162:165], v[54:57]
	v_mfma_f32_16x16x32_bf16 v[44:47], v[146:149], v[170:173], v[44:47]
	v_mfma_f32_16x16x32_bf16 v[36:39], v[154:157], v[170:173], v[36:39]
	v_mfma_f32_16x16x32_bf16 v[28:31], v[146:149], v[178:181], v[28:31]
	v_mfma_f32_16x16x32_bf16 v[20:23], v[154:157], v[178:181], v[20:23]
	v_mfma_f32_16x16x32_bf16 v[12:15], v[146:149], v[186:189], v[12:15]
	v_mfma_f32_16x16x32_bf16 v[4:7], v[154:157], v[186:189], v[4:7]
	v_mfma_f32_16x16x32_bf16 v[62:65], v[150:153], v[166:169], v[62:65]
	v_mfma_f32_16x16x32_bf16 v[54:57], v[158:161], v[166:169], v[54:57]
	v_mfma_f32_16x16x32_bf16 v[44:47], v[150:153], v[174:177], v[44:47]
	v_mfma_f32_16x16x32_bf16 v[36:39], v[158:161], v[174:177], v[36:39]
	v_mfma_f32_16x16x32_bf16 v[28:31], v[150:153], v[182:185], v[28:31]
	v_mfma_f32_16x16x32_bf16 v[20:23], v[158:161], v[182:185], v[20:23]
	v_mfma_f32_16x16x32_bf16 v[12:15], v[150:153], v[190:193], v[12:15]
	v_mfma_f32_16x16x32_bf16 v[4:7], v[158:161], v[190:193], v[4:7]
	s_setprio 0
	s_barrier
	s_add_u32 s28, s28, 0x40080
	s_addc_u32 s29, s29, 0
	s_add_i32 s30, s30, s37
	s_mov_b32 m0, s30
	s_nop 0
	global_load_lds_dwordx4 v48, s[28:29]
	s_add_i32 m0, s30, 0x2000
	s_nop 0
	global_load_lds_dwordx4 v130, s[28:29]
	s_waitcnt vmcnt(6)
	s_barrier
	s_setprio 1
	v_mfma_f32_16x16x32_bf16 v[58:61], v[198:201], v[162:165], v[58:61]
	v_mfma_f32_16x16x32_bf16 v[50:53], v[206:209], v[162:165], v[50:53]
	v_mfma_f32_16x16x32_bf16 v[40:43], v[198:201], v[170:173], v[40:43]
	v_mfma_f32_16x16x32_bf16 v[32:35], v[206:209], v[170:173], v[32:35]
	v_mfma_f32_16x16x32_bf16 v[24:27], v[198:201], v[178:181], v[24:27]
	v_mfma_f32_16x16x32_bf16 v[16:19], v[206:209], v[178:181], v[16:19]
	v_mfma_f32_16x16x32_bf16 v[8:11], v[198:201], v[186:189], v[8:11]
	v_mfma_f32_16x16x32_bf16 v[0:3], v[206:209], v[186:189], v[0:3]
	v_mfma_f32_16x16x32_bf16 v[58:61], v[202:205], v[166:169], v[58:61]
	v_mfma_f32_16x16x32_bf16 v[50:53], v[210:213], v[166:169], v[50:53]
	v_mfma_f32_16x16x32_bf16 v[40:43], v[202:205], v[174:177], v[40:43]
	v_mfma_f32_16x16x32_bf16 v[32:35], v[210:213], v[174:177], v[32:35]
	v_mfma_f32_16x16x32_bf16 v[24:27], v[202:205], v[182:185], v[24:27]
	v_mfma_f32_16x16x32_bf16 v[16:19], v[210:213], v[182:185], v[16:19]
	v_mfma_f32_16x16x32_bf16 v[8:11], v[202:205], v[190:193], v[8:11]
	v_mfma_f32_16x16x32_bf16 v[0:3], v[210:213], v[190:193], v[0:3]
	s_setprio 0
	s_add_i32 s45, s45, 2
	s_add_u32 s26, s26, 0x100
	s_addc_u32 s27, s27, 0
	s_add_u32 s15, s15, 0x100
	s_addc_u32 s17, s17, 0
	s_cmp_gt_u32 s45, 13
	s_barrier
	s_cbranch_scc0 .LBB0_1356
	v_mul_f32_e32 v147, 0xbfb8aa3b, v126
	v_exp_f32_e32 v148, v147
	v_mul_f32_e32 v147, 0xbfb8aa3b, v118
	v_exp_f32_e32 v150, v147
	v_mul_f32_e32 v147, 0xbfb8aa3b, v127
	v_exp_f32_e32 v149, v147
	v_lshl_or_b32 v140, s22, 7, v144
	v_lshl_add_u32 v146, s24, 8, v142
	v_ashrrev_i32_e32 v141, 31, v140
	v_pk_add_f32 v[148:149], v[148:149], 1.0 op_sel_hi:[1,0]
	s_movk_i32 s15, 0x1600
	s_mov_b32 s22, s14
	s_mov_b32 s24, s16
	s_mov_b64 s[28:29], s[20:21]
	v_rcp_f32_e32 v147, v149
	s_nop 0
	v_mul_f32_e32 v127, v127, v147
	s_nop 0
	v_rcp_f32_e32 v147, v148
	s_nop 0
	v_mul_f32_e32 v126, v126, v147
	v_pk_mul_f32 v[122:123], v[122:123], v[126:127]
	v_mul_f32_e32 v126, 0xbfb8aa3b, v119
	v_exp_f32_e32 v151, v126
	s_nop 0
	v_pk_add_f32 v[126:127], v[150:151], 1.0 op_sel_hi:[1,0]
	s_nop 0
	s_nop 0
	v_rcp_f32_e32 v147, v127
	s_nop 0
	v_mul_f32_e32 v119, v119, v147
	s_nop 0
	v_rcp_f32_e32 v127, v126
	s_nop 0
	v_mul_f32_e32 v118, v118, v127
	v_pk_mul_f32 v[114:115], v[114:115], v[118:119]
	v_mul_f32_e32 v119, 0xbfb8aa3b, v120
	v_mul_f32_e32 v118, 0xbfb8aa3b, v128
	v_exp_f32_e32 v126, v119
	v_mul_f32_e32 v119, 0xbfb8aa3b, v129
	v_exp_f32_e32 v118, v118
	v_exp_f32_e32 v119, v119
	s_nop 0
	v_pk_add_f32 v[118:119], v[118:119], 1.0 op_sel_hi:[1,0]
	s_nop 0
	s_nop 0
	v_rcp_f32_e32 v127, v119
	s_nop 0
	v_mul_f32_e32 v119, v129, v127
	s_nop 0
	v_rcp_f32_e32 v127, v118
	s_nop 0
	v_mul_f32_e32 v118, v128, v127
	v_pk_mul_f32 v[124:125], v[124:125], v[118:119]
	v_mul_f32_e32 v118, 0xbfb8aa3b, v121
	v_exp_f32_e32 v127, v118
	s_nop 0
	v_pk_add_f32 v[118:119], v[126:127], 1.0 op_sel_hi:[1,0]
	s_nop 0
	s_nop 0
	v_rcp_f32_e32 v126, v119
	s_nop 0
	v_mul_f32_e32 v119, v121, v126
	s_nop 0
	v_rcp_f32_e32 v121, v118
	s_nop 0
	v_mul_f32_e32 v118, v120, v121
	v_pk_mul_f32 v[116:117], v[116:117], v[118:119]
	v_cvt_pk_bf16_f32 v120, v114, v115
	v_mov_b64_e32 v[114:115], s[12:13]
	v_cvt_pk_bf16_f32 v118, v122, v123
	v_cvt_pk_bf16_f32 v121, v116, v117
	v_mad_i64_i32 v[122:123], s[26:27], v146, s15, v[114:115]
	v_lshlrev_b64 v[116:117], 1, v[140:141]
	v_cvt_pk_bf16_f32 v119, v124, v125
	v_lshl_add_u64 v[122:123], v[122:123], 0, v[116:117]
	global_store_dwordx4 v[122:123], v[118:121], off
	s_nop 1
	v_mul_f32_e32 v119, 0xbfb8aa3b, v102
	v_mul_f32_e32 v118, 0xbfb8aa3b, v110
	v_exp_f32_e32 v120, v119
	v_mul_f32_e32 v119, 0xbfb8aa3b, v111
	v_exp_f32_e32 v118, v118
	v_exp_f32_e32 v119, v119
	s_nop 0
	v_pk_add_f32 v[118:119], v[118:119], 1.0 op_sel_hi:[1,0]
	s_nop 0
	s_nop 0
	v_rcp_f32_e32 v121, v119
	s_nop 0
	v_mul_f32_e32 v111, v111, v121
	s_nop 0
	v_rcp_f32_e32 v119, v118
	s_nop 0
	v_mul_f32_e32 v110, v110, v119
	v_pk_mul_f32 v[106:107], v[106:107], v[110:111]
	v_mul_f32_e32 v110, 0xbfb8aa3b, v103
	v_exp_f32_e32 v121, v110
	s_nop 0
	v_pk_add_f32 v[110:111], v[120:121], 1.0 op_sel_hi:[1,0]
	s_nop 0
	s_nop 0
	v_rcp_f32_e32 v118, v111
	s_nop 0
	v_mul_f32_e32 v103, v103, v118
	s_nop 0
	v_rcp_f32_e32 v111, v110
	s_nop 0
	v_mul_f32_e32 v102, v102, v111
	v_pk_mul_f32 v[102:103], v[98:99], v[102:103]
	v_mul_f32_e32 v99, 0xbfb8aa3b, v104
	v_mul_f32_e32 v98, 0xbfb8aa3b, v112
	v_exp_f32_e32 v110, v99
	v_mul_f32_e32 v99, 0xbfb8aa3b, v113
	v_exp_f32_e32 v98, v98
	v_exp_f32_e32 v99, v99
	s_nop 0
	v_pk_add_f32 v[98:99], v[98:99], 1.0 op_sel_hi:[1,0]
	s_nop 0
	s_nop 0
	v_rcp_f32_e32 v111, v99
	s_nop 0
	v_mul_f32_e32 v99, v113, v111
	s_nop 0
	v_rcp_f32_e32 v111, v98
	s_nop 0
	v_mul_f32_e32 v98, v112, v111
	v_pk_mul_f32 v[108:109], v[108:109], v[98:99]
	v_mul_f32_e32 v98, 0xbfb8aa3b, v105
	v_exp_f32_e32 v111, v98
	s_nop 0
	v_pk_add_f32 v[98:99], v[110:111], 1.0 op_sel_hi:[1,0]
	s_nop 0
	s_nop 0
	v_rcp_f32_e32 v110, v99
	s_nop 0
	v_mul_f32_e32 v99, v105, v110
	s_nop 0
	v_rcp_f32_e32 v105, v98
	s_nop 0
	v_mul_f32_e32 v98, v104, v105
	v_or_b32_e32 v110, 16, v146
	v_pk_mul_f32 v[104:105], v[100:101], v[98:99]
	v_cvt_pk_bf16_f32 v100, v102, v103
	v_mad_i64_i32 v[102:103], s[26:27], v110, s15, v[114:115]
	v_cvt_pk_bf16_f32 v98, v106, v107
	v_cvt_pk_bf16_f32 v99, v108, v109
	v_cvt_pk_bf16_f32 v101, v104, v105
	v_lshl_add_u64 v[102:103], v[102:103], 0, v[116:117]
	global_store_dwordx4 v[102:103], v[98:101], off
	s_nop 1
	v_mul_f32_e32 v99, 0xbfb8aa3b, v86
	v_mul_f32_e32 v98, 0xbfb8aa3b, v94
	v_exp_f32_e32 v100, v99
	v_mul_f32_e32 v99, 0xbfb8aa3b, v95
	v_exp_f32_e32 v98, v98
	v_exp_f32_e32 v99, v99
	s_nop 0
	v_pk_add_f32 v[98:99], v[98:99], 1.0 op_sel_hi:[1,0]
	s_nop 0
	s_nop 0
	v_rcp_f32_e32 v101, v99
	s_nop 0
	v_mul_f32_e32 v95, v95, v101
	s_nop 0
	v_rcp_f32_e32 v99, v98
	s_nop 0
	v_mul_f32_e32 v94, v94, v99
	v_pk_mul_f32 v[90:91], v[90:91], v[94:95]
	v_mul_f32_e32 v94, 0xbfb8aa3b, v87
	v_exp_f32_e32 v101, v94
	s_nop 0
	v_pk_add_f32 v[94:95], v[100:101], 1.0 op_sel_hi:[1,0]
	s_nop 0
	s_nop 0
	v_rcp_f32_e32 v98, v95
	s_nop 0
	v_mul_f32_e32 v87, v87, v98
	s_nop 0
	v_rcp_f32_e32 v95, v94
	s_nop 0
	v_mul_f32_e32 v86, v86, v95
	v_pk_mul_f32 v[86:87], v[82:83], v[86:87]
	v_mul_f32_e32 v83, 0xbfb8aa3b, v88
	v_mul_f32_e32 v82, 0xbfb8aa3b, v96
	v_exp_f32_e32 v94, v83
	v_mul_f32_e32 v83, 0xbfb8aa3b, v97
	v_exp_f32_e32 v82, v82
	v_exp_f32_e32 v83, v83
	s_nop 0
	v_pk_add_f32 v[82:83], v[82:83], 1.0 op_sel_hi:[1,0]
	s_nop 0
	s_nop 0
	v_rcp_f32_e32 v95, v83
	s_nop 0
	v_mul_f32_e32 v83, v97, v95
	s_nop 0
	v_rcp_f32_e32 v95, v82
	s_nop 0
	v_mul_f32_e32 v82, v96, v95
	v_pk_mul_f32 v[92:93], v[92:93], v[82:83]
	v_mul_f32_e32 v82, 0xbfb8aa3b, v89
	v_exp_f32_e32 v95, v82
	s_nop 0
	v_pk_add_f32 v[82:83], v[94:95], 1.0 op_sel_hi:[1,0]
	s_nop 0
	s_nop 0
	v_rcp_f32_e32 v94, v83
	s_nop 0
	v_mul_f32_e32 v83, v89, v94
	s_nop 0
	v_rcp_f32_e32 v89, v82
	s_nop 0
	v_mul_f32_e32 v82, v88, v89
	v_or_b32_e32 v94, 32, v146
	v_pk_mul_f32 v[88:89], v[84:85], v[82:83]
	v_cvt_pk_bf16_f32 v84, v86, v87
	v_mad_i64_i32 v[86:87], s[26:27], v94, s15, v[114:115]
	v_cvt_pk_bf16_f32 v82, v90, v91
	v_cvt_pk_bf16_f32 v83, v92, v93
	v_cvt_pk_bf16_f32 v85, v88, v89
	v_lshl_add_u64 v[86:87], v[86:87], 0, v[116:117]
	global_store_dwordx4 v[86:87], v[82:85], off
	s_nop 1
	v_mul_f32_e32 v83, 0xbfb8aa3b, v70
	v_mul_f32_e32 v82, 0xbfb8aa3b, v78
	v_exp_f32_e32 v84, v83
	v_mul_f32_e32 v83, 0xbfb8aa3b, v79
	v_exp_f32_e32 v82, v82
	v_exp_f32_e32 v83, v83
	s_nop 0
	v_pk_add_f32 v[82:83], v[82:83], 1.0 op_sel_hi:[1,0]
	s_nop 0
	s_nop 0
	v_rcp_f32_e32 v85, v83
	s_nop 0
	v_mul_f32_e32 v79, v79, v85
	s_nop 0
	v_rcp_f32_e32 v83, v82
	s_nop 0
	v_mul_f32_e32 v78, v78, v83
	v_pk_mul_f32 v[74:75], v[74:75], v[78:79]
	v_mul_f32_e32 v78, 0xbfb8aa3b, v71
	v_exp_f32_e32 v85, v78
	s_nop 0
	v_pk_add_f32 v[78:79], v[84:85], 1.0 op_sel_hi:[1,0]
	s_nop 0
	s_nop 0
	v_rcp_f32_e32 v82, v79
	s_nop 0
	v_mul_f32_e32 v71, v71, v82
	s_nop 0
	v_rcp_f32_e32 v79, v78
	s_nop 0
	v_mul_f32_e32 v70, v70, v79
	v_pk_mul_f32 v[70:71], v[66:67], v[70:71]
	v_mul_f32_e32 v67, 0xbfb8aa3b, v72
	v_mul_f32_e32 v66, 0xbfb8aa3b, v80
	v_exp_f32_e32 v78, v67
	v_mul_f32_e32 v67, 0xbfb8aa3b, v81
	v_exp_f32_e32 v66, v66
	v_exp_f32_e32 v67, v67
	s_nop 0
	v_pk_add_f32 v[66:67], v[66:67], 1.0 op_sel_hi:[1,0]
	s_nop 0
	s_nop 0
	v_rcp_f32_e32 v79, v67
	s_nop 0
	v_mul_f32_e32 v67, v81, v79
	s_nop 0
	v_rcp_f32_e32 v79, v66
	s_nop 0
	v_mul_f32_e32 v66, v80, v79
	v_pk_mul_f32 v[76:77], v[76:77], v[66:67]
	v_mul_f32_e32 v66, 0xbfb8aa3b, v73
	v_exp_f32_e32 v79, v66
	s_nop 0
	v_pk_add_f32 v[66:67], v[78:79], 1.0 op_sel_hi:[1,0]
	s_nop 0
	s_nop 0
	v_rcp_f32_e32 v78, v67
	s_nop 0
	v_mul_f32_e32 v67, v73, v78
	s_nop 0
	v_rcp_f32_e32 v73, v66
	s_nop 0
	v_mul_f32_e32 v66, v72, v73
	v_or_b32_e32 v78, 48, v146
	v_pk_mul_f32 v[72:73], v[68:69], v[66:67]
	v_cvt_pk_bf16_f32 v68, v70, v71
	v_mad_i64_i32 v[70:71], s[26:27], v78, s15, v[114:115]
	v_cvt_pk_bf16_f32 v66, v74, v75
	v_cvt_pk_bf16_f32 v67, v76, v77
	v_cvt_pk_bf16_f32 v69, v72, v73
	v_lshl_add_u64 v[70:71], v[70:71], 0, v[116:117]
	global_store_dwordx4 v[70:71], v[66:69], off
	v_add_u32_e32 v70, 0x80, v146
	s_nop 0
	v_mul_f32_e32 v67, 0xbfb8aa3b, v54
	v_mul_f32_e32 v66, 0xbfb8aa3b, v62
	v_exp_f32_e32 v68, v67
	v_mul_f32_e32 v67, 0xbfb8aa3b, v63
	v_exp_f32_e32 v66, v66
	v_exp_f32_e32 v67, v67
	s_nop 0
	v_pk_add_f32 v[66:67], v[66:67], 1.0 op_sel_hi:[1,0]
	s_nop 0
	s_nop 0
	v_rcp_f32_e32 v69, v67
	s_nop 0
	v_mul_f32_e32 v63, v63, v69
	s_nop 0
	v_rcp_f32_e32 v67, v66
	s_nop 0
	v_mul_f32_e32 v62, v62, v67
	v_pk_mul_f32 v[58:59], v[58:59], v[62:63]
	v_mul_f32_e32 v62, 0xbfb8aa3b, v55
	v_exp_f32_e32 v69, v62
	s_nop 0
	v_pk_add_f32 v[62:63], v[68:69], 1.0 op_sel_hi:[1,0]
	s_nop 0
	s_nop 0
	v_rcp_f32_e32 v66, v63
	s_nop 0
	v_mul_f32_e32 v55, v55, v66
	s_nop 0
	v_rcp_f32_e32 v63, v62
	s_nop 0
	v_mul_f32_e32 v54, v54, v63
	v_pk_mul_f32 v[54:55], v[50:51], v[54:55]
	v_mul_f32_e32 v51, 0xbfb8aa3b, v56
	v_mul_f32_e32 v50, 0xbfb8aa3b, v64
	v_exp_f32_e32 v62, v51
	v_mul_f32_e32 v51, 0xbfb8aa3b, v65
	v_exp_f32_e32 v50, v50
	v_exp_f32_e32 v51, v51
	s_nop 0
	v_pk_add_f32 v[50:51], v[50:51], 1.0 op_sel_hi:[1,0]
	s_nop 0
	s_nop 0
	v_rcp_f32_e32 v63, v51
	s_nop 0
	v_mul_f32_e32 v51, v65, v63
	s_nop 0
	v_rcp_f32_e32 v63, v50
	s_nop 0
	v_mul_f32_e32 v50, v64, v63
	v_pk_mul_f32 v[60:61], v[60:61], v[50:51]
	v_mul_f32_e32 v50, 0xbfb8aa3b, v57
	v_exp_f32_e32 v63, v50
	s_nop 0
	v_pk_add_f32 v[50:51], v[62:63], 1.0 op_sel_hi:[1,0]
	s_nop 0
	s_nop 0
	v_rcp_f32_e32 v62, v51
	s_nop 0
	v_mul_f32_e32 v51, v57, v62
	s_nop 0
	v_rcp_f32_e32 v57, v50
	s_nop 0
	v_mul_f32_e32 v50, v56, v57
	v_pk_mul_f32 v[56:57], v[52:53], v[50:51]
	v_cvt_pk_bf16_f32 v52, v54, v55
	v_mad_i64_i32 v[54:55], s[26:27], v70, s15, v[114:115]
	v_cvt_pk_bf16_f32 v50, v58, v59
	v_cvt_pk_bf16_f32 v51, v60, v61
	v_cvt_pk_bf16_f32 v53, v56, v57
	v_lshl_add_u64 v[54:55], v[54:55], 0, v[116:117]
	global_store_dwordx4 v[54:55], v[50:53], off
	s_nop 1
	v_mul_f32_e32 v51, 0xbfb8aa3b, v36
	v_mul_f32_e32 v50, 0xbfb8aa3b, v44
	v_exp_f32_e32 v52, v51
	v_mul_f32_e32 v51, 0xbfb8aa3b, v45
	v_exp_f32_e32 v50, v50
	v_exp_f32_e32 v51, v51
	s_nop 0
	v_pk_add_f32 v[50:51], v[50:51], 1.0 op_sel_hi:[1,0]
	s_nop 0
	s_nop 0
	v_rcp_f32_e32 v53, v51
	s_nop 0
	v_mul_f32_e32 v45, v45, v53
	s_nop 0
	v_rcp_f32_e32 v51, v50
	s_nop 0
	v_mul_f32_e32 v44, v44, v51
	v_pk_mul_f32 v[40:41], v[40:41], v[44:45]
	v_mul_f32_e32 v44, 0xbfb8aa3b, v37
	v_exp_f32_e32 v53, v44
	s_nop 0
	v_pk_add_f32 v[44:45], v[52:53], 1.0 op_sel_hi:[1,0]
	s_nop 0
	s_nop 0
	v_rcp_f32_e32 v50, v45
	s_nop 0
	v_mul_f32_e32 v37, v37, v50
	s_nop 0
	v_rcp_f32_e32 v45, v44
	s_nop 0
	v_mul_f32_e32 v36, v36, v45
	v_pk_mul_f32 v[36:37], v[32:33], v[36:37]
	v_mul_f32_e32 v33, 0xbfb8aa3b, v38
	v_mul_f32_e32 v32, 0xbfb8aa3b, v46
	v_exp_f32_e32 v44, v33
	v_mul_f32_e32 v33, 0xbfb8aa3b, v47
	v_exp_f32_e32 v32, v32
	v_exp_f32_e32 v33, v33
	s_nop 0
	v_pk_add_f32 v[32:33], v[32:33], 1.0 op_sel_hi:[1,0]
	s_nop 0
	s_nop 0
	v_rcp_f32_e32 v45, v33
	s_nop 0
	v_mul_f32_e32 v33, v47, v45
	s_nop 0
	v_rcp_f32_e32 v45, v32
	s_nop 0
	v_mul_f32_e32 v32, v46, v45
	v_pk_mul_f32 v[42:43], v[42:43], v[32:33]
	v_mul_f32_e32 v32, 0xbfb8aa3b, v39
	v_exp_f32_e32 v45, v32
	s_nop 0
	v_pk_add_f32 v[32:33], v[44:45], 1.0 op_sel_hi:[1,0]
	s_nop 0
	s_nop 0
	v_rcp_f32_e32 v44, v33
	s_nop 0
	v_mul_f32_e32 v33, v39, v44
	s_nop 0
	v_rcp_f32_e32 v39, v32
	s_nop 0
	v_mul_f32_e32 v32, v38, v39
	v_add_u32_e32 v44, 0x90, v146
	v_pk_mul_f32 v[38:39], v[34:35], v[32:33]
	v_cvt_pk_bf16_f32 v34, v36, v37
	v_mad_i64_i32 v[36:37], s[26:27], v44, s15, v[114:115]
	v_cvt_pk_bf16_f32 v32, v40, v41
	v_cvt_pk_bf16_f32 v33, v42, v43
	v_cvt_pk_bf16_f32 v35, v38, v39
	v_lshl_add_u64 v[36:37], v[36:37], 0, v[116:117]
	global_store_dwordx4 v[36:37], v[32:35], off
	s_nop 1
	v_mul_f32_e32 v33, 0xbfb8aa3b, v20
	v_mul_f32_e32 v32, 0xbfb8aa3b, v28
	v_exp_f32_e32 v34, v33
	v_mul_f32_e32 v33, 0xbfb8aa3b, v29
	v_exp_f32_e32 v32, v32
	v_exp_f32_e32 v33, v33
	s_nop 0
	v_pk_add_f32 v[32:33], v[32:33], 1.0 op_sel_hi:[1,0]
	s_nop 0
	s_nop 0
	v_rcp_f32_e32 v35, v33
	s_nop 0
	v_mul_f32_e32 v29, v29, v35
	s_nop 0
	v_rcp_f32_e32 v33, v32
	s_nop 0
	v_mul_f32_e32 v28, v28, v33
	v_pk_mul_f32 v[24:25], v[24:25], v[28:29]
	v_mul_f32_e32 v28, 0xbfb8aa3b, v21
	v_exp_f32_e32 v35, v28
	s_nop 0
	v_pk_add_f32 v[28:29], v[34:35], 1.0 op_sel_hi:[1,0]
	s_nop 0
	s_nop 0
	v_rcp_f32_e32 v32, v29
	s_nop 0
	v_mul_f32_e32 v21, v21, v32
	s_nop 0
	v_rcp_f32_e32 v29, v28
	s_nop 0
	v_mul_f32_e32 v20, v20, v29
	v_pk_mul_f32 v[20:21], v[16:17], v[20:21]
	v_mul_f32_e32 v17, 0xbfb8aa3b, v22
	v_mul_f32_e32 v16, 0xbfb8aa3b, v30
	v_exp_f32_e32 v28, v17
	v_mul_f32_e32 v17, 0xbfb8aa3b, v31
	v_exp_f32_e32 v16, v16
	v_exp_f32_e32 v17, v17
	s_nop 0
	v_pk_add_f32 v[16:17], v[16:17], 1.0 op_sel_hi:[1,0]
	s_nop 0
	s_nop 0
	v_rcp_f32_e32 v29, v17
	s_nop 0
	v_mul_f32_e32 v17, v31, v29
	s_nop 0
	v_rcp_f32_e32 v29, v16
	s_nop 0
	v_mul_f32_e32 v16, v30, v29
	v_pk_mul_f32 v[26:27], v[26:27], v[16:17]
	v_mul_f32_e32 v16, 0xbfb8aa3b, v23
	v_exp_f32_e32 v29, v16
	s_nop 0
	v_pk_add_f32 v[16:17], v[28:29], 1.0 op_sel_hi:[1,0]
	s_nop 0
	s_nop 0
	v_rcp_f32_e32 v28, v17
	s_nop 0
	v_mul_f32_e32 v17, v23, v28
	s_nop 0
	v_rcp_f32_e32 v23, v16
	s_nop 0
	v_mul_f32_e32 v16, v22, v23
	v_add_u32_e32 v28, 0xa0, v146
	v_pk_mul_f32 v[22:23], v[18:19], v[16:17]
	v_cvt_pk_bf16_f32 v18, v20, v21
	v_mad_i64_i32 v[20:21], s[26:27], v28, s15, v[114:115]
	v_cvt_pk_bf16_f32 v16, v24, v25
	v_cvt_pk_bf16_f32 v17, v26, v27
	v_cvt_pk_bf16_f32 v19, v22, v23
	v_lshl_add_u64 v[20:21], v[20:21], 0, v[116:117]
	global_store_dwordx4 v[20:21], v[16:19], off
	s_nop 1
	v_mul_f32_e32 v17, 0xbfb8aa3b, v4
	v_mul_f32_e32 v16, 0xbfb8aa3b, v12
	v_exp_f32_e32 v18, v17
	v_mul_f32_e32 v17, 0xbfb8aa3b, v13
	v_exp_f32_e32 v16, v16
	v_exp_f32_e32 v17, v17
	s_nop 0
	v_pk_add_f32 v[16:17], v[16:17], 1.0 op_sel_hi:[1,0]
	s_nop 0
	s_nop 0
	v_rcp_f32_e32 v19, v17
	s_nop 0
	v_mul_f32_e32 v13, v13, v19
	s_nop 0
	v_rcp_f32_e32 v17, v16
	s_nop 0
	v_mul_f32_e32 v12, v12, v17
	v_pk_mul_f32 v[8:9], v[8:9], v[12:13]
	v_mul_f32_e32 v12, 0xbfb8aa3b, v5
	v_exp_f32_e32 v19, v12
	s_nop 0
	v_pk_add_f32 v[12:13], v[18:19], 1.0 op_sel_hi:[1,0]
	s_nop 0
	s_nop 0
	v_rcp_f32_e32 v16, v13
	s_nop 0
	v_mul_f32_e32 v5, v5, v16
	s_nop 0
	v_rcp_f32_e32 v13, v12
	s_nop 0
	v_mul_f32_e32 v4, v4, v13
	v_pk_mul_f32 v[4:5], v[0:1], v[4:5]
	v_mul_f32_e32 v1, 0xbfb8aa3b, v6
	v_mul_f32_e32 v0, 0xbfb8aa3b, v14
	v_exp_f32_e32 v12, v1
	v_mul_f32_e32 v1, 0xbfb8aa3b, v15
	v_exp_f32_e32 v0, v0
	v_exp_f32_e32 v1, v1
	s_nop 0
	v_pk_add_f32 v[0:1], v[0:1], 1.0 op_sel_hi:[1,0]
	s_nop 0
	s_nop 0
	v_rcp_f32_e32 v13, v1
	s_nop 0
	v_mul_f32_e32 v1, v15, v13
	s_nop 0
	v_rcp_f32_e32 v13, v0
	s_nop 0
	v_mul_f32_e32 v0, v14, v13
	v_pk_mul_f32 v[10:11], v[10:11], v[0:1]
	v_mul_f32_e32 v0, 0xbfb8aa3b, v7
	v_exp_f32_e32 v13, v0
	s_nop 0
	v_pk_add_f32 v[0:1], v[12:13], 1.0 op_sel_hi:[1,0]
	s_nop 0
	s_nop 0
	v_rcp_f32_e32 v12, v1
	s_nop 0
	v_mul_f32_e32 v1, v7, v12
	s_nop 0
	v_rcp_f32_e32 v7, v0
	s_nop 0
	v_mul_f32_e32 v0, v6, v7
	v_add_u32_e32 v12, 0xb0, v146
	v_pk_mul_f32 v[6:7], v[2:3], v[0:1]
	v_cvt_pk_bf16_f32 v2, v4, v5
	v_mad_i64_i32 v[4:5], s[26:27], v12, s15, v[114:115]
	v_cvt_pk_bf16_f32 v0, v8, v9
	v_cvt_pk_bf16_f32 v1, v10, v11
	v_cvt_pk_bf16_f32 v3, v6, v7
	v_lshl_add_u64 v[4:5], v[4:5], 0, v[116:117]
	s_and_b64 vcc, exec, s[0:1]
	s_mov_b64 s[26:27], s[18:19]
	global_store_dwordx4 v[4:5], v[0:3], off
	s_cbranch_vccz .LBB0_1353
	s_waitcnt vmcnt(0)
	s_cmpk_gt_u32 s5, 0xff
	s_cbranch_scc1 .LBB0_1360
	s_barrier

.LBB0_1421:
	s_add_u32 s18, s16, 0x100
	s_addc_u32 s19, s17, 0
	s_add_i32 s47, 0, 0x10000
	v_add_u32_e32 v142, s47, v204
	ds_read_b128 v[130:133], v142
	ds_read_b128 v[134:137], v142 offset:1024
	ds_read_b128 v[138:141], v142 offset:2048
	ds_read_b128 v[142:145], v142 offset:3072
	s_cmp_eq_u32 s46, 40
	s_cselect_b32 s23, s11, s19
	s_cselect_b32 s22, s10, s18
	s_cselect_b32 s21, s13, s45
	s_cselect_b32 s20, s12, s44
	v_lshl_add_u64 v[188:189], s[16:17], 0, v[152:153]
	s_add_i32 m0, s31, 0xc000
	ds_read_b128 v[156:159], v206
	ds_read_b128 v[160:163], v206 offset:1024
	ds_read_b128 v[164:167], v206 offset:2048
	ds_read_b128 v[168:171], v206 offset:3072
	ds_read_b128 v[172:175], v206 offset:4096
	ds_read_b128 v[176:179], v206 offset:5120
	ds_read_b128 v[180:183], v206 offset:6144
	ds_read_b128 v[184:187], v206 offset:7168
	global_load_lds_dwordx4 v[188:189], off
	v_lshl_add_u64 v[188:189], s[16:17], 0, v[154:155]
	s_add_i32 m0, s31, 0xe000
	s_nop 0
	global_load_lds_dwordx4 v[188:189], off
	s_waitcnt lgkmcnt(8)
	s_barrier
	s_waitcnt lgkmcnt(0)
	s_setprio 1
	s_waitcnt lgkmcnt(0)
	v_mfma_f32_16x16x32_bf16 v[126:129], v[130:133], v[156:159], v[126:129]
	v_mfma_f32_16x16x32_bf16 v[122:125], v[138:141], v[156:159], v[122:125]
	v_mfma_f32_16x16x32_bf16 v[114:117], v[130:133], v[164:167], v[114:117]
	v_mfma_f32_16x16x32_bf16 v[106:109], v[138:141], v[164:167], v[106:109]
	v_mfma_f32_16x16x32_bf16 v[98:101], v[130:133], v[172:175], v[98:101]
	v_mfma_f32_16x16x32_bf16 v[90:93], v[138:141], v[172:175], v[90:93]
	v_mfma_f32_16x16x32_bf16 v[82:85], v[130:133], v[180:183], v[82:85]
	v_mfma_f32_16x16x32_bf16 v[74:77], v[138:141], v[180:183], v[74:77]
	v_mfma_f32_16x16x32_bf16 v[126:129], v[134:137], v[160:163], v[126:129]
	v_mfma_f32_16x16x32_bf16 v[122:125], v[142:145], v[160:163], v[122:125]
	v_mfma_f32_16x16x32_bf16 v[114:117], v[134:137], v[168:171], v[114:117]
	v_mfma_f32_16x16x32_bf16 v[106:109], v[142:145], v[168:171], v[106:109]
	v_mfma_f32_16x16x32_bf16 v[98:101], v[134:137], v[176:179], v[98:101]
	v_mfma_f32_16x16x32_bf16 v[90:93], v[142:145], v[176:179], v[90:93]
	v_mfma_f32_16x16x32_bf16 v[82:85], v[134:137], v[184:187], v[82:85]
	v_mfma_f32_16x16x32_bf16 v[74:77], v[142:145], v[184:187], v[74:77]
	s_setprio 0
	s_barrier
	s_add_i32 s48, 0, 0x14000
	v_add_u32_e32 v192, s48, v204
	s_add_i32 s16, s47, s25
	ds_read_b128 v[188:191], v192
	ds_read_b128 v[198:201], v192 offset:1024
	ds_read_b128 v[208:211], v192 offset:2048
	ds_read_b128 v[212:215], v192 offset:3072
	s_mov_b32 m0, s16
	global_load_lds_dwordx4 v48, s[20:21]
	s_add_i32 m0, s16, 0x2000
	s_nop 0
	global_load_lds_dwordx4 v146, s[20:21]
	s_barrier
	s_waitcnt lgkmcnt(0)
	s_setprio 1
	s_waitcnt lgkmcnt(0)
	v_mfma_f32_16x16x32_bf16 v[118:121], v[188:191], v[156:159], v[118:121]
	v_mfma_f32_16x16x32_bf16 v[110:113], v[208:211], v[156:159], v[110:113]
	v_mfma_f32_16x16x32_bf16 v[102:105], v[188:191], v[164:167], v[102:105]
	v_mfma_f32_16x16x32_bf16 v[94:97], v[208:211], v[164:167], v[94:97]
	v_mfma_f32_16x16x32_bf16 v[86:89], v[188:191], v[172:175], v[86:89]
	v_mfma_f32_16x16x32_bf16 v[78:81], v[208:211], v[172:175], v[78:81]
	v_mfma_f32_16x16x32_bf16 v[70:73], v[188:191], v[180:183], v[70:73]
	v_mfma_f32_16x16x32_bf16 v[66:69], v[208:211], v[180:183], v[66:69]
	v_mfma_f32_16x16x32_bf16 v[118:121], v[198:201], v[160:163], v[118:121]
	v_mfma_f32_16x16x32_bf16 v[110:113], v[212:215], v[160:163], v[110:113]
	v_mfma_f32_16x16x32_bf16 v[102:105], v[198:201], v[168:171], v[102:105]
	v_mfma_f32_16x16x32_bf16 v[94:97], v[212:215], v[168:171], v[94:97]
	v_mfma_f32_16x16x32_bf16 v[86:89], v[198:201], v[176:179], v[86:89]
	v_mfma_f32_16x16x32_bf16 v[78:81], v[212:215], v[176:179], v[78:81]
	v_mfma_f32_16x16x32_bf16 v[70:73], v[198:201], v[184:187], v[70:73]
	v_mfma_f32_16x16x32_bf16 v[66:69], v[212:215], v[184:187], v[66:69]
	s_setprio 0
	s_mov_b32 m0, s31
	v_lshl_add_u64 v[216:217], s[22:23], 0, v[48:49]
	s_barrier
	ds_read_b128 v[156:159], v206 offset:16384
	ds_read_b128 v[160:163], v206 offset:17408
	ds_read_b128 v[164:167], v206 offset:18432
	ds_read_b128 v[168:171], v206 offset:19456
	ds_read_b128 v[172:175], v206 offset:20480
	ds_read_b128 v[176:179], v206 offset:21504
	ds_read_b128 v[180:183], v206 offset:22528
	ds_read_b128 v[184:187], v206 offset:23552
	global_load_lds_dwordx4 v[216:217], off
	v_lshl_add_u64 v[218:219], s[22:23], 0, v[146:147]
	s_mov_b32 m0, s34
	s_nop 0
	global_load_lds_dwordx4 v[218:219], off
	s_barrier
	s_waitcnt lgkmcnt(0)
	s_setprio 1
	s_waitcnt lgkmcnt(0)
	v_mfma_f32_16x16x32_bf16 v[62:65], v[130:133], v[156:159], v[62:65]
	v_mfma_f32_16x16x32_bf16 v[58:61], v[138:141], v[156:159], v[58:61]
	v_mfma_f32_16x16x32_bf16 v[50:53], v[130:133], v[164:167], v[50:53]
	v_mfma_f32_16x16x32_bf16 v[40:43], v[138:141], v[164:167], v[40:43]
	v_mfma_f32_16x16x32_bf16 v[32:35], v[130:133], v[172:175], v[32:35]
	v_mfma_f32_16x16x32_bf16 v[24:27], v[138:141], v[172:175], v[24:27]
	v_mfma_f32_16x16x32_bf16 v[16:19], v[130:133], v[180:183], v[16:19]
	v_mfma_f32_16x16x32_bf16 v[8:11], v[138:141], v[180:183], v[8:11]
	v_mfma_f32_16x16x32_bf16 v[62:65], v[134:137], v[160:163], v[62:65]
	v_mfma_f32_16x16x32_bf16 v[58:61], v[142:145], v[160:163], v[58:61]
	v_mfma_f32_16x16x32_bf16 v[50:53], v[134:137], v[168:171], v[50:53]
	v_mfma_f32_16x16x32_bf16 v[40:43], v[142:145], v[168:171], v[40:43]
	v_mfma_f32_16x16x32_bf16 v[32:35], v[134:137], v[176:179], v[32:35]
	v_mfma_f32_16x16x32_bf16 v[24:27], v[142:145], v[176:179], v[24:27]
	v_mfma_f32_16x16x32_bf16 v[16:19], v[134:137], v[184:187], v[16:19]
	v_mfma_f32_16x16x32_bf16 v[8:11], v[142:145], v[184:187], v[8:11]
	s_setprio 0
	s_barrier
	s_add_u32 s16, s20, 0xb0000
	s_addc_u32 s17, s21, 0
	s_add_i32 s47, s48, s25
	s_mov_b32 m0, s47
	s_nop 0
	global_load_lds_dwordx4 v48, s[16:17]
	s_add_i32 m0, s47, 0x2000
	s_nop 0
	global_load_lds_dwordx4 v146, s[16:17]
	s_waitcnt vmcnt(6)
	s_barrier
	s_setprio 1
	v_mfma_f32_16x16x32_bf16 v[54:57], v[188:191], v[156:159], v[54:57]
	v_mfma_f32_16x16x32_bf16 v[44:47], v[208:211], v[156:159], v[44:47]
	v_mfma_f32_16x16x32_bf16 v[36:39], v[188:191], v[164:167], v[36:39]
	v_mfma_f32_16x16x32_bf16 v[28:31], v[208:211], v[164:167], v[28:31]
	v_mfma_f32_16x16x32_bf16 v[20:23], v[188:191], v[172:175], v[20:23]
	v_mfma_f32_16x16x32_bf16 v[12:15], v[208:211], v[172:175], v[12:15]
	v_mfma_f32_16x16x32_bf16 v[4:7], v[188:191], v[180:183], v[4:7]
	v_mfma_f32_16x16x32_bf16 v[0:3], v[208:211], v[180:183], v[0:3]
	v_mfma_f32_16x16x32_bf16 v[54:57], v[198:201], v[160:163], v[54:57]
	v_mfma_f32_16x16x32_bf16 v[44:47], v[212:215], v[160:163], v[44:47]
	v_mfma_f32_16x16x32_bf16 v[36:39], v[198:201], v[168:171], v[36:39]
	v_mfma_f32_16x16x32_bf16 v[28:31], v[212:215], v[168:171], v[28:31]
	v_mfma_f32_16x16x32_bf16 v[20:23], v[198:201], v[176:179], v[20:23]
	v_mfma_f32_16x16x32_bf16 v[12:15], v[212:215], v[176:179], v[12:15]
	v_mfma_f32_16x16x32_bf16 v[4:7], v[198:201], v[184:187], v[4:7]
	v_mfma_f32_16x16x32_bf16 v[0:3], v[212:215], v[184:187], v[0:3]
	s_setprio 0
	s_add_i32 s47, 0, 0x18000
	v_add_u32_e32 v142, s47, v204
	s_barrier
	ds_read_b128 v[130:133], v142
	ds_read_b128 v[134:137], v142 offset:1024
	ds_read_b128 v[138:141], v142 offset:2048
	ds_read_b128 v[142:145], v142 offset:3072
	s_add_u32 s16, s22, 0xb0000
	s_addc_u32 s17, s23, 0
	s_mov_b32 m0, s35
	ds_read_b128 v[156:159], v206 offset:32768
	ds_read_b128 v[160:163], v206 offset:33792
	ds_read_b128 v[164:167], v206 offset:34816
	ds_read_b128 v[168:171], v206 offset:35840
	ds_read_b128 v[172:175], v206 offset:36864
	ds_read_b128 v[176:179], v206 offset:37888
	ds_read_b128 v[180:183], v206 offset:38912
	ds_read_b128 v[184:187], v206 offset:39936
	global_load_lds_dwordx4 v48, s[16:17]
	s_mov_b32 m0, s36
	s_nop 0
	global_load_lds_dwordx4 v146, s[16:17]
	s_waitcnt lgkmcnt(8)
	s_barrier
	s_waitcnt lgkmcnt(0)
	s_setprio 1
	s_waitcnt lgkmcnt(0)
	v_mfma_f32_16x16x32_bf16 v[126:129], v[130:133], v[156:159], v[126:129]
	v_mfma_f32_16x16x32_bf16 v[122:125], v[138:141], v[156:159], v[122:125]
	v_mfma_f32_16x16x32_bf16 v[114:117], v[130:133], v[164:167], v[114:117]
	v_mfma_f32_16x16x32_bf16 v[106:109], v[138:141], v[164:167], v[106:109]
	v_mfma_f32_16x16x32_bf16 v[98:101], v[130:133], v[172:175], v[98:101]
	v_mfma_f32_16x16x32_bf16 v[90:93], v[138:141], v[172:175], v[90:93]
	v_mfma_f32_16x16x32_bf16 v[82:85], v[130:133], v[180:183], v[82:85]
	v_mfma_f32_16x16x32_bf16 v[74:77], v[138:141], v[180:183], v[74:77]
	v_mfma_f32_16x16x32_bf16 v[126:129], v[134:137], v[160:163], v[126:129]
	v_mfma_f32_16x16x32_bf16 v[122:125], v[142:145], v[160:163], v[122:125]
	v_mfma_f32_16x16x32_bf16 v[114:117], v[134:137], v[168:171], v[114:117]
	v_mfma_f32_16x16x32_bf16 v[106:109], v[142:145], v[168:171], v[106:109]
	v_mfma_f32_16x16x32_bf16 v[98:101], v[134:137], v[176:179], v[98:101]
	v_mfma_f32_16x16x32_bf16 v[90:93], v[142:145], v[176:179], v[90:93]
	v_mfma_f32_16x16x32_bf16 v[82:85], v[134:137], v[184:187], v[82:85]
	v_mfma_f32_16x16x32_bf16 v[74:77], v[142:145], v[184:187], v[74:77]
	s_setprio 0
	s_barrier
	s_add_i32 s22, 0, 0x1c000
	s_add_i32 s16, s47, s25
	v_add_u32_e32 v207, s22, v204
	s_add_u32 s52, s20, s66
	s_addc_u32 s53, s21, s67
	s_mov_b32 m0, s16
	ds_read_b128 v[188:191], v207
	ds_read_b128 v[198:201], v207 offset:1024
	ds_read_b128 v[208:211], v207 offset:2048
	ds_read_b128 v[212:215], v207 offset:3072
	global_load_lds_dwordx4 v48, s[52:53]
	s_add_u32 s52, s20, s66
	s_addc_u32 s53, s21, s67
	s_add_i32 m0, s16, 0x2000
	s_nop 0
	global_load_lds_dwordx4 v146, s[52:53]
	s_barrier
	s_waitcnt lgkmcnt(0)
	s_setprio 1
	s_waitcnt lgkmcnt(0)
	v_mfma_f32_16x16x32_bf16 v[118:121], v[188:191], v[156:159], v[118:121]
	v_mfma_f32_16x16x32_bf16 v[110:113], v[208:211], v[156:159], v[110:113]
	v_mfma_f32_16x16x32_bf16 v[102:105], v[188:191], v[164:167], v[102:105]
	v_mfma_f32_16x16x32_bf16 v[94:97], v[208:211], v[164:167], v[94:97]
	v_mfma_f32_16x16x32_bf16 v[86:89], v[188:191], v[172:175], v[86:89]
	v_mfma_f32_16x16x32_bf16 v[78:81], v[208:211], v[172:175], v[78:81]
	v_mfma_f32_16x16x32_bf16 v[70:73], v[188:191], v[180:183], v[70:73]
	v_mfma_f32_16x16x32_bf16 v[66:69], v[208:211], v[180:183], v[66:69]
	v_mfma_f32_16x16x32_bf16 v[118:121], v[198:201], v[160:163], v[118:121]
	v_mfma_f32_16x16x32_bf16 v[110:113], v[212:215], v[160:163], v[110:113]
	v_mfma_f32_16x16x32_bf16 v[102:105], v[198:201], v[168:171], v[102:105]
	v_mfma_f32_16x16x32_bf16 v[94:97], v[212:215], v[168:171], v[94:97]
	v_mfma_f32_16x16x32_bf16 v[86:89], v[198:201], v[176:179], v[86:89]
	v_mfma_f32_16x16x32_bf16 v[78:81], v[212:215], v[176:179], v[78:81]
	v_mfma_f32_16x16x32_bf16 v[70:73], v[198:201], v[184:187], v[70:73]
	v_mfma_f32_16x16x32_bf16 v[66:69], v[212:215], v[184:187], v[66:69]
	s_setprio 0
	s_mov_b32 m0, s39
	v_lshl_add_u64 v[192:193], v[216:217], 0, s[66:67]
	s_barrier
	ds_read_b128 v[156:159], v206 offset:49152
	ds_read_b128 v[160:163], v206 offset:50176
	ds_read_b128 v[164:167], v206 offset:51200
	ds_read_b128 v[168:171], v206 offset:52224
	ds_read_b128 v[172:175], v206 offset:53248
	ds_read_b128 v[176:179], v206 offset:54272
	ds_read_b128 v[180:183], v206 offset:55296
	ds_read_b128 v[184:187], v206 offset:56320
	global_load_lds_dwordx4 v[192:193], off
	v_lshl_add_u64 v[192:193], v[218:219], 0, s[66:67]
	s_mov_b32 m0, s40
	s_nop 0
	global_load_lds_dwordx4 v[192:193], off
	s_barrier
	s_waitcnt lgkmcnt(0)
	s_setprio 1
	s_waitcnt lgkmcnt(0)
	v_mfma_f32_16x16x32_bf16 v[62:65], v[130:133], v[156:159], v[62:65]
	v_mfma_f32_16x16x32_bf16 v[58:61], v[138:141], v[156:159], v[58:61]
	v_mfma_f32_16x16x32_bf16 v[50:53], v[130:133], v[164:167], v[50:53]
	v_mfma_f32_16x16x32_bf16 v[40:43], v[138:141], v[164:167], v[40:43]
	v_mfma_f32_16x16x32_bf16 v[32:35], v[130:133], v[172:175], v[32:35]
	v_mfma_f32_16x16x32_bf16 v[24:27], v[138:141], v[172:175], v[24:27]
	v_mfma_f32_16x16x32_bf16 v[16:19], v[130:133], v[180:183], v[16:19]
	v_mfma_f32_16x16x32_bf16 v[8:11], v[138:141], v[180:183], v[8:11]
	v_mfma_f32_16x16x32_bf16 v[62:65], v[134:137], v[160:163], v[62:65]
	v_mfma_f32_16x16x32_bf16 v[58:61], v[142:145], v[160:163], v[58:61]
	v_mfma_f32_16x16x32_bf16 v[50:53], v[134:137], v[168:171], v[50:53]
	v_mfma_f32_16x16x32_bf16 v[40:43], v[142:145], v[168:171], v[40:43]
	v_mfma_f32_16x16x32_bf16 v[32:35], v[134:137], v[176:179], v[32:35]
	v_mfma_f32_16x16x32_bf16 v[24:27], v[142:145], v[176:179], v[24:27]
	v_mfma_f32_16x16x32_bf16 v[16:19], v[134:137], v[184:187], v[16:19]
	v_mfma_f32_16x16x32_bf16 v[8:11], v[142:145], v[184:187], v[8:11]
	s_setprio 0
	s_barrier
	s_add_u32 s16, s20, 0xb0080
	s_addc_u32 s17, s21, 0
	s_add_i32 s20, s22, s25
	s_mov_b32 m0, s20
	s_nop 0
	global_load_lds_dwordx4 v48, s[16:17]
	s_add_i32 m0, s20, 0x2000
	s_nop 0
	global_load_lds_dwordx4 v146, s[16:17]
	s_waitcnt vmcnt(6)
	s_barrier
	s_setprio 1
	v_mfma_f32_16x16x32_bf16 v[54:57], v[188:191], v[156:159], v[54:57]
	v_mfma_f32_16x16x32_bf16 v[44:47], v[208:211], v[156:159], v[44:47]
	v_mfma_f32_16x16x32_bf16 v[36:39], v[188:191], v[164:167], v[36:39]
	v_mfma_f32_16x16x32_bf16 v[28:31], v[208:211], v[164:167], v[28:31]
	v_mfma_f32_16x16x32_bf16 v[20:23], v[188:191], v[172:175], v[20:23]
	v_mfma_f32_16x16x32_bf16 v[12:15], v[208:211], v[172:175], v[12:15]
	v_mfma_f32_16x16x32_bf16 v[4:7], v[188:191], v[180:183], v[4:7]
	v_mfma_f32_16x16x32_bf16 v[0:3], v[208:211], v[180:183], v[0:3]
	v_mfma_f32_16x16x32_bf16 v[54:57], v[198:201], v[160:163], v[54:57]
	v_mfma_f32_16x16x32_bf16 v[44:47], v[212:215], v[160:163], v[44:47]
	v_mfma_f32_16x16x32_bf16 v[36:39], v[198:201], v[168:171], v[36:39]
	v_mfma_f32_16x16x32_bf16 v[28:31], v[212:215], v[168:171], v[28:31]
	v_mfma_f32_16x16x32_bf16 v[20:23], v[198:201], v[176:179], v[20:23]
	v_mfma_f32_16x16x32_bf16 v[12:15], v[212:215], v[176:179], v[12:15]
	v_mfma_f32_16x16x32_bf16 v[4:7], v[198:201], v[184:187], v[4:7]
	v_mfma_f32_16x16x32_bf16 v[0:3], v[212:215], v[184:187], v[0:3]
	s_setprio 0
	s_add_i32 s46, s46, 2
	s_add_u32 s44, s44, 0x100
	s_addc_u32 s45, s45, 0
	s_cmp_gt_u32 s46, 41
	s_mov_b64 s[16:17], s[18:19]
	s_barrier
	s_cbranch_scc0 .LBB0_1421
	s_mul_hi_i32 s16, s14, 0x38e38e39
	s_lshr_b32 s17, s16, 31
	s_ashr_i32 s16, s16, 1
	s_add_i32 s16, s16, s17
	s_mul_i32 s17, s16, -9
	v_lshl_or_b32 v156, s15, 8, v205
	s_ashr_i32 s15, s14, 31
	s_add_i32 s18, s17, s14
	s_lshl_b64 s[14:15], s[14:15], 19
	s_ashr_i32 s17, s16, 31
	v_lshl_add_u64 v[158:159], v[150:151], 0, s[14:15]
	v_sub_co_u32_e64 v130, s[14:15], s18, 1
	s_lshl_b64 s[18:19], s[16:17], 23
	s_and_b64 s[14:15], s[14:15], exec
	v_ashrrev_i32_e32 v131, 31, v130
	s_cselect_b32 s14, 32, s16
	v_lshlrev_b64 v[130:131], 20, v[130:131]
	s_mul_hi_i32 s15, s14, 0x6000
	s_mulk_i32 s14, 0x6000
	v_ashrrev_i32_e32 v157, 31, v156
	v_lshl_add_u64 v[130:131], s[6:7], 0, v[130:131]
	s_add_u32 s14, s37, s14
	v_lshl_add_u64 v[130:131], v[130:131], 0, s[18:19]
	s_addc_u32 s15, s38, s15
	v_lshlrev_b64 v[208:209], 2, v[156:157]
	v_lshl_add_u64 v[162:163], v[130:131], 0, v[148:149]
	v_lshl_add_u64 v[130:131], s[14:15], 0, v[208:209]
	v_lshl_add_u64 v[156:157], v[156:157], 1, v[158:159]
	global_load_dwordx4 v[142:145], v[130:131], off
	global_load_dwordx4 v[138:141], v[130:131], off offset:64
	global_load_dwordx4 v[134:137], v[130:131], off offset:512
	s_nop 0
	global_load_dwordx4 v[130:133], v[130:131], off offset:576
	s_nop 0
	s_mov_b32 s14, 0x40000
	s_nop 0
	v_lshl_add_u64 v[162:163], v[162:163], 0, v[208:209]
	s_nop 0
	s_mov_b32 s15, s42
	s_nop 0
	s_mov_b32 s14, 0x48000
	s_nop 0
	s_mov_b32 s14, 0x50000
	s_nop 0
	s_mov_b32 s14, 0x58000
	s_nop 0
	s_mov_b32 s14, 0x20000
	s_nop 0
	s_nop 0
	s_mov_b64 s[18:19], s[12:13]
	s_mov_b64 s[16:17], s[10:11]
	v_and_b32_e32 v202, 16, v224
	v_lshrrev_b32_e32 v203, 1, v202
	v_add_u32_e32 v202, v202, v203
	v_mov_b32_e32 v203, 0
	v_mov_b32_e32 v223, 0
	v_lshl_add_u64 v[246:247], v[156:157], 0, v[202:203]
	v_mov_b32_e32 v222, 0x0
	v_lshl_add_u64 v[190:191], v[246:247], 0, v[222:223]
	global_load_dwordx4 v[198:201], v[190:191], off
	global_load_dwordx4 v[218:221], v[190:191], off offset:256
	v_mov_b32_e32 v222, 0x8000
	v_lshl_add_u64 v[190:191], v[246:247], 0, v[222:223]
	global_load_dwordx4 v[242:245], v[190:191], off
	global_load_dwordx4 v[164:167], v[190:191], off offset:256
	v_mov_b32_e32 v222, 0x10000
	v_lshl_add_u64 v[190:191], v[246:247], 0, v[222:223]
	global_load_dwordx4 v[168:171], v[190:191], off
	global_load_dwordx4 v[172:175], v[190:191], off offset:256
	v_mov_b32_e32 v222, 0x18000
	v_lshl_add_u64 v[190:191], v[246:247], 0, v[222:223]
	global_load_dwordx4 v[176:179], v[190:191], off
	global_load_dwordx4 v[180:183], v[190:191], off offset:256
	v_mov_b32_e32 v222, 0x40000
	v_lshl_add_u64 v[190:191], v[246:247], 0, v[222:223]
	global_load_dwordx4 v[184:187], v[190:191], off
	s_waitcnt vmcnt(8)
	v_permlane16_swap_b32 v198, v200
	v_permlane16_swap_b32 v199, v201
	s_nop 1
	v_lshlrev_b32_e32 v210, 16, v198
	v_and_b32_e32 v211, 0xffff0000, v198
	v_lshlrev_b32_e32 v212, 16, v199
	v_and_b32_e32 v213, 0xffff0000, v199
	v_pk_fma_f32 v[126:127], v[126:127], v[142:143], v[210:211]
	v_pk_fma_f32 v[128:129], v[128:129], v[144:145], v[212:213]
	v_lshlrev_b32_e32 v214, 16, v200
	v_and_b32_e32 v215, 0xffff0000, v200
	v_lshlrev_b32_e32 v216, 16, v201
	v_and_b32_e32 v217, 0xffff0000, v201
	v_pk_fma_f32 v[122:123], v[122:123], v[138:139], v[214:215]
	v_pk_fma_f32 v[124:125], v[124:125], v[140:141], v[216:217]
	v_mov_b32_e32 v222, 0x0
	v_lshl_add_u64 v[192:193], v[162:163], 0, v[222:223]
	global_store_dwordx4 v[192:193], v[126:129], off
	global_store_dwordx4 v[192:193], v[122:125], off offset:64
	global_load_dwordx4 v[198:201], v[190:191], off offset:256
	s_waitcnt vmcnt(10)
	v_permlane16_swap_b32 v218, v220
	v_permlane16_swap_b32 v219, v221
	s_nop 1
	v_lshlrev_b32_e32 v210, 16, v218
	v_and_b32_e32 v211, 0xffff0000, v218
	v_lshlrev_b32_e32 v212, 16, v219
	v_and_b32_e32 v213, 0xffff0000, v219
	v_pk_fma_f32 v[118:119], v[118:119], v[134:135], v[210:211]
	v_pk_fma_f32 v[120:121], v[120:121], v[136:137], v[212:213]
	v_lshlrev_b32_e32 v214, 16, v220
	v_and_b32_e32 v215, 0xffff0000, v220
	v_lshlrev_b32_e32 v216, 16, v221
	v_and_b32_e32 v217, 0xffff0000, v221
	v_pk_fma_f32 v[110:111], v[110:111], v[130:131], v[214:215]
	v_pk_fma_f32 v[112:113], v[112:113], v[132:133], v[216:217]
	v_mov_b32_e32 v222, 0x0
	v_lshl_add_u64 v[192:193], v[162:163], 0, v[222:223]
	global_store_dwordx4 v[192:193], v[118:121], off offset:512
	global_store_dwordx4 v[192:193], v[110:113], off offset:576
	v_mov_b32_e32 v222, 0x48000
	v_lshl_add_u64 v[190:191], v[246:247], 0, v[222:223]
	global_load_dwordx4 v[218:221], v[190:191], off
	s_waitcnt vmcnt(12)
	v_permlane16_swap_b32 v242, v244
	v_permlane16_swap_b32 v243, v245
	s_nop 1
	v_lshlrev_b32_e32 v210, 16, v242
	v_and_b32_e32 v211, 0xffff0000, v242
	v_lshlrev_b32_e32 v212, 16, v243
	v_and_b32_e32 v213, 0xffff0000, v243
	v_pk_fma_f32 v[114:115], v[114:115], v[142:143], v[210:211]
	v_pk_fma_f32 v[116:117], v[116:117], v[144:145], v[212:213]
	v_lshlrev_b32_e32 v214, 16, v244
	v_and_b32_e32 v215, 0xffff0000, v244
	v_lshlrev_b32_e32 v216, 16, v245
	v_and_b32_e32 v217, 0xffff0000, v245
	v_pk_fma_f32 v[106:107], v[106:107], v[138:139], v[214:215]
	v_pk_fma_f32 v[108:109], v[108:109], v[140:141], v[216:217]
	v_mov_b32_e32 v222, 0x10000
	v_lshl_add_u64 v[192:193], v[162:163], 0, v[222:223]
	global_store_dwordx4 v[192:193], v[114:117], off
	global_store_dwordx4 v[192:193], v[106:109], off offset:64
	global_load_dwordx4 v[242:245], v[190:191], off offset:256
	s_waitcnt vmcnt(14)
	v_permlane16_swap_b32 v164, v166
	v_permlane16_swap_b32 v165, v167
	s_nop 1
	v_lshlrev_b32_e32 v210, 16, v164
	v_and_b32_e32 v211, 0xffff0000, v164
	v_lshlrev_b32_e32 v212, 16, v165
	v_and_b32_e32 v213, 0xffff0000, v165
	v_pk_fma_f32 v[102:103], v[102:103], v[134:135], v[210:211]
	v_pk_fma_f32 v[104:105], v[104:105], v[136:137], v[212:213]
	v_lshlrev_b32_e32 v214, 16, v166
	v_and_b32_e32 v215, 0xffff0000, v166
	v_lshlrev_b32_e32 v216, 16, v167
	v_and_b32_e32 v217, 0xffff0000, v167
	v_pk_fma_f32 v[94:95], v[94:95], v[130:131], v[214:215]
	v_pk_fma_f32 v[96:97], v[96:97], v[132:133], v[216:217]
	v_mov_b32_e32 v222, 0x10000
	v_lshl_add_u64 v[192:193], v[162:163], 0, v[222:223]
	global_store_dwordx4 v[192:193], v[102:105], off offset:512
	global_store_dwordx4 v[192:193], v[94:97], off offset:576
	v_mov_b32_e32 v222, 0x50000
	v_lshl_add_u64 v[190:191], v[246:247], 0, v[222:223]
	global_load_dwordx4 v[164:167], v[190:191], off
	s_waitcnt vmcnt(16)
	v_permlane16_swap_b32 v168, v170
	v_permlane16_swap_b32 v169, v171
	s_nop 1
	v_lshlrev_b32_e32 v210, 16, v168
	v_and_b32_e32 v211, 0xffff0000, v168
	v_lshlrev_b32_e32 v212, 16, v169
	v_and_b32_e32 v213, 0xffff0000, v169
	v_pk_fma_f32 v[98:99], v[98:99], v[142:143], v[210:211]
	v_pk_fma_f32 v[100:101], v[100:101], v[144:145], v[212:213]
	v_lshlrev_b32_e32 v214, 16, v170
	v_and_b32_e32 v215, 0xffff0000, v170
	v_lshlrev_b32_e32 v216, 16, v171
	v_and_b32_e32 v217, 0xffff0000, v171
	v_pk_fma_f32 v[90:91], v[90:91], v[138:139], v[214:215]
	v_pk_fma_f32 v[92:93], v[92:93], v[140:141], v[216:217]
	v_mov_b32_e32 v222, 0x20000
	v_lshl_add_u64 v[192:193], v[162:163], 0, v[222:223]
	global_store_dwordx4 v[192:193], v[98:101], off
	global_store_dwordx4 v[192:193], v[90:93], off offset:64
	global_load_dwordx4 v[168:171], v[190:191], off offset:256
	s_waitcnt vmcnt(18)
	v_permlane16_swap_b32 v172, v174
	v_permlane16_swap_b32 v173, v175
	s_nop 1
	v_lshlrev_b32_e32 v210, 16, v172
	v_and_b32_e32 v211, 0xffff0000, v172
	v_lshlrev_b32_e32 v212, 16, v173
	v_and_b32_e32 v213, 0xffff0000, v173
	v_pk_fma_f32 v[86:87], v[86:87], v[134:135], v[210:211]
	v_pk_fma_f32 v[88:89], v[88:89], v[136:137], v[212:213]
	v_lshlrev_b32_e32 v214, 16, v174
	v_and_b32_e32 v215, 0xffff0000, v174
	v_lshlrev_b32_e32 v216, 16, v175
	v_and_b32_e32 v217, 0xffff0000, v175
	v_pk_fma_f32 v[78:79], v[78:79], v[130:131], v[214:215]
	v_pk_fma_f32 v[80:81], v[80:81], v[132:133], v[216:217]
	v_mov_b32_e32 v222, 0x20000
	v_lshl_add_u64 v[192:193], v[162:163], 0, v[222:223]
	global_store_dwordx4 v[192:193], v[86:89], off offset:512
	global_store_dwordx4 v[192:193], v[78:81], off offset:576
	v_mov_b32_e32 v222, 0x58000
	v_lshl_add_u64 v[190:191], v[246:247], 0, v[222:223]
	global_load_dwordx4 v[172:175], v[190:191], off
	s_waitcnt vmcnt(20)
	v_permlane16_swap_b32 v176, v178
	v_permlane16_swap_b32 v177, v179
	s_nop 1
	v_lshlrev_b32_e32 v210, 16, v176
	v_and_b32_e32 v211, 0xffff0000, v176
	v_lshlrev_b32_e32 v212, 16, v177
	v_and_b32_e32 v213, 0xffff0000, v177
	v_pk_fma_f32 v[82:83], v[82:83], v[142:143], v[210:211]
	v_pk_fma_f32 v[84:85], v[84:85], v[144:145], v[212:213]
	v_lshlrev_b32_e32 v214, 16, v178
	v_and_b32_e32 v215, 0xffff0000, v178
	v_lshlrev_b32_e32 v216, 16, v179
	v_and_b32_e32 v217, 0xffff0000, v179
	v_pk_fma_f32 v[74:75], v[74:75], v[138:139], v[214:215]
	v_pk_fma_f32 v[76:77], v[76:77], v[140:141], v[216:217]
	v_mov_b32_e32 v222, 0x30000
	v_lshl_add_u64 v[192:193], v[162:163], 0, v[222:223]
	global_store_dwordx4 v[192:193], v[82:85], off
	global_store_dwordx4 v[192:193], v[74:77], off offset:64
	global_load_dwordx4 v[176:179], v[190:191], off offset:256
	s_waitcnt vmcnt(22)
	v_permlane16_swap_b32 v180, v182
	v_permlane16_swap_b32 v181, v183
	s_nop 1
	v_lshlrev_b32_e32 v210, 16, v180
	v_and_b32_e32 v211, 0xffff0000, v180
	v_lshlrev_b32_e32 v212, 16, v181
	v_and_b32_e32 v213, 0xffff0000, v181
	v_pk_fma_f32 v[70:71], v[70:71], v[134:135], v[210:211]
	v_pk_fma_f32 v[72:73], v[72:73], v[136:137], v[212:213]
	v_lshlrev_b32_e32 v214, 16, v182
	v_and_b32_e32 v215, 0xffff0000, v182
	v_lshlrev_b32_e32 v216, 16, v183
	v_and_b32_e32 v217, 0xffff0000, v183
	v_pk_fma_f32 v[66:67], v[66:67], v[130:131], v[214:215]
	v_pk_fma_f32 v[68:69], v[68:69], v[132:133], v[216:217]
	v_mov_b32_e32 v222, 0x30000
	v_lshl_add_u64 v[192:193], v[162:163], 0, v[222:223]
	global_store_dwordx4 v[192:193], v[70:73], off offset:512
	global_store_dwordx4 v[192:193], v[66:69], off offset:576
	s_waitcnt vmcnt(23)
	v_permlane16_swap_b32 v184, v186
	v_permlane16_swap_b32 v185, v187
	s_nop 1
	v_lshlrev_b32_e32 v210, 16, v184
	v_and_b32_e32 v211, 0xffff0000, v184
	v_lshlrev_b32_e32 v212, 16, v185
	v_and_b32_e32 v213, 0xffff0000, v185
	v_pk_fma_f32 v[62:63], v[62:63], v[142:143], v[210:211]
	v_pk_fma_f32 v[64:65], v[64:65], v[144:145], v[212:213]
	v_lshlrev_b32_e32 v214, 16, v186
	v_and_b32_e32 v215, 0xffff0000, v186
	v_lshlrev_b32_e32 v216, 16, v187
	v_and_b32_e32 v217, 0xffff0000, v187
	v_pk_fma_f32 v[58:59], v[58:59], v[138:139], v[214:215]
	v_pk_fma_f32 v[60:61], v[60:61], v[140:141], v[216:217]
	v_mov_b32_e32 v222, 0x80000
	v_lshl_add_u64 v[192:193], v[162:163], 0, v[222:223]
	global_store_dwordx4 v[192:193], v[62:65], off
	global_store_dwordx4 v[192:193], v[58:61], off offset:64
	s_waitcnt vmcnt(22)
	v_permlane16_swap_b32 v198, v200
	v_permlane16_swap_b32 v199, v201
	s_nop 1
	v_lshlrev_b32_e32 v210, 16, v198
	v_and_b32_e32 v211, 0xffff0000, v198
	v_lshlrev_b32_e32 v212, 16, v199
	v_and_b32_e32 v213, 0xffff0000, v199
	v_pk_fma_f32 v[54:55], v[54:55], v[134:135], v[210:211]
	v_pk_fma_f32 v[56:57], v[56:57], v[136:137], v[212:213]
	v_lshlrev_b32_e32 v214, 16, v200
	v_and_b32_e32 v215, 0xffff0000, v200
	v_lshlrev_b32_e32 v216, 16, v201
	v_and_b32_e32 v217, 0xffff0000, v201
	v_pk_fma_f32 v[44:45], v[44:45], v[130:131], v[214:215]
	v_pk_fma_f32 v[46:47], v[46:47], v[132:133], v[216:217]
	v_mov_b32_e32 v222, 0x80000
	v_lshl_add_u64 v[192:193], v[162:163], 0, v[222:223]
	global_store_dwordx4 v[192:193], v[54:57], off offset:512
	global_store_dwordx4 v[192:193], v[44:47], off offset:576
	s_waitcnt vmcnt(21)
	v_permlane16_swap_b32 v218, v220
	v_permlane16_swap_b32 v219, v221
	s_nop 1
	v_lshlrev_b32_e32 v210, 16, v218
	v_and_b32_e32 v211, 0xffff0000, v218
	v_lshlrev_b32_e32 v212, 16, v219
	v_and_b32_e32 v213, 0xffff0000, v219
	v_pk_fma_f32 v[50:51], v[50:51], v[142:143], v[210:211]
	v_pk_fma_f32 v[52:53], v[52:53], v[144:145], v[212:213]
	v_lshlrev_b32_e32 v214, 16, v220
	v_and_b32_e32 v215, 0xffff0000, v220
	v_lshlrev_b32_e32 v216, 16, v221
	v_and_b32_e32 v217, 0xffff0000, v221
	v_pk_fma_f32 v[40:41], v[40:41], v[138:139], v[214:215]
	v_pk_fma_f32 v[42:43], v[42:43], v[140:141], v[216:217]
	v_mov_b32_e32 v222, 0x90000
	v_lshl_add_u64 v[192:193], v[162:163], 0, v[222:223]
	global_store_dwordx4 v[192:193], v[50:53], off
	global_store_dwordx4 v[192:193], v[40:43], off offset:64
	s_waitcnt vmcnt(20)
	v_permlane16_swap_b32 v242, v244
	v_permlane16_swap_b32 v243, v245
	s_nop 1
	v_lshlrev_b32_e32 v210, 16, v242
	v_and_b32_e32 v211, 0xffff0000, v242
	v_lshlrev_b32_e32 v212, 16, v243
	v_and_b32_e32 v213, 0xffff0000, v243
	v_pk_fma_f32 v[36:37], v[36:37], v[134:135], v[210:211]
	v_pk_fma_f32 v[38:39], v[38:39], v[136:137], v[212:213]
	v_lshlrev_b32_e32 v214, 16, v244
	v_and_b32_e32 v215, 0xffff0000, v244
	v_lshlrev_b32_e32 v216, 16, v245
	v_and_b32_e32 v217, 0xffff0000, v245
	v_pk_fma_f32 v[28:29], v[28:29], v[130:131], v[214:215]
	v_pk_fma_f32 v[30:31], v[30:31], v[132:133], v[216:217]
	v_mov_b32_e32 v222, 0x90000
	v_lshl_add_u64 v[192:193], v[162:163], 0, v[222:223]
	global_store_dwordx4 v[192:193], v[36:39], off offset:512
	global_store_dwordx4 v[192:193], v[28:31], off offset:576
	s_waitcnt vmcnt(19)
	v_permlane16_swap_b32 v164, v166
	v_permlane16_swap_b32 v165, v167
	s_nop 1
	v_lshlrev_b32_e32 v210, 16, v164
	v_and_b32_e32 v211, 0xffff0000, v164
	v_lshlrev_b32_e32 v212, 16, v165
	v_and_b32_e32 v213, 0xffff0000, v165
	v_pk_fma_f32 v[32:33], v[32:33], v[142:143], v[210:211]
	v_pk_fma_f32 v[34:35], v[34:35], v[144:145], v[212:213]
	v_lshlrev_b32_e32 v214, 16, v166
	v_and_b32_e32 v215, 0xffff0000, v166
	v_lshlrev_b32_e32 v216, 16, v167
	v_and_b32_e32 v217, 0xffff0000, v167
	v_pk_fma_f32 v[24:25], v[24:25], v[138:139], v[214:215]
	v_pk_fma_f32 v[26:27], v[26:27], v[140:141], v[216:217]
	v_mov_b32_e32 v222, 0xa0000
	v_lshl_add_u64 v[192:193], v[162:163], 0, v[222:223]
	global_store_dwordx4 v[192:193], v[32:35], off
	global_store_dwordx4 v[192:193], v[24:27], off offset:64
	s_waitcnt vmcnt(18)
	v_permlane16_swap_b32 v168, v170
	v_permlane16_swap_b32 v169, v171
	s_nop 1
	v_lshlrev_b32_e32 v210, 16, v168
	v_and_b32_e32 v211, 0xffff0000, v168
	v_lshlrev_b32_e32 v212, 16, v169
	v_and_b32_e32 v213, 0xffff0000, v169
	v_pk_fma_f32 v[20:21], v[20:21], v[134:135], v[210:211]
	v_pk_fma_f32 v[22:23], v[22:23], v[136:137], v[212:213]
	v_lshlrev_b32_e32 v214, 16, v170
	v_and_b32_e32 v215, 0xffff0000, v170
	v_lshlrev_b32_e32 v216, 16, v171
	v_and_b32_e32 v217, 0xffff0000, v171
	v_pk_fma_f32 v[12:13], v[12:13], v[130:131], v[214:215]
	v_pk_fma_f32 v[14:15], v[14:15], v[132:133], v[216:217]
	v_mov_b32_e32 v222, 0xa0000
	v_lshl_add_u64 v[192:193], v[162:163], 0, v[222:223]
	global_store_dwordx4 v[192:193], v[20:23], off offset:512
	global_store_dwordx4 v[192:193], v[12:15], off offset:576
	s_waitcnt vmcnt(17)
	v_permlane16_swap_b32 v172, v174
	v_permlane16_swap_b32 v173, v175
	s_nop 1
	v_lshlrev_b32_e32 v210, 16, v172
	v_and_b32_e32 v211, 0xffff0000, v172
	v_lshlrev_b32_e32 v212, 16, v173
	v_and_b32_e32 v213, 0xffff0000, v173
	v_pk_fma_f32 v[16:17], v[16:17], v[142:143], v[210:211]
	v_pk_fma_f32 v[18:19], v[18:19], v[144:145], v[212:213]
	v_lshlrev_b32_e32 v214, 16, v174
	v_and_b32_e32 v215, 0xffff0000, v174
	v_lshlrev_b32_e32 v216, 16, v175
	v_and_b32_e32 v217, 0xffff0000, v175
	v_pk_fma_f32 v[8:9], v[8:9], v[138:139], v[214:215]
	v_pk_fma_f32 v[10:11], v[10:11], v[140:141], v[216:217]
	v_mov_b32_e32 v222, 0xb0000
	v_lshl_add_u64 v[192:193], v[162:163], 0, v[222:223]
	global_store_dwordx4 v[192:193], v[16:19], off
	global_store_dwordx4 v[192:193], v[8:11], off offset:64
	s_waitcnt vmcnt(16)
	v_permlane16_swap_b32 v176, v178
	v_permlane16_swap_b32 v177, v179
	s_nop 1
	v_lshlrev_b32_e32 v210, 16, v176
	v_and_b32_e32 v211, 0xffff0000, v176
	v_lshlrev_b32_e32 v212, 16, v177
	v_and_b32_e32 v213, 0xffff0000, v177
	v_pk_fma_f32 v[4:5], v[4:5], v[134:135], v[210:211]
	v_pk_fma_f32 v[6:7], v[6:7], v[136:137], v[212:213]
	v_lshlrev_b32_e32 v214, 16, v178
	v_and_b32_e32 v215, 0xffff0000, v178
	v_lshlrev_b32_e32 v216, 16, v179
	v_and_b32_e32 v217, 0xffff0000, v179
	v_pk_fma_f32 v[0:1], v[0:1], v[130:131], v[214:215]
	v_pk_fma_f32 v[2:3], v[2:3], v[132:133], v[216:217]
	v_mov_b32_e32 v222, 0xb0000
	v_lshl_add_u64 v[192:193], v[162:163], 0, v[222:223]
	global_store_dwordx4 v[192:193], v[4:7], off offset:512
	global_store_dwordx4 v[192:193], v[0:3], off offset:576
	s_mov_b32 s14, 0x30000
	s_mov_b32 s14, 0x80000
	s_mov_b32 s14, 0x90000
	s_mov_b32 s14, 0xa0000
	s_mov_b32 s14, 0xb0000
	s_and_b64 vcc, exec, s[0:1]
	s_mov_b32 s14, s43
	s_cbranch_vccz .LBB0_1418
	s_waitcnt vmcnt(0)
	s_cmpk_gt_u32 s24, 0xff
	s_cbranch_scc1 .LBB0_1425
	s_barrier

.LBB0_1435:
	s_add_u32 s20, s18, 0x100
	s_addc_u32 s21, s19, 0
	s_add_i32 s47, 0, 0x10000
	v_add_u32_e32 v142, s47, v242
	ds_read_b128 v[130:133], v142
	ds_read_b128 v[134:137], v142 offset:1024
	ds_read_b128 v[138:141], v142 offset:2048
	ds_read_b128 v[142:145], v142 offset:3072
	s_cmp_eq_u32 s46, 40
	s_cselect_b32 s25, s13, s21
	s_cselect_b32 s24, s12, s20
	s_cselect_b32 s23, s15, s45
	s_cselect_b32 s22, s14, s44
	v_lshl_add_u64 v[186:187], s[18:19], 0, v[150:151]
	s_add_i32 m0, s31, 0xc000
	ds_read_b128 v[154:157], v244
	ds_read_b128 v[158:161], v244 offset:1024
	ds_read_b128 v[162:165], v244 offset:2048
	ds_read_b128 v[166:169], v244 offset:3072
	ds_read_b128 v[170:173], v244 offset:4096
	ds_read_b128 v[174:177], v244 offset:5120
	ds_read_b128 v[178:181], v244 offset:6144
	ds_read_b128 v[182:185], v244 offset:7168
	global_load_lds_dwordx4 v[186:187], off
	v_lshl_add_u64 v[186:187], s[18:19], 0, v[152:153]
	s_add_i32 m0, s31, 0xe000
	s_nop 0
	global_load_lds_dwordx4 v[186:187], off
	s_waitcnt lgkmcnt(8)
	s_barrier
	s_waitcnt lgkmcnt(0)
	s_setprio 1
	s_waitcnt lgkmcnt(0)
	v_mfma_f32_16x16x32_bf16 v[126:129], v[130:133], v[154:157], v[126:129]
	v_mfma_f32_16x16x32_bf16 v[122:125], v[138:141], v[154:157], v[122:125]
	v_mfma_f32_16x16x32_bf16 v[114:117], v[130:133], v[162:165], v[114:117]
	v_mfma_f32_16x16x32_bf16 v[106:109], v[138:141], v[162:165], v[106:109]
	v_mfma_f32_16x16x32_bf16 v[98:101], v[130:133], v[170:173], v[98:101]
	v_mfma_f32_16x16x32_bf16 v[90:93], v[138:141], v[170:173], v[90:93]
	v_mfma_f32_16x16x32_bf16 v[82:85], v[130:133], v[178:181], v[82:85]
	v_mfma_f32_16x16x32_bf16 v[74:77], v[138:141], v[178:181], v[74:77]
	v_mfma_f32_16x16x32_bf16 v[126:129], v[134:137], v[158:161], v[126:129]
	v_mfma_f32_16x16x32_bf16 v[122:125], v[142:145], v[158:161], v[122:125]
	v_mfma_f32_16x16x32_bf16 v[114:117], v[134:137], v[166:169], v[114:117]
	v_mfma_f32_16x16x32_bf16 v[106:109], v[142:145], v[166:169], v[106:109]
	v_mfma_f32_16x16x32_bf16 v[98:101], v[134:137], v[174:177], v[98:101]
	v_mfma_f32_16x16x32_bf16 v[90:93], v[142:145], v[174:177], v[90:93]
	v_mfma_f32_16x16x32_bf16 v[82:85], v[134:137], v[182:185], v[82:85]
	v_mfma_f32_16x16x32_bf16 v[74:77], v[142:145], v[182:185], v[74:77]
	s_setprio 0
	s_barrier
	s_add_i32 s48, 0, 0x14000
	s_add_i32 s18, s47, s30
	v_add_u32_e32 v202, s48, v242
	s_mov_b32 m0, s18
	ds_read_b128 v[186:189], v202
	ds_read_b128 v[190:193], v202 offset:1024
	ds_read_b128 v[198:201], v202 offset:2048
	ds_read_b128 v[202:205], v202 offset:3072
	global_load_lds_dwordx4 v48, s[22:23]
	v_lshl_add_u64 v[208:209], s[22:23], 0, v[146:147]
	s_add_i32 m0, s18, 0x2000
	s_nop 0
	global_load_lds_dwordx4 v[208:209], off
	s_barrier
	s_waitcnt lgkmcnt(0)
	s_setprio 1
	s_waitcnt lgkmcnt(0)
	v_mfma_f32_16x16x32_bf16 v[118:121], v[186:189], v[154:157], v[118:121]
	v_mfma_f32_16x16x32_bf16 v[110:113], v[198:201], v[154:157], v[110:113]
	v_mfma_f32_16x16x32_bf16 v[102:105], v[186:189], v[162:165], v[102:105]
	v_mfma_f32_16x16x32_bf16 v[94:97], v[198:201], v[162:165], v[94:97]
	v_mfma_f32_16x16x32_bf16 v[86:89], v[186:189], v[170:173], v[86:89]
	v_mfma_f32_16x16x32_bf16 v[78:81], v[198:201], v[170:173], v[78:81]
	v_mfma_f32_16x16x32_bf16 v[70:73], v[186:189], v[178:181], v[70:73]
	v_mfma_f32_16x16x32_bf16 v[66:69], v[198:201], v[178:181], v[66:69]
	v_mfma_f32_16x16x32_bf16 v[118:121], v[190:193], v[158:161], v[118:121]
	v_mfma_f32_16x16x32_bf16 v[110:113], v[202:205], v[158:161], v[110:113]
	v_mfma_f32_16x16x32_bf16 v[102:105], v[190:193], v[166:169], v[102:105]
	v_mfma_f32_16x16x32_bf16 v[94:97], v[202:205], v[166:169], v[94:97]
	v_mfma_f32_16x16x32_bf16 v[86:89], v[190:193], v[174:177], v[86:89]
	v_mfma_f32_16x16x32_bf16 v[78:81], v[202:205], v[174:177], v[78:81]
	v_mfma_f32_16x16x32_bf16 v[70:73], v[190:193], v[182:185], v[70:73]
	v_mfma_f32_16x16x32_bf16 v[66:69], v[202:205], v[182:185], v[66:69]
	s_setprio 0
	s_mov_b32 m0, s31
	v_lshl_add_u64 v[210:211], s[24:25], 0, v[48:49]
	s_barrier
	ds_read_b128 v[154:157], v244 offset:16384
	ds_read_b128 v[158:161], v244 offset:17408
	ds_read_b128 v[162:165], v244 offset:18432
	ds_read_b128 v[166:169], v244 offset:19456
	ds_read_b128 v[170:173], v244 offset:20480
	ds_read_b128 v[174:177], v244 offset:21504
	ds_read_b128 v[178:181], v244 offset:22528
	ds_read_b128 v[182:185], v244 offset:23552
	global_load_lds_dwordx4 v[210:211], off
	v_lshl_add_u64 v[212:213], s[24:25], 0, v[146:147]
	s_mov_b32 m0, s34
	s_nop 0
	global_load_lds_dwordx4 v[212:213], off
	s_barrier
	s_waitcnt lgkmcnt(0)
	s_setprio 1
	s_waitcnt lgkmcnt(0)
	v_mfma_f32_16x16x32_bf16 v[62:65], v[130:133], v[154:157], v[62:65]
	v_mfma_f32_16x16x32_bf16 v[58:61], v[138:141], v[154:157], v[58:61]
	v_mfma_f32_16x16x32_bf16 v[50:53], v[130:133], v[162:165], v[50:53]
	v_mfma_f32_16x16x32_bf16 v[40:43], v[138:141], v[162:165], v[40:43]
	v_mfma_f32_16x16x32_bf16 v[32:35], v[130:133], v[170:173], v[32:35]
	v_mfma_f32_16x16x32_bf16 v[24:27], v[138:141], v[170:173], v[24:27]
	v_mfma_f32_16x16x32_bf16 v[16:19], v[130:133], v[178:181], v[16:19]
	v_mfma_f32_16x16x32_bf16 v[8:11], v[138:141], v[178:181], v[8:11]
	v_mfma_f32_16x16x32_bf16 v[62:65], v[134:137], v[158:161], v[62:65]
	v_mfma_f32_16x16x32_bf16 v[58:61], v[142:145], v[158:161], v[58:61]
	v_mfma_f32_16x16x32_bf16 v[50:53], v[134:137], v[166:169], v[50:53]
	v_mfma_f32_16x16x32_bf16 v[40:43], v[142:145], v[166:169], v[40:43]
	v_mfma_f32_16x16x32_bf16 v[32:35], v[134:137], v[174:177], v[32:35]
	v_mfma_f32_16x16x32_bf16 v[24:27], v[142:145], v[174:177], v[24:27]
	v_mfma_f32_16x16x32_bf16 v[16:19], v[134:137], v[182:185], v[16:19]
	v_mfma_f32_16x16x32_bf16 v[8:11], v[142:145], v[182:185], v[8:11]
	s_setprio 0
	s_barrier
	s_add_u32 s18, s22, 0xb0000
	s_addc_u32 s19, s23, 0
	s_add_i32 s47, s48, s30
	s_mov_b32 m0, s47
	s_nop 0
	global_load_lds_dwordx4 v48, s[18:19]
	s_add_i32 m0, s47, 0x2000
	s_nop 0
	global_load_lds_dwordx4 v146, s[18:19]
	s_waitcnt vmcnt(6)
	s_barrier
	s_setprio 1
	v_mfma_f32_16x16x32_bf16 v[54:57], v[186:189], v[154:157], v[54:57]
	v_mfma_f32_16x16x32_bf16 v[44:47], v[198:201], v[154:157], v[44:47]
	v_mfma_f32_16x16x32_bf16 v[36:39], v[186:189], v[162:165], v[36:39]
	v_mfma_f32_16x16x32_bf16 v[28:31], v[198:201], v[162:165], v[28:31]
	v_mfma_f32_16x16x32_bf16 v[20:23], v[186:189], v[170:173], v[20:23]
	v_mfma_f32_16x16x32_bf16 v[12:15], v[198:201], v[170:173], v[12:15]
	v_mfma_f32_16x16x32_bf16 v[4:7], v[186:189], v[178:181], v[4:7]
	v_mfma_f32_16x16x32_bf16 v[0:3], v[198:201], v[178:181], v[0:3]
	v_mfma_f32_16x16x32_bf16 v[54:57], v[190:193], v[158:161], v[54:57]
	v_mfma_f32_16x16x32_bf16 v[44:47], v[202:205], v[158:161], v[44:47]
	v_mfma_f32_16x16x32_bf16 v[36:39], v[190:193], v[166:169], v[36:39]
	v_mfma_f32_16x16x32_bf16 v[28:31], v[202:205], v[166:169], v[28:31]
	v_mfma_f32_16x16x32_bf16 v[20:23], v[190:193], v[174:177], v[20:23]
	v_mfma_f32_16x16x32_bf16 v[12:15], v[202:205], v[174:177], v[12:15]
	v_mfma_f32_16x16x32_bf16 v[4:7], v[190:193], v[182:185], v[4:7]
	v_mfma_f32_16x16x32_bf16 v[0:3], v[202:205], v[182:185], v[0:3]
	s_setprio 0
	s_add_i32 s47, 0, 0x18000
	v_add_u32_e32 v142, s47, v242
	s_barrier
	ds_read_b128 v[130:133], v142
	ds_read_b128 v[134:137], v142 offset:1024
	ds_read_b128 v[138:141], v142 offset:2048
	ds_read_b128 v[142:145], v142 offset:3072
	s_add_u32 s18, s24, 0xb0000
	s_addc_u32 s19, s25, 0
	s_mov_b32 m0, s35
	ds_read_b128 v[154:157], v244 offset:32768
	ds_read_b128 v[158:161], v244 offset:33792
	ds_read_b128 v[162:165], v244 offset:34816
	ds_read_b128 v[166:169], v244 offset:35840
	ds_read_b128 v[170:173], v244 offset:36864
	ds_read_b128 v[174:177], v244 offset:37888
	ds_read_b128 v[178:181], v244 offset:38912
	ds_read_b128 v[182:185], v244 offset:39936
	global_load_lds_dwordx4 v48, s[18:19]
	s_mov_b32 m0, s36
	s_nop 0
	global_load_lds_dwordx4 v146, s[18:19]
	s_waitcnt lgkmcnt(8)
	s_barrier
	s_waitcnt lgkmcnt(0)
	s_setprio 1
	s_waitcnt lgkmcnt(0)
	v_mfma_f32_16x16x32_bf16 v[126:129], v[130:133], v[154:157], v[126:129]
	v_mfma_f32_16x16x32_bf16 v[122:125], v[138:141], v[154:157], v[122:125]
	v_mfma_f32_16x16x32_bf16 v[114:117], v[130:133], v[162:165], v[114:117]
	v_mfma_f32_16x16x32_bf16 v[106:109], v[138:141], v[162:165], v[106:109]
	v_mfma_f32_16x16x32_bf16 v[98:101], v[130:133], v[170:173], v[98:101]
	v_mfma_f32_16x16x32_bf16 v[90:93], v[138:141], v[170:173], v[90:93]
	v_mfma_f32_16x16x32_bf16 v[82:85], v[130:133], v[178:181], v[82:85]
	v_mfma_f32_16x16x32_bf16 v[74:77], v[138:141], v[178:181], v[74:77]
	v_mfma_f32_16x16x32_bf16 v[126:129], v[134:137], v[158:161], v[126:129]
	v_mfma_f32_16x16x32_bf16 v[122:125], v[142:145], v[158:161], v[122:125]
	v_mfma_f32_16x16x32_bf16 v[114:117], v[134:137], v[166:169], v[114:117]
	v_mfma_f32_16x16x32_bf16 v[106:109], v[142:145], v[166:169], v[106:109]
	v_mfma_f32_16x16x32_bf16 v[98:101], v[134:137], v[174:177], v[98:101]
	v_mfma_f32_16x16x32_bf16 v[90:93], v[142:145], v[174:177], v[90:93]
	v_mfma_f32_16x16x32_bf16 v[82:85], v[134:137], v[182:185], v[82:85]
	v_mfma_f32_16x16x32_bf16 v[74:77], v[142:145], v[182:185], v[74:77]
	s_setprio 0
	s_barrier
	s_add_i32 s24, 0, 0x1c000
	s_add_i32 s18, s47, s30
	v_add_u32_e32 v202, s24, v242
	s_add_u32 s52, s22, s66
	s_addc_u32 s53, s23, s67
	s_mov_b32 m0, s18
	ds_read_b128 v[186:189], v202
	ds_read_b128 v[190:193], v202 offset:1024
	ds_read_b128 v[198:201], v202 offset:2048
	ds_read_b128 v[202:205], v202 offset:3072
	global_load_lds_dwordx4 v48, s[52:53]
	s_add_u32 s52, s22, s66
	s_addc_u32 s53, s23, s67
	s_add_i32 m0, s18, 0x2000
	s_nop 0
	global_load_lds_dwordx4 v146, s[52:53]
	s_barrier
	s_waitcnt lgkmcnt(0)
	s_setprio 1
	s_waitcnt lgkmcnt(0)
	v_mfma_f32_16x16x32_bf16 v[118:121], v[186:189], v[154:157], v[118:121]
	v_mfma_f32_16x16x32_bf16 v[110:113], v[198:201], v[154:157], v[110:113]
	v_mfma_f32_16x16x32_bf16 v[102:105], v[186:189], v[162:165], v[102:105]
	v_mfma_f32_16x16x32_bf16 v[94:97], v[198:201], v[162:165], v[94:97]
	v_mfma_f32_16x16x32_bf16 v[86:89], v[186:189], v[170:173], v[86:89]
	v_mfma_f32_16x16x32_bf16 v[78:81], v[198:201], v[170:173], v[78:81]
	v_mfma_f32_16x16x32_bf16 v[70:73], v[186:189], v[178:181], v[70:73]
	v_mfma_f32_16x16x32_bf16 v[66:69], v[198:201], v[178:181], v[66:69]
	v_mfma_f32_16x16x32_bf16 v[118:121], v[190:193], v[158:161], v[118:121]
	v_mfma_f32_16x16x32_bf16 v[110:113], v[202:205], v[158:161], v[110:113]
	v_mfma_f32_16x16x32_bf16 v[102:105], v[190:193], v[166:169], v[102:105]
	v_mfma_f32_16x16x32_bf16 v[94:97], v[202:205], v[166:169], v[94:97]
	v_mfma_f32_16x16x32_bf16 v[86:89], v[190:193], v[174:177], v[86:89]
	v_mfma_f32_16x16x32_bf16 v[78:81], v[202:205], v[174:177], v[78:81]
	v_mfma_f32_16x16x32_bf16 v[70:73], v[190:193], v[182:185], v[70:73]
	v_mfma_f32_16x16x32_bf16 v[66:69], v[202:205], v[182:185], v[66:69]
	s_setprio 0
	s_mov_b32 m0, s39
	v_lshl_add_u64 v[206:207], v[210:211], 0, s[66:67]
	s_barrier
	ds_read_b128 v[154:157], v244 offset:49152
	ds_read_b128 v[158:161], v244 offset:50176
	ds_read_b128 v[162:165], v244 offset:51200
	ds_read_b128 v[166:169], v244 offset:52224
	ds_read_b128 v[170:173], v244 offset:53248
	ds_read_b128 v[174:177], v244 offset:54272
	ds_read_b128 v[178:181], v244 offset:55296
	ds_read_b128 v[182:185], v244 offset:56320
	global_load_lds_dwordx4 v[206:207], off
	v_lshl_add_u64 v[206:207], v[212:213], 0, s[66:67]
	s_mov_b32 m0, s40
	s_nop 0
	global_load_lds_dwordx4 v[206:207], off
	s_barrier
	s_waitcnt lgkmcnt(0)
	s_setprio 1
	s_waitcnt lgkmcnt(0)
	v_mfma_f32_16x16x32_bf16 v[62:65], v[130:133], v[154:157], v[62:65]
	v_mfma_f32_16x16x32_bf16 v[58:61], v[138:141], v[154:157], v[58:61]
	v_mfma_f32_16x16x32_bf16 v[50:53], v[130:133], v[162:165], v[50:53]
	v_mfma_f32_16x16x32_bf16 v[40:43], v[138:141], v[162:165], v[40:43]
	v_mfma_f32_16x16x32_bf16 v[32:35], v[130:133], v[170:173], v[32:35]
	v_mfma_f32_16x16x32_bf16 v[24:27], v[138:141], v[170:173], v[24:27]
	v_mfma_f32_16x16x32_bf16 v[16:19], v[130:133], v[178:181], v[16:19]
	v_mfma_f32_16x16x32_bf16 v[8:11], v[138:141], v[178:181], v[8:11]
	v_mfma_f32_16x16x32_bf16 v[62:65], v[134:137], v[158:161], v[62:65]
	v_mfma_f32_16x16x32_bf16 v[58:61], v[142:145], v[158:161], v[58:61]
	v_mfma_f32_16x16x32_bf16 v[50:53], v[134:137], v[166:169], v[50:53]
	v_mfma_f32_16x16x32_bf16 v[40:43], v[142:145], v[166:169], v[40:43]
	v_mfma_f32_16x16x32_bf16 v[32:35], v[134:137], v[174:177], v[32:35]
	v_mfma_f32_16x16x32_bf16 v[24:27], v[142:145], v[174:177], v[24:27]
	v_mfma_f32_16x16x32_bf16 v[16:19], v[134:137], v[182:185], v[16:19]
	v_mfma_f32_16x16x32_bf16 v[8:11], v[142:145], v[182:185], v[8:11]
	s_setprio 0
	s_barrier
	s_add_u32 s18, s22, 0xb0080
	s_addc_u32 s19, s23, 0
	s_add_i32 s22, s24, s30
	s_mov_b32 m0, s22
	s_nop 0
	global_load_lds_dwordx4 v48, s[18:19]
	s_add_i32 m0, s22, 0x2000
	s_nop 0
	global_load_lds_dwordx4 v146, s[18:19]
	s_waitcnt vmcnt(6)
	s_barrier
	s_setprio 1
	v_mfma_f32_16x16x32_bf16 v[54:57], v[186:189], v[154:157], v[54:57]
	v_mfma_f32_16x16x32_bf16 v[44:47], v[198:201], v[154:157], v[44:47]
	v_mfma_f32_16x16x32_bf16 v[36:39], v[186:189], v[162:165], v[36:39]
	v_mfma_f32_16x16x32_bf16 v[28:31], v[198:201], v[162:165], v[28:31]
	v_mfma_f32_16x16x32_bf16 v[20:23], v[186:189], v[170:173], v[20:23]
	v_mfma_f32_16x16x32_bf16 v[12:15], v[198:201], v[170:173], v[12:15]
	v_mfma_f32_16x16x32_bf16 v[4:7], v[186:189], v[178:181], v[4:7]
	v_mfma_f32_16x16x32_bf16 v[0:3], v[198:201], v[178:181], v[0:3]
	v_mfma_f32_16x16x32_bf16 v[54:57], v[190:193], v[158:161], v[54:57]
	v_mfma_f32_16x16x32_bf16 v[44:47], v[202:205], v[158:161], v[44:47]
	v_mfma_f32_16x16x32_bf16 v[36:39], v[190:193], v[166:169], v[36:39]
	v_mfma_f32_16x16x32_bf16 v[28:31], v[202:205], v[166:169], v[28:31]
	v_mfma_f32_16x16x32_bf16 v[20:23], v[190:193], v[174:177], v[20:23]
	v_mfma_f32_16x16x32_bf16 v[12:15], v[202:205], v[174:177], v[12:15]
	v_mfma_f32_16x16x32_bf16 v[4:7], v[190:193], v[182:185], v[4:7]
	v_mfma_f32_16x16x32_bf16 v[0:3], v[202:205], v[182:185], v[0:3]
	s_setprio 0
	s_add_i32 s46, s46, 2
	s_add_u32 s44, s44, 0x100
	s_addc_u32 s45, s45, 0
	s_cmp_gt_u32 s46, 41
	s_mov_b64 s[18:19], s[20:21]
	s_barrier
	s_cbranch_scc0 .LBB0_1435
	s_mul_hi_i32 s18, s16, 0x38e38e39
	s_lshr_b32 s19, s18, 31
	s_ashr_i32 s18, s18, 1
	s_add_i32 s18, s18, s19
	s_mul_i32 s19, s18, -9
	v_lshl_or_b32 v154, s17, 8, v243
	s_sub_i32 s17, 0, s16
	s_cmp_lg_u32 s19, s17
	s_cselect_b32 s17, s18, 32
	s_mul_hi_i32 s19, s17, 0x6000
	s_mulk_i32 s17, 0x6000
	s_add_u32 s18, s37, s17
	s_addc_u32 s19, s38, s19
	s_ashr_i32 s17, s16, 31
	s_lshl_b64 s[16:17], s[16:17], 18
	v_ashrrev_i32_e32 v155, 31, v154
	v_lshl_add_u64 v[156:157], s[16:17], 0, v[148:149]
	v_lshl_add_u64 v[130:131], v[154:155], 2, s[18:19]
	v_lshl_add_u64 v[154:155], v[156:157], 0, v[154:155]
	v_lshlrev_b64 v[184:185], 1, v[154:155]
	v_lshl_add_u64 v[154:155], s[10:11], 0, v[184:185]
	global_load_dwordx4 v[142:145], v[130:131], off
	global_load_dwordx4 v[138:141], v[130:131], off offset:64
	global_load_dwordx4 v[134:137], v[130:131], off offset:512
	s_nop 0
	global_load_dwordx4 v[130:133], v[130:131], off offset:576
	s_nop 0
	s_mov_b32 s16, 0x40000
	s_nop 0
	s_mov_b32 s17, 0x48000
	s_nop 0
	s_mov_b32 s18, 0x50000
	s_nop 0
	s_mov_b32 s19, 0x58000
	s_nop 0
	v_lshl_add_u64 v[184:185], s[6:7], 0, v[184:185]
	s_nop 0
	s_mov_b64 s[20:21], s[14:15]
	s_nop 0
	v_and_b32_e32 v210, 16, v224
	v_lshrrev_b32_e32 v211, 1, v210
	v_add_u32_e32 v210, v210, v211
	v_mov_b32_e32 v211, 0
	v_mov_b32_e32 v213, 0
	v_lshl_add_u64 v[214:215], v[154:155], 0, v[210:211]
	v_lshl_add_u64 v[216:217], v[184:185], 0, v[210:211]
	v_mov_b32_e32 v212, 0x0
	v_lshl_add_u64 v[218:219], v[214:215], 0, v[212:213]
	global_load_dwordx4 v[164:167], v[218:219], off
	global_load_dwordx4 v[168:171], v[218:219], off offset:256
	v_mov_b32_e32 v212, 0x8000
	v_lshl_add_u64 v[218:219], v[214:215], 0, v[212:213]
	global_load_dwordx4 v[172:175], v[218:219], off
	global_load_dwordx4 v[176:179], v[218:219], off offset:256
	v_mov_b32_e32 v212, 0x10000
	v_lshl_add_u64 v[218:219], v[214:215], 0, v[212:213]
	global_load_dwordx4 v[180:183], v[218:219], off
	global_load_dwordx4 v[198:201], v[218:219], off offset:256
	v_mov_b32_e32 v212, 0x18000
	v_lshl_add_u64 v[218:219], v[214:215], 0, v[212:213]
	global_load_dwordx4 v[202:205], v[218:219], off
	global_load_dwordx4 v[206:209], v[218:219], off offset:256
	s_waitcnt vmcnt(7)
	v_permlane16_swap_b32 v164, v166
	v_permlane16_swap_b32 v165, v167
	s_nop 1
	v_lshlrev_b32_e32 v186, 16, v164
	v_and_b32_e32 v187, 0xffff0000, v164
	v_lshlrev_b32_e32 v188, 16, v165
	v_and_b32_e32 v189, 0xffff0000, v165
	v_pk_fma_f32 v[126:127], v[126:127], v[142:143], v[186:187]
	v_pk_fma_f32 v[128:129], v[128:129], v[144:145], v[188:189]
	v_lshlrev_b32_e32 v190, 16, v166
	v_and_b32_e32 v191, 0xffff0000, v166
	v_lshlrev_b32_e32 v192, 16, v167
	v_and_b32_e32 v193, 0xffff0000, v167
	v_pk_fma_f32 v[122:123], v[122:123], v[138:139], v[190:191]
	v_pk_fma_f32 v[124:125], v[124:125], v[140:141], v[192:193]
	v_cvt_pk_bf16_f32 v126, v126, v127
	v_cvt_pk_bf16_f32 v127, v128, v129
	v_cvt_pk_bf16_f32 v128, v122, v123
	v_cvt_pk_bf16_f32 v129, v124, v125
	s_nop 1
	v_permlane16_swap_b32 v126, v128
	v_permlane16_swap_b32 v127, v129
	v_mov_b32_e32 v212, 0x0
	v_lshl_add_u64 v[220:221], v[216:217], 0, v[212:213]
	global_store_dwordx4 v[220:221], v[126:129], off
	v_mov_b32_e32 v212, 0x40000
	v_lshl_add_u64 v[218:219], v[214:215], 0, v[212:213]
	global_load_dwordx4 v[164:167], v[218:219], off
	s_waitcnt vmcnt(8)
	v_permlane16_swap_b32 v168, v170
	v_permlane16_swap_b32 v169, v171
	s_nop 1
	v_lshlrev_b32_e32 v186, 16, v168
	v_and_b32_e32 v187, 0xffff0000, v168
	v_lshlrev_b32_e32 v188, 16, v169
	v_and_b32_e32 v189, 0xffff0000, v169
	v_pk_fma_f32 v[118:119], v[118:119], v[134:135], v[186:187]
	v_pk_fma_f32 v[120:121], v[120:121], v[136:137], v[188:189]
	v_lshlrev_b32_e32 v190, 16, v170
	v_and_b32_e32 v191, 0xffff0000, v170
	v_lshlrev_b32_e32 v192, 16, v171
	v_and_b32_e32 v193, 0xffff0000, v171
	v_pk_fma_f32 v[110:111], v[110:111], v[130:131], v[190:191]
	v_pk_fma_f32 v[112:113], v[112:113], v[132:133], v[192:193]
	v_cvt_pk_bf16_f32 v118, v118, v119
	v_cvt_pk_bf16_f32 v119, v120, v121
	v_cvt_pk_bf16_f32 v120, v110, v111
	v_cvt_pk_bf16_f32 v121, v112, v113
	s_nop 1
	v_permlane16_swap_b32 v118, v120
	v_permlane16_swap_b32 v119, v121
	v_mov_b32_e32 v212, 0x0
	v_lshl_add_u64 v[220:221], v[216:217], 0, v[212:213]
	global_store_dwordx4 v[220:221], v[118:121], off offset:256
	global_load_dwordx4 v[168:171], v[218:219], off offset:256
	s_waitcnt vmcnt(9)
	v_permlane16_swap_b32 v172, v174
	v_permlane16_swap_b32 v173, v175
	s_nop 1
	v_lshlrev_b32_e32 v186, 16, v172
	v_and_b32_e32 v187, 0xffff0000, v172
	v_lshlrev_b32_e32 v188, 16, v173
	v_and_b32_e32 v189, 0xffff0000, v173
	v_pk_fma_f32 v[114:115], v[114:115], v[142:143], v[186:187]
	v_pk_fma_f32 v[116:117], v[116:117], v[144:145], v[188:189]
	v_lshlrev_b32_e32 v190, 16, v174
	v_and_b32_e32 v191, 0xffff0000, v174
	v_lshlrev_b32_e32 v192, 16, v175
	v_and_b32_e32 v193, 0xffff0000, v175
	v_pk_fma_f32 v[106:107], v[106:107], v[138:139], v[190:191]
	v_pk_fma_f32 v[108:109], v[108:109], v[140:141], v[192:193]
	v_cvt_pk_bf16_f32 v114, v114, v115
	v_cvt_pk_bf16_f32 v115, v116, v117
	v_cvt_pk_bf16_f32 v116, v106, v107
	v_cvt_pk_bf16_f32 v117, v108, v109
	s_nop 1
	v_permlane16_swap_b32 v114, v116
	v_permlane16_swap_b32 v115, v117
	v_mov_b32_e32 v212, 0x8000
	v_lshl_add_u64 v[220:221], v[216:217], 0, v[212:213]
	global_store_dwordx4 v[220:221], v[114:117], off
	v_mov_b32_e32 v212, 0x48000
	v_lshl_add_u64 v[218:219], v[214:215], 0, v[212:213]
	global_load_dwordx4 v[172:175], v[218:219], off
	s_waitcnt vmcnt(10)
	v_permlane16_swap_b32 v176, v178
	v_permlane16_swap_b32 v177, v179
	s_nop 1
	v_lshlrev_b32_e32 v186, 16, v176
	v_and_b32_e32 v187, 0xffff0000, v176
	v_lshlrev_b32_e32 v188, 16, v177
	v_and_b32_e32 v189, 0xffff0000, v177
	v_pk_fma_f32 v[102:103], v[102:103], v[134:135], v[186:187]
	v_pk_fma_f32 v[104:105], v[104:105], v[136:137], v[188:189]
	v_lshlrev_b32_e32 v190, 16, v178
	v_and_b32_e32 v191, 0xffff0000, v178
	v_lshlrev_b32_e32 v192, 16, v179
	v_and_b32_e32 v193, 0xffff0000, v179
	v_pk_fma_f32 v[94:95], v[94:95], v[130:131], v[190:191]
	v_pk_fma_f32 v[96:97], v[96:97], v[132:133], v[192:193]
	v_cvt_pk_bf16_f32 v102, v102, v103
	v_cvt_pk_bf16_f32 v103, v104, v105
	v_cvt_pk_bf16_f32 v104, v94, v95
	v_cvt_pk_bf16_f32 v105, v96, v97
	s_nop 1
	v_permlane16_swap_b32 v102, v104
	v_permlane16_swap_b32 v103, v105
	v_mov_b32_e32 v212, 0x8000
	v_lshl_add_u64 v[220:221], v[216:217], 0, v[212:213]
	global_store_dwordx4 v[220:221], v[102:105], off offset:256
	global_load_dwordx4 v[176:179], v[218:219], off offset:256
	s_waitcnt vmcnt(11)
	v_permlane16_swap_b32 v180, v182
	v_permlane16_swap_b32 v181, v183
	s_nop 1
	v_lshlrev_b32_e32 v186, 16, v180
	v_and_b32_e32 v187, 0xffff0000, v180
	v_lshlrev_b32_e32 v188, 16, v181
	v_and_b32_e32 v189, 0xffff0000, v181
	v_pk_fma_f32 v[98:99], v[98:99], v[142:143], v[186:187]
	v_pk_fma_f32 v[100:101], v[100:101], v[144:145], v[188:189]
	v_lshlrev_b32_e32 v190, 16, v182
	v_and_b32_e32 v191, 0xffff0000, v182
	v_lshlrev_b32_e32 v192, 16, v183
	v_and_b32_e32 v193, 0xffff0000, v183
	v_pk_fma_f32 v[90:91], v[90:91], v[138:139], v[190:191]
	v_pk_fma_f32 v[92:93], v[92:93], v[140:141], v[192:193]
	v_cvt_pk_bf16_f32 v98, v98, v99
	v_cvt_pk_bf16_f32 v99, v100, v101
	v_cvt_pk_bf16_f32 v100, v90, v91
	v_cvt_pk_bf16_f32 v101, v92, v93
	s_nop 1
	v_permlane16_swap_b32 v98, v100
	v_permlane16_swap_b32 v99, v101
	v_mov_b32_e32 v212, 0x10000
	v_lshl_add_u64 v[220:221], v[216:217], 0, v[212:213]
	global_store_dwordx4 v[220:221], v[98:101], off
	v_mov_b32_e32 v212, 0x50000
	v_lshl_add_u64 v[218:219], v[214:215], 0, v[212:213]
	global_load_dwordx4 v[180:183], v[218:219], off
	s_waitcnt vmcnt(12)
	v_permlane16_swap_b32 v198, v200
	v_permlane16_swap_b32 v199, v201
	s_nop 1
	v_lshlrev_b32_e32 v186, 16, v198
	v_and_b32_e32 v187, 0xffff0000, v198
	v_lshlrev_b32_e32 v188, 16, v199
	v_and_b32_e32 v189, 0xffff0000, v199
	v_pk_fma_f32 v[86:87], v[86:87], v[134:135], v[186:187]
	v_pk_fma_f32 v[88:89], v[88:89], v[136:137], v[188:189]
	v_lshlrev_b32_e32 v190, 16, v200
	v_and_b32_e32 v191, 0xffff0000, v200
	v_lshlrev_b32_e32 v192, 16, v201
	v_and_b32_e32 v193, 0xffff0000, v201
	v_pk_fma_f32 v[78:79], v[78:79], v[130:131], v[190:191]
	v_pk_fma_f32 v[80:81], v[80:81], v[132:133], v[192:193]
	v_cvt_pk_bf16_f32 v86, v86, v87
	v_cvt_pk_bf16_f32 v87, v88, v89
	v_cvt_pk_bf16_f32 v88, v78, v79
	v_cvt_pk_bf16_f32 v89, v80, v81
	s_nop 1
	v_permlane16_swap_b32 v86, v88
	v_permlane16_swap_b32 v87, v89
	v_mov_b32_e32 v212, 0x10000
	v_lshl_add_u64 v[220:221], v[216:217], 0, v[212:213]
	global_store_dwordx4 v[220:221], v[86:89], off offset:256
	global_load_dwordx4 v[198:201], v[218:219], off offset:256
	s_waitcnt vmcnt(13)
	v_permlane16_swap_b32 v202, v204
	v_permlane16_swap_b32 v203, v205
	s_nop 1
	v_lshlrev_b32_e32 v186, 16, v202
	v_and_b32_e32 v187, 0xffff0000, v202
	v_lshlrev_b32_e32 v188, 16, v203
	v_and_b32_e32 v189, 0xffff0000, v203
	v_pk_fma_f32 v[82:83], v[82:83], v[142:143], v[186:187]
	v_pk_fma_f32 v[84:85], v[84:85], v[144:145], v[188:189]
	v_lshlrev_b32_e32 v190, 16, v204
	v_and_b32_e32 v191, 0xffff0000, v204
	v_lshlrev_b32_e32 v192, 16, v205
	v_and_b32_e32 v193, 0xffff0000, v205
	v_pk_fma_f32 v[74:75], v[74:75], v[138:139], v[190:191]
	v_pk_fma_f32 v[76:77], v[76:77], v[140:141], v[192:193]
	v_cvt_pk_bf16_f32 v82, v82, v83
	v_cvt_pk_bf16_f32 v83, v84, v85
	v_cvt_pk_bf16_f32 v84, v74, v75
	v_cvt_pk_bf16_f32 v85, v76, v77
	s_nop 1
	v_permlane16_swap_b32 v82, v84
	v_permlane16_swap_b32 v83, v85
	v_mov_b32_e32 v212, 0x18000
	v_lshl_add_u64 v[220:221], v[216:217], 0, v[212:213]
	global_store_dwordx4 v[220:221], v[82:85], off
	v_mov_b32_e32 v212, 0x58000
	v_lshl_add_u64 v[218:219], v[214:215], 0, v[212:213]
	global_load_dwordx4 v[202:205], v[218:219], off
	s_waitcnt vmcnt(14)
	v_permlane16_swap_b32 v206, v208
	v_permlane16_swap_b32 v207, v209
	s_nop 1
	v_lshlrev_b32_e32 v186, 16, v206
	v_and_b32_e32 v187, 0xffff0000, v206
	v_lshlrev_b32_e32 v188, 16, v207
	v_and_b32_e32 v189, 0xffff0000, v207
	v_pk_fma_f32 v[70:71], v[70:71], v[134:135], v[186:187]
	v_pk_fma_f32 v[72:73], v[72:73], v[136:137], v[188:189]
	v_lshlrev_b32_e32 v190, 16, v208
	v_and_b32_e32 v191, 0xffff0000, v208
	v_lshlrev_b32_e32 v192, 16, v209
	v_and_b32_e32 v193, 0xffff0000, v209
	v_pk_fma_f32 v[66:67], v[66:67], v[130:131], v[190:191]
	v_pk_fma_f32 v[68:69], v[68:69], v[132:133], v[192:193]
	v_cvt_pk_bf16_f32 v70, v70, v71
	v_cvt_pk_bf16_f32 v71, v72, v73
	v_cvt_pk_bf16_f32 v72, v66, v67
	v_cvt_pk_bf16_f32 v73, v68, v69
	s_nop 1
	v_permlane16_swap_b32 v70, v72
	v_permlane16_swap_b32 v71, v73
	v_mov_b32_e32 v212, 0x18000
	v_lshl_add_u64 v[220:221], v[216:217], 0, v[212:213]
	global_store_dwordx4 v[220:221], v[70:73], off offset:256
	global_load_dwordx4 v[206:209], v[218:219], off offset:256
	s_waitcnt vmcnt(14)
	v_permlane16_swap_b32 v164, v166
	v_permlane16_swap_b32 v165, v167
	s_nop 1
	v_lshlrev_b32_e32 v186, 16, v164
	v_and_b32_e32 v187, 0xffff0000, v164
	v_lshlrev_b32_e32 v188, 16, v165
	v_and_b32_e32 v189, 0xffff0000, v165
	v_pk_fma_f32 v[62:63], v[62:63], v[142:143], v[186:187]
	v_pk_fma_f32 v[64:65], v[64:65], v[144:145], v[188:189]
	v_lshlrev_b32_e32 v190, 16, v166
	v_and_b32_e32 v191, 0xffff0000, v166
	v_lshlrev_b32_e32 v192, 16, v167
	v_and_b32_e32 v193, 0xffff0000, v167
	v_pk_fma_f32 v[58:59], v[58:59], v[138:139], v[190:191]
	v_pk_fma_f32 v[60:61], v[60:61], v[140:141], v[192:193]
	v_cvt_pk_bf16_f32 v62, v62, v63
	v_cvt_pk_bf16_f32 v63, v64, v65
	v_cvt_pk_bf16_f32 v64, v58, v59
	v_cvt_pk_bf16_f32 v65, v60, v61
	s_nop 1
	v_permlane16_swap_b32 v62, v64
	v_permlane16_swap_b32 v63, v65
	v_mov_b32_e32 v212, 0x40000
	v_lshl_add_u64 v[220:221], v[216:217], 0, v[212:213]
	global_store_dwordx4 v[220:221], v[62:65], off
	s_waitcnt vmcnt(13)
	v_permlane16_swap_b32 v168, v170
	v_permlane16_swap_b32 v169, v171
	s_nop 1
	v_lshlrev_b32_e32 v186, 16, v168
	v_and_b32_e32 v187, 0xffff0000, v168
	v_lshlrev_b32_e32 v188, 16, v169
	v_and_b32_e32 v189, 0xffff0000, v169
	v_pk_fma_f32 v[54:55], v[54:55], v[134:135], v[186:187]
	v_pk_fma_f32 v[56:57], v[56:57], v[136:137], v[188:189]
	v_lshlrev_b32_e32 v190, 16, v170
	v_and_b32_e32 v191, 0xffff0000, v170
	v_lshlrev_b32_e32 v192, 16, v171
	v_and_b32_e32 v193, 0xffff0000, v171
	v_pk_fma_f32 v[44:45], v[44:45], v[130:131], v[190:191]
	v_pk_fma_f32 v[46:47], v[46:47], v[132:133], v[192:193]
	v_cvt_pk_bf16_f32 v54, v54, v55
	v_cvt_pk_bf16_f32 v55, v56, v57
	v_cvt_pk_bf16_f32 v56, v44, v45
	v_cvt_pk_bf16_f32 v57, v46, v47
	s_nop 1
	v_permlane16_swap_b32 v54, v56
	v_permlane16_swap_b32 v55, v57
	v_mov_b32_e32 v212, 0x40000
	v_lshl_add_u64 v[220:221], v[216:217], 0, v[212:213]
	global_store_dwordx4 v[220:221], v[54:57], off offset:256
	s_waitcnt vmcnt(12)
	v_permlane16_swap_b32 v172, v174
	v_permlane16_swap_b32 v173, v175
	s_nop 1
	v_lshlrev_b32_e32 v186, 16, v172
	v_and_b32_e32 v187, 0xffff0000, v172
	v_lshlrev_b32_e32 v188, 16, v173
	v_and_b32_e32 v189, 0xffff0000, v173
	v_pk_fma_f32 v[50:51], v[50:51], v[142:143], v[186:187]
	v_pk_fma_f32 v[52:53], v[52:53], v[144:145], v[188:189]
	v_lshlrev_b32_e32 v190, 16, v174
	v_and_b32_e32 v191, 0xffff0000, v174
	v_lshlrev_b32_e32 v192, 16, v175
	v_and_b32_e32 v193, 0xffff0000, v175
	v_pk_fma_f32 v[40:41], v[40:41], v[138:139], v[190:191]
	v_pk_fma_f32 v[42:43], v[42:43], v[140:141], v[192:193]
	v_cvt_pk_bf16_f32 v50, v50, v51
	v_cvt_pk_bf16_f32 v51, v52, v53
	v_cvt_pk_bf16_f32 v52, v40, v41
	v_cvt_pk_bf16_f32 v53, v42, v43
	s_nop 1
	v_permlane16_swap_b32 v50, v52
	v_permlane16_swap_b32 v51, v53
	v_mov_b32_e32 v212, 0x48000
	v_lshl_add_u64 v[220:221], v[216:217], 0, v[212:213]
	global_store_dwordx4 v[220:221], v[50:53], off
	s_waitcnt vmcnt(11)
	v_permlane16_swap_b32 v176, v178
	v_permlane16_swap_b32 v177, v179
	s_nop 1
	v_lshlrev_b32_e32 v186, 16, v176
	v_and_b32_e32 v187, 0xffff0000, v176
	v_lshlrev_b32_e32 v188, 16, v177
	v_and_b32_e32 v189, 0xffff0000, v177
	v_pk_fma_f32 v[36:37], v[36:37], v[134:135], v[186:187]
	v_pk_fma_f32 v[38:39], v[38:39], v[136:137], v[188:189]
	v_lshlrev_b32_e32 v190, 16, v178
	v_and_b32_e32 v191, 0xffff0000, v178
	v_lshlrev_b32_e32 v192, 16, v179
	v_and_b32_e32 v193, 0xffff0000, v179
	v_pk_fma_f32 v[28:29], v[28:29], v[130:131], v[190:191]
	v_pk_fma_f32 v[30:31], v[30:31], v[132:133], v[192:193]
	v_cvt_pk_bf16_f32 v36, v36, v37
	v_cvt_pk_bf16_f32 v37, v38, v39
	v_cvt_pk_bf16_f32 v38, v28, v29
	v_cvt_pk_bf16_f32 v39, v30, v31
	s_nop 1
	v_permlane16_swap_b32 v36, v38
	v_permlane16_swap_b32 v37, v39
	v_mov_b32_e32 v212, 0x48000
	v_lshl_add_u64 v[220:221], v[216:217], 0, v[212:213]
	global_store_dwordx4 v[220:221], v[36:39], off offset:256
	s_waitcnt vmcnt(10)
	v_permlane16_swap_b32 v180, v182
	v_permlane16_swap_b32 v181, v183
	s_nop 1
	v_lshlrev_b32_e32 v186, 16, v180
	v_and_b32_e32 v187, 0xffff0000, v180
	v_lshlrev_b32_e32 v188, 16, v181
	v_and_b32_e32 v189, 0xffff0000, v181
	v_pk_fma_f32 v[32:33], v[32:33], v[142:143], v[186:187]
	v_pk_fma_f32 v[34:35], v[34:35], v[144:145], v[188:189]
	v_lshlrev_b32_e32 v190, 16, v182
	v_and_b32_e32 v191, 0xffff0000, v182
	v_lshlrev_b32_e32 v192, 16, v183
	v_and_b32_e32 v193, 0xffff0000, v183
	v_pk_fma_f32 v[24:25], v[24:25], v[138:139], v[190:191]
	v_pk_fma_f32 v[26:27], v[26:27], v[140:141], v[192:193]
	v_cvt_pk_bf16_f32 v32, v32, v33
	v_cvt_pk_bf16_f32 v33, v34, v35
	v_cvt_pk_bf16_f32 v34, v24, v25
	v_cvt_pk_bf16_f32 v35, v26, v27
	s_nop 1
	v_permlane16_swap_b32 v32, v34
	v_permlane16_swap_b32 v33, v35
	v_mov_b32_e32 v212, 0x50000
	v_lshl_add_u64 v[220:221], v[216:217], 0, v[212:213]
	global_store_dwordx4 v[220:221], v[32:35], off
	s_waitcnt vmcnt(9)
	v_permlane16_swap_b32 v198, v200
	v_permlane16_swap_b32 v199, v201
	s_nop 1
	v_lshlrev_b32_e32 v186, 16, v198
	v_and_b32_e32 v187, 0xffff0000, v198
	v_lshlrev_b32_e32 v188, 16, v199
	v_and_b32_e32 v189, 0xffff0000, v199
	v_pk_fma_f32 v[20:21], v[20:21], v[134:135], v[186:187]
	v_pk_fma_f32 v[22:23], v[22:23], v[136:137], v[188:189]
	v_lshlrev_b32_e32 v190, 16, v200
	v_and_b32_e32 v191, 0xffff0000, v200
	v_lshlrev_b32_e32 v192, 16, v201
	v_and_b32_e32 v193, 0xffff0000, v201
	v_pk_fma_f32 v[12:13], v[12:13], v[130:131], v[190:191]
	v_pk_fma_f32 v[14:15], v[14:15], v[132:133], v[192:193]
	v_cvt_pk_bf16_f32 v20, v20, v21
	v_cvt_pk_bf16_f32 v21, v22, v23
	v_cvt_pk_bf16_f32 v22, v12, v13
	v_cvt_pk_bf16_f32 v23, v14, v15
	s_nop 1
	v_permlane16_swap_b32 v20, v22
	v_permlane16_swap_b32 v21, v23
	v_mov_b32_e32 v212, 0x50000
	v_lshl_add_u64 v[220:221], v[216:217], 0, v[212:213]
	global_store_dwordx4 v[220:221], v[20:23], off offset:256
	s_waitcnt vmcnt(8)
	v_permlane16_swap_b32 v202, v204
	v_permlane16_swap_b32 v203, v205
	s_nop 1
	v_lshlrev_b32_e32 v186, 16, v202
	v_and_b32_e32 v187, 0xffff0000, v202
	v_lshlrev_b32_e32 v188, 16, v203
	v_and_b32_e32 v189, 0xffff0000, v203
	v_pk_fma_f32 v[16:17], v[16:17], v[142:143], v[186:187]
	v_pk_fma_f32 v[18:19], v[18:19], v[144:145], v[188:189]
	v_lshlrev_b32_e32 v190, 16, v204
	v_and_b32_e32 v191, 0xffff0000, v204
	v_lshlrev_b32_e32 v192, 16, v205
	v_and_b32_e32 v193, 0xffff0000, v205
	v_pk_fma_f32 v[8:9], v[8:9], v[138:139], v[190:191]
	v_pk_fma_f32 v[10:11], v[10:11], v[140:141], v[192:193]
	v_cvt_pk_bf16_f32 v16, v16, v17
	v_cvt_pk_bf16_f32 v17, v18, v19
	v_cvt_pk_bf16_f32 v18, v8, v9
	v_cvt_pk_bf16_f32 v19, v10, v11
	s_nop 1
	v_permlane16_swap_b32 v16, v18
	v_permlane16_swap_b32 v17, v19
	v_mov_b32_e32 v212, 0x58000
	v_lshl_add_u64 v[220:221], v[216:217], 0, v[212:213]
	global_store_dwordx4 v[220:221], v[16:19], off
	s_waitcnt vmcnt(7)
	v_permlane16_swap_b32 v206, v208
	v_permlane16_swap_b32 v207, v209
	s_nop 1
	v_lshlrev_b32_e32 v186, 16, v206
	v_and_b32_e32 v187, 0xffff0000, v206
	v_lshlrev_b32_e32 v188, 16, v207
	v_and_b32_e32 v189, 0xffff0000, v207
	v_pk_fma_f32 v[4:5], v[4:5], v[134:135], v[186:187]
	v_pk_fma_f32 v[6:7], v[6:7], v[136:137], v[188:189]
	v_lshlrev_b32_e32 v190, 16, v208
	v_and_b32_e32 v191, 0xffff0000, v208
	v_lshlrev_b32_e32 v192, 16, v209
	v_and_b32_e32 v193, 0xffff0000, v209
	v_pk_fma_f32 v[0:1], v[0:1], v[130:131], v[190:191]
	v_pk_fma_f32 v[2:3], v[2:3], v[132:133], v[192:193]
	v_cvt_pk_bf16_f32 v4, v4, v5
	v_cvt_pk_bf16_f32 v5, v6, v7
	v_cvt_pk_bf16_f32 v6, v0, v1
	v_cvt_pk_bf16_f32 v7, v2, v3
	s_nop 1
	v_permlane16_swap_b32 v4, v6
	v_permlane16_swap_b32 v5, v7
	v_mov_b32_e32 v212, 0x58000
	v_lshl_add_u64 v[220:221], v[216:217], 0, v[212:213]
	global_store_dwordx4 v[220:221], v[4:7], off offset:256
	s_mov_b32 s16, s43
	s_mov_b32 s17, s42
	s_and_b64 vcc, exec, s[0:1]
	s_mov_b64 s[18:19], s[12:13]
	s_cbranch_vccz .LBB0_1432
	s_waitcnt vmcnt(0)
	s_cmpk_gt_u32 s29, 0xff
	s_cbranch_scc1 .LBB0_1439
	s_barrier
